# write-through publish for the mixer: all mixer and transpose stores sc1, release write-back dropped from the barrier that ends the phase
# baseline (speedup 1.0000x reference)
.LBB0_985:
	v_cmp_lt_i32_e32 vcc, v197, v203
	v_lshlrev_b64 v[2:3], 11, v[198:199]
	v_lshl_add_u64 v[2:3], s[22:23], 0, v[2:3]
	v_cndmask_b32_e32 v0, v195, v197, vcc
	v_cmp_lt_i32_e32 vcc, v204, v203
	s_waitcnt vmcnt(4)
	v_lshlrev_b32_e32 v26, 2, v0
	s_mov_b64 s[0:1], 0xd800500
	v_cndmask_b32_e32 v0, v195, v204, vcc
	v_lshlrev_b32_e32 v27, 2, v0
	v_mov_b32_e32 v0, v212
	s_nop 1
	v_permlane16_swap_b32_e32 v0, v212
	v_lshl_add_u64 v[2:3], v[2:3], 0, s[0:1]
	v_lshl_add_u64 v[20:21], s[36:37], 1, v[2:3]
	v_mov_b32_e32 v197, v1
	v_lshl_add_u64 v[20:21], v[20:21], 0, v[196:197]
	s_waitcnt lgkmcnt(0)
	v_add_f32_e32 v0, v212, v0
	v_mov_b32_e32 v22, v0
	s_nop 1
	v_permlane32_swap_b32_e32 v22, v0
	v_lshl_add_u64 v[2:3], s[38:39], 1, v[2:3]
	v_lshl_add_u64 v[2:3], v[2:3], 0, v[196:197]
	s_waitcnt lgkmcnt(0)
	v_add_f32_e32 v0, v0, v22
	v_div_scale_f32 v22, s[0:1], v0, v0, 1.0
	v_rcp_f32_e32 v23, v22
	s_nop 0
	v_fma_f32 v24, -v22, v23, 1.0
	v_fmac_f32_e32 v23, v24, v23
	v_div_scale_f32 v24, vcc, 1.0, v0, 1.0
	v_mul_f32_e32 v25, v24, v23
	s_waitcnt vmcnt(3)
	v_fma_f32 v28, -v22, v25, v24
	v_fmac_f32_e32 v25, v28, v23
	v_fma_f32 v22, -v22, v25, v24
	v_div_fmas_f32 v22, v22, v23, v25
	v_div_fixup_f32 v0, v22, v0, 1.0
	v_mov_b32_e32 v22, v120
	v_mov_b32_e32 v23, v122
	v_pk_mul_f32 v[22:23], v[22:23], v[0:1] op_sel_hi:[1,0]
	v_mov_b32_e32 v122, v121
	v_pk_mul_f32 v[24:25], v[122:123], v[0:1] op_sel_hi:[1,0]
	v_and_b32_sdwa v28, v23, v236 dst_sel:DWORD dst_unused:UNUSED_PAD src0_sel:WORD_1 src1_sel:DWORD
	v_and_b32_sdwa v29, v22, v236 dst_sel:DWORD dst_unused:UNUSED_PAD src0_sel:WORD_1 src1_sel:DWORD
	v_add3_u32 v22, v22, v29, s60
	v_add3_u32 v23, v23, v28, s60
	v_and_b32_sdwa v28, v25, v236 dst_sel:DWORD dst_unused:UNUSED_PAD src0_sel:WORD_1 src1_sel:DWORD
	v_and_b32_sdwa v29, v24, v236 dst_sel:DWORD dst_unused:UNUSED_PAD src0_sel:WORD_1 src1_sel:DWORD
	v_add3_u32 v25, v25, v28, s60
	v_add3_u32 v24, v24, v29, s60
	v_and_b32_e32 v25, 0xffff0000, v25
	v_and_b32_e32 v24, 0xffff0000, v24
	v_or_b32_sdwa v23, v25, v23 dst_sel:DWORD dst_unused:UNUSED_PAD src0_sel:DWORD src1_sel:WORD_1
	v_or_b32_sdwa v22, v24, v22 dst_sel:DWORD dst_unused:UNUSED_PAD src0_sel:DWORD src1_sel:WORD_1
	global_store_dwordx2 v[20:21], v[22:23], off sc1
	v_mov_b32_e32 v22, v100
	v_mov_b32_e32 v23, v102
	v_pk_mul_f32 v[22:23], v[22:23], v[0:1] op_sel_hi:[1,0]
	v_mov_b32_e32 v102, v101
	v_pk_mul_f32 v[24:25], v[102:103], v[0:1] op_sel_hi:[1,0]
	v_and_b32_sdwa v28, v23, v236 dst_sel:DWORD dst_unused:UNUSED_PAD src0_sel:WORD_1 src1_sel:DWORD
	v_and_b32_sdwa v29, v22, v236 dst_sel:DWORD dst_unused:UNUSED_PAD src0_sel:WORD_1 src1_sel:DWORD
	v_add3_u32 v22, v22, v29, s60
	v_add3_u32 v23, v23, v28, s60
	v_and_b32_sdwa v28, v25, v236 dst_sel:DWORD dst_unused:UNUSED_PAD src0_sel:WORD_1 src1_sel:DWORD
	v_and_b32_sdwa v29, v24, v236 dst_sel:DWORD dst_unused:UNUSED_PAD src0_sel:WORD_1 src1_sel:DWORD
	v_add3_u32 v25, v25, v28, s60
	v_add3_u32 v24, v24, v29, s60
	v_and_b32_e32 v25, 0xffff0000, v25
	v_and_b32_e32 v24, 0xffff0000, v24
	v_or_b32_sdwa v23, v25, v23 dst_sel:DWORD dst_unused:UNUSED_PAD src0_sel:DWORD src1_sel:WORD_1
	v_or_b32_sdwa v22, v24, v22 dst_sel:DWORD dst_unused:UNUSED_PAD src0_sel:DWORD src1_sel:WORD_1
	global_store_dwordx2 v[20:21], v[22:23], off offset:32 sc1
	v_mov_b32_e32 v22, v96
	v_mov_b32_e32 v23, v98
	v_pk_mul_f32 v[22:23], v[22:23], v[0:1] op_sel_hi:[1,0]
	v_mov_b32_e32 v98, v97
	v_pk_mul_f32 v[24:25], v[98:99], v[0:1] op_sel_hi:[1,0]
	v_and_b32_sdwa v28, v23, v236 dst_sel:DWORD dst_unused:UNUSED_PAD src0_sel:WORD_1 src1_sel:DWORD
	v_and_b32_sdwa v29, v22, v236 dst_sel:DWORD dst_unused:UNUSED_PAD src0_sel:WORD_1 src1_sel:DWORD
	v_add3_u32 v22, v22, v29, s60
	v_add3_u32 v23, v23, v28, s60
	v_and_b32_sdwa v28, v25, v236 dst_sel:DWORD dst_unused:UNUSED_PAD src0_sel:WORD_1 src1_sel:DWORD
	v_and_b32_sdwa v29, v24, v236 dst_sel:DWORD dst_unused:UNUSED_PAD src0_sel:WORD_1 src1_sel:DWORD
	v_add3_u32 v25, v25, v28, s60
	v_add3_u32 v24, v24, v29, s60
	v_and_b32_e32 v25, 0xffff0000, v25
	v_and_b32_e32 v24, 0xffff0000, v24
	v_or_b32_sdwa v23, v25, v23 dst_sel:DWORD dst_unused:UNUSED_PAD src0_sel:DWORD src1_sel:WORD_1
	v_or_b32_sdwa v22, v24, v22 dst_sel:DWORD dst_unused:UNUSED_PAD src0_sel:DWORD src1_sel:WORD_1
	global_store_dwordx2 v[20:21], v[22:23], off offset:64 sc1
	v_mov_b32_e32 v22, v92
	v_mov_b32_e32 v23, v94
	v_pk_mul_f32 v[22:23], v[22:23], v[0:1] op_sel_hi:[1,0]
	v_mov_b32_e32 v94, v93
	v_pk_mul_f32 v[24:25], v[94:95], v[0:1] op_sel_hi:[1,0]
	v_and_b32_sdwa v0, v23, v236 dst_sel:DWORD dst_unused:UNUSED_PAD src0_sel:WORD_1 src1_sel:DWORD
	v_add3_u32 v0, v23, v0, s60
	v_and_b32_sdwa v23, v25, v236 dst_sel:DWORD dst_unused:UNUSED_PAD src0_sel:WORD_1 src1_sel:DWORD
	v_add3_u32 v23, v25, v23, s60
	v_and_b32_e32 v23, 0xffff0000, v23
	v_or_b32_sdwa v23, v23, v0 dst_sel:DWORD dst_unused:UNUSED_PAD src0_sel:DWORD src1_sel:WORD_1
	v_mov_b32_e32 v0, v211
	s_nop 1
	v_permlane16_swap_b32_e32 v0, v211
	v_and_b32_sdwa v28, v22, v236 dst_sel:DWORD dst_unused:UNUSED_PAD src0_sel:WORD_1 src1_sel:DWORD
	v_add3_u32 v22, v22, v28, s60
	v_and_b32_sdwa v28, v24, v236 dst_sel:DWORD dst_unused:UNUSED_PAD src0_sel:WORD_1 src1_sel:DWORD
	v_add3_u32 v24, v24, v28, s60
	v_and_b32_e32 v24, 0xffff0000, v24
	v_or_b32_sdwa v22, v24, v22 dst_sel:DWORD dst_unused:UNUSED_PAD src0_sel:DWORD src1_sel:WORD_1
	s_waitcnt lgkmcnt(0)
	v_add_f32_e32 v0, v211, v0
	global_store_dwordx2 v[20:21], v[22:23], off offset:96 sc1
	v_mov_b32_e32 v22, v0
	s_nop 1
	v_permlane32_swap_b32_e32 v22, v0
	s_waitcnt lgkmcnt(0)
	v_add_f32_e32 v0, v0, v22
	v_div_scale_f32 v22, s[0:1], v0, v0, 1.0
	v_rcp_f32_e32 v23, v22
	s_nop 0
	v_fma_f32 v24, -v22, v23, 1.0
	v_fmac_f32_e32 v23, v24, v23
	v_div_scale_f32 v24, vcc, 1.0, v0, 1.0
	v_mul_f32_e32 v25, v24, v23
	v_fma_f32 v28, -v22, v25, v24
	v_fmac_f32_e32 v25, v28, v23
	v_fma_f32 v22, -v22, v25, v24
	v_div_fmas_f32 v22, v22, v23, v25
	v_div_fixup_f32 v0, v22, v0, 1.0
	v_mov_b32_e32 v22, v56
	v_mov_b32_e32 v23, v58
	v_pk_mul_f32 v[22:23], v[22:23], v[0:1] op_sel_hi:[1,0]
	v_mov_b32_e32 v58, v57
	v_pk_mul_f32 v[24:25], v[58:59], v[0:1] op_sel_hi:[1,0]
	v_and_b32_sdwa v28, v23, v236 dst_sel:DWORD dst_unused:UNUSED_PAD src0_sel:WORD_1 src1_sel:DWORD
	v_and_b32_sdwa v29, v22, v236 dst_sel:DWORD dst_unused:UNUSED_PAD src0_sel:WORD_1 src1_sel:DWORD
	v_add3_u32 v22, v22, v29, s60
	v_add3_u32 v23, v23, v28, s60
	v_and_b32_sdwa v28, v25, v236 dst_sel:DWORD dst_unused:UNUSED_PAD src0_sel:WORD_1 src1_sel:DWORD
	v_and_b32_sdwa v29, v24, v236 dst_sel:DWORD dst_unused:UNUSED_PAD src0_sel:WORD_1 src1_sel:DWORD
	v_add3_u32 v25, v25, v28, s60
	v_add3_u32 v24, v24, v29, s60
	v_and_b32_e32 v25, 0xffff0000, v25
	v_and_b32_e32 v24, 0xffff0000, v24
	v_or_b32_sdwa v23, v25, v23 dst_sel:DWORD dst_unused:UNUSED_PAD src0_sel:DWORD src1_sel:WORD_1
	v_or_b32_sdwa v22, v24, v22 dst_sel:DWORD dst_unused:UNUSED_PAD src0_sel:DWORD src1_sel:WORD_1
	global_store_dwordx2 v[20:21], v[22:23], off offset:128 sc1
	v_mov_b32_e32 v22, v52
	v_mov_b32_e32 v23, v54
	v_pk_mul_f32 v[22:23], v[22:23], v[0:1] op_sel_hi:[1,0]
	v_mov_b32_e32 v54, v53
	v_pk_mul_f32 v[24:25], v[54:55], v[0:1] op_sel_hi:[1,0]
	v_and_b32_sdwa v28, v23, v236 dst_sel:DWORD dst_unused:UNUSED_PAD src0_sel:WORD_1 src1_sel:DWORD
	v_and_b32_sdwa v29, v22, v236 dst_sel:DWORD dst_unused:UNUSED_PAD src0_sel:WORD_1 src1_sel:DWORD
	v_add3_u32 v22, v22, v29, s60
	v_add3_u32 v23, v23, v28, s60
	v_and_b32_sdwa v28, v25, v236 dst_sel:DWORD dst_unused:UNUSED_PAD src0_sel:WORD_1 src1_sel:DWORD
	v_and_b32_sdwa v29, v24, v236 dst_sel:DWORD dst_unused:UNUSED_PAD src0_sel:WORD_1 src1_sel:DWORD
	v_add3_u32 v25, v25, v28, s60
	v_add3_u32 v24, v24, v29, s60
	v_and_b32_e32 v25, 0xffff0000, v25
	v_and_b32_e32 v24, 0xffff0000, v24
	v_or_b32_sdwa v23, v25, v23 dst_sel:DWORD dst_unused:UNUSED_PAD src0_sel:DWORD src1_sel:WORD_1
	v_or_b32_sdwa v22, v24, v22 dst_sel:DWORD dst_unused:UNUSED_PAD src0_sel:DWORD src1_sel:WORD_1
	global_store_dwordx2 v[20:21], v[22:23], off offset:160 sc1
	v_mov_b32_e32 v22, v48
	v_mov_b32_e32 v23, v50
	v_pk_mul_f32 v[22:23], v[22:23], v[0:1] op_sel_hi:[1,0]
	v_mov_b32_e32 v50, v49
	v_pk_mul_f32 v[24:25], v[50:51], v[0:1] op_sel_hi:[1,0]
	v_and_b32_sdwa v28, v23, v236 dst_sel:DWORD dst_unused:UNUSED_PAD src0_sel:WORD_1 src1_sel:DWORD
	v_and_b32_sdwa v29, v22, v236 dst_sel:DWORD dst_unused:UNUSED_PAD src0_sel:WORD_1 src1_sel:DWORD
	v_add3_u32 v22, v22, v29, s60
	v_add3_u32 v23, v23, v28, s60
	v_and_b32_sdwa v28, v25, v236 dst_sel:DWORD dst_unused:UNUSED_PAD src0_sel:WORD_1 src1_sel:DWORD
	v_and_b32_sdwa v29, v24, v236 dst_sel:DWORD dst_unused:UNUSED_PAD src0_sel:WORD_1 src1_sel:DWORD
	v_add3_u32 v25, v25, v28, s60
	v_add3_u32 v24, v24, v29, s60
	v_and_b32_e32 v25, 0xffff0000, v25
	v_and_b32_e32 v24, 0xffff0000, v24
	v_or_b32_sdwa v23, v25, v23 dst_sel:DWORD dst_unused:UNUSED_PAD src0_sel:DWORD src1_sel:WORD_1
	v_or_b32_sdwa v22, v24, v22 dst_sel:DWORD dst_unused:UNUSED_PAD src0_sel:DWORD src1_sel:WORD_1
	global_store_dwordx2 v[20:21], v[22:23], off offset:192 sc1
	v_mov_b32_e32 v22, v44
	v_mov_b32_e32 v23, v46
	v_pk_mul_f32 v[22:23], v[22:23], v[0:1] op_sel_hi:[1,0]
	v_mov_b32_e32 v46, v45
	v_pk_mul_f32 v[24:25], v[46:47], v[0:1] op_sel_hi:[1,0]
	v_and_b32_sdwa v0, v23, v236 dst_sel:DWORD dst_unused:UNUSED_PAD src0_sel:WORD_1 src1_sel:DWORD
	v_add3_u32 v0, v23, v0, s60
	v_and_b32_sdwa v23, v25, v236 dst_sel:DWORD dst_unused:UNUSED_PAD src0_sel:WORD_1 src1_sel:DWORD
	v_add3_u32 v23, v25, v23, s60
	v_and_b32_e32 v23, 0xffff0000, v23
	v_or_b32_sdwa v23, v23, v0 dst_sel:DWORD dst_unused:UNUSED_PAD src0_sel:DWORD src1_sel:WORD_1
	v_mov_b32_e32 v0, v202
	s_nop 1
	v_permlane16_swap_b32_e32 v0, v202
	v_and_b32_sdwa v28, v22, v236 dst_sel:DWORD dst_unused:UNUSED_PAD src0_sel:WORD_1 src1_sel:DWORD
	v_add3_u32 v22, v22, v28, s60
	v_and_b32_sdwa v28, v24, v236 dst_sel:DWORD dst_unused:UNUSED_PAD src0_sel:WORD_1 src1_sel:DWORD
	v_add3_u32 v24, v24, v28, s60
	v_and_b32_e32 v24, 0xffff0000, v24
	v_or_b32_sdwa v22, v24, v22 dst_sel:DWORD dst_unused:UNUSED_PAD src0_sel:DWORD src1_sel:WORD_1
	s_waitcnt lgkmcnt(0)
	v_add_f32_e32 v0, v202, v0
	global_store_dwordx2 v[20:21], v[22:23], off offset:224 sc1
	v_mov_b32_e32 v20, v0
	s_nop 1
	v_permlane32_swap_b32_e32 v20, v0
	s_waitcnt lgkmcnt(0)
	v_add_f32_e32 v0, v0, v20
	v_div_scale_f32 v20, s[0:1], v0, v0, 1.0
	v_rcp_f32_e32 v21, v20
	s_nop 0
	v_fma_f32 v22, -v20, v21, 1.0
	v_fmac_f32_e32 v21, v22, v21
	v_div_scale_f32 v22, vcc, 1.0, v0, 1.0
	v_mul_f32_e32 v23, v22, v21
	v_fma_f32 v24, -v20, v23, v22
	v_fmac_f32_e32 v23, v24, v21
	v_fma_f32 v20, -v20, v23, v22
	v_div_fmas_f32 v20, v20, v21, v23
	v_div_fixup_f32 v0, v20, v0, 1.0
	v_mov_b32_e32 v20, v16
	v_mov_b32_e32 v21, v18
	v_pk_mul_f32 v[20:21], v[20:21], v[0:1] op_sel_hi:[1,0]
	v_mov_b32_e32 v18, v17
	v_pk_mul_f32 v[16:17], v[18:19], v[0:1] op_sel_hi:[1,0]
	v_and_b32_sdwa v18, v21, v236 dst_sel:DWORD dst_unused:UNUSED_PAD src0_sel:WORD_1 src1_sel:DWORD
	v_and_b32_sdwa v19, v20, v236 dst_sel:DWORD dst_unused:UNUSED_PAD src0_sel:WORD_1 src1_sel:DWORD
	v_add3_u32 v19, v20, v19, s60
	v_add3_u32 v18, v21, v18, s60
	v_and_b32_sdwa v20, v17, v236 dst_sel:DWORD dst_unused:UNUSED_PAD src0_sel:WORD_1 src1_sel:DWORD
	v_and_b32_sdwa v21, v16, v236 dst_sel:DWORD dst_unused:UNUSED_PAD src0_sel:WORD_1 src1_sel:DWORD
	v_add3_u32 v17, v17, v20, s60
	v_add3_u32 v16, v16, v21, s60
	v_and_b32_e32 v17, 0xffff0000, v17
	v_and_b32_e32 v16, 0xffff0000, v16
	v_or_b32_sdwa v17, v17, v18 dst_sel:DWORD dst_unused:UNUSED_PAD src0_sel:DWORD src1_sel:WORD_1
	v_or_b32_sdwa v16, v16, v19 dst_sel:DWORD dst_unused:UNUSED_PAD src0_sel:DWORD src1_sel:WORD_1
	global_store_dwordx2 v[2:3], v[16:17], off sc1
	v_mov_b32_e32 v16, v12
	v_mov_b32_e32 v17, v14
	v_pk_mul_f32 v[16:17], v[16:17], v[0:1] op_sel_hi:[1,0]
	v_mov_b32_e32 v14, v13
	v_pk_mul_f32 v[12:13], v[14:15], v[0:1] op_sel_hi:[1,0]
	v_and_b32_sdwa v14, v17, v236 dst_sel:DWORD dst_unused:UNUSED_PAD src0_sel:WORD_1 src1_sel:DWORD
	v_and_b32_sdwa v15, v16, v236 dst_sel:DWORD dst_unused:UNUSED_PAD src0_sel:WORD_1 src1_sel:DWORD
	v_add3_u32 v15, v16, v15, s60
	v_add3_u32 v14, v17, v14, s60
	v_and_b32_sdwa v16, v13, v236 dst_sel:DWORD dst_unused:UNUSED_PAD src0_sel:WORD_1 src1_sel:DWORD
	v_and_b32_sdwa v17, v12, v236 dst_sel:DWORD dst_unused:UNUSED_PAD src0_sel:WORD_1 src1_sel:DWORD
	v_add3_u32 v13, v13, v16, s60
	v_add3_u32 v12, v12, v17, s60
	v_and_b32_e32 v13, 0xffff0000, v13
	v_and_b32_e32 v12, 0xffff0000, v12
	v_or_b32_sdwa v13, v13, v14 dst_sel:DWORD dst_unused:UNUSED_PAD src0_sel:DWORD src1_sel:WORD_1
	v_or_b32_sdwa v12, v12, v15 dst_sel:DWORD dst_unused:UNUSED_PAD src0_sel:DWORD src1_sel:WORD_1
	global_store_dwordx2 v[2:3], v[12:13], off offset:32 sc1
	v_mov_b32_e32 v12, v8
	v_mov_b32_e32 v13, v10
	v_pk_mul_f32 v[12:13], v[12:13], v[0:1] op_sel_hi:[1,0]
	v_mov_b32_e32 v10, v9
	v_pk_mul_f32 v[8:9], v[10:11], v[0:1] op_sel_hi:[1,0]
	v_and_b32_sdwa v10, v13, v236 dst_sel:DWORD dst_unused:UNUSED_PAD src0_sel:WORD_1 src1_sel:DWORD
	v_and_b32_sdwa v11, v12, v236 dst_sel:DWORD dst_unused:UNUSED_PAD src0_sel:WORD_1 src1_sel:DWORD
	v_add3_u32 v11, v12, v11, s60
	v_add3_u32 v10, v13, v10, s60
	v_and_b32_sdwa v12, v9, v236 dst_sel:DWORD dst_unused:UNUSED_PAD src0_sel:WORD_1 src1_sel:DWORD
	v_and_b32_sdwa v13, v8, v236 dst_sel:DWORD dst_unused:UNUSED_PAD src0_sel:WORD_1 src1_sel:DWORD
	v_add3_u32 v9, v9, v12, s60
	v_add3_u32 v8, v8, v13, s60
	v_and_b32_e32 v9, 0xffff0000, v9
	v_and_b32_e32 v8, 0xffff0000, v8
	v_or_b32_sdwa v9, v9, v10 dst_sel:DWORD dst_unused:UNUSED_PAD src0_sel:DWORD src1_sel:WORD_1
	v_or_b32_sdwa v8, v8, v11 dst_sel:DWORD dst_unused:UNUSED_PAD src0_sel:DWORD src1_sel:WORD_1
	global_store_dwordx2 v[2:3], v[8:9], off offset:64 sc1
	v_mov_b32_e32 v8, v4
	v_mov_b32_e32 v9, v6
	v_pk_mul_f32 v[8:9], v[8:9], v[0:1] op_sel_hi:[1,0]
	v_mov_b32_e32 v6, v5
	v_pk_mul_f32 v[4:5], v[6:7], v[0:1] op_sel_hi:[1,0]
	v_and_b32_sdwa v6, v8, v236 dst_sel:DWORD dst_unused:UNUSED_PAD src0_sel:WORD_1 src1_sel:DWORD
	v_add3_u32 v6, v8, v6, s60
	v_and_b32_sdwa v7, v5, v236 dst_sel:DWORD dst_unused:UNUSED_PAD src0_sel:WORD_1 src1_sel:DWORD
	v_and_b32_sdwa v8, v4, v236 dst_sel:DWORD dst_unused:UNUSED_PAD src0_sel:WORD_1 src1_sel:DWORD
	v_and_b32_sdwa v0, v9, v236 dst_sel:DWORD dst_unused:UNUSED_PAD src0_sel:WORD_1 src1_sel:DWORD
	v_add3_u32 v5, v5, v7, s60
	v_add3_u32 v4, v4, v8, s60
	v_add3_u32 v0, v9, v0, s60
	v_and_b32_e32 v5, 0xffff0000, v5
	v_and_b32_e32 v4, 0xffff0000, v4
	v_or_b32_sdwa v5, v5, v0 dst_sel:DWORD dst_unused:UNUSED_PAD src0_sel:DWORD src1_sel:WORD_1
	v_or_b32_sdwa v4, v4, v6 dst_sel:DWORD dst_unused:UNUSED_PAD src0_sel:DWORD src1_sel:WORD_1
	global_store_dwordx2 v[2:3], v[4:5], off offset:96 sc1

.LBB0_1062:
	s_or_b64 exec, exec, s[12:13]
	v_add_f32_e32 v94, 0, v153
	v_add_f32_e32 v94, v155, v94
	v_add_f32_e32 v11, 0, v11
	v_add_f32_e32 v94, v157, v94
	v_add_f32_e32 v11, v164, v11
	v_add_f32_e32 v94, v159, v94
	v_add_f32_e32 v11, v165, v11
	v_add_f32_e32 v94, v160, v94
	v_add_f32_e32 v11, v166, v11
	v_add_f32_e32 v94, v161, v94
	v_add_f32_e32 v11, v167, v11
	v_add_f32_e32 v94, v162, v94
	v_add_f32_e32 v11, v168, v11
	v_add_f32_e32 v94, v163, v94
	v_add_f32_e32 v11, v169, v11
	v_add_f32_e32 v10, v10, v94
	v_add_f32_e32 v11, v170, v11
	v_fmac_f32_e32 v11, v10, v152
	v_add_f32_e32 v10, 0, v171
	v_add_f32_e32 v10, v172, v10
	v_add_f32_e32 v10, v173, v10
	v_add_f32_e32 v10, v174, v10
	v_add_f32_e32 v10, v175, v10
	v_add_f32_e32 v10, v176, v10
	v_add_f32_e32 v10, v177, v10
	v_add_f32_e32 v10, v178, v10
	v_fmac_f32_e32 v10, v11, v154
	v_add_f32_e32 v11, 0, v191
	v_add_f32_e32 v11, v193, v11
	v_add_f32_e32 v11, v194, v11
	v_add_f32_e32 v11, v195, v11
	v_add_f32_e32 v11, v196, v11
	v_add_f32_e32 v11, v197, v11
	v_add_f32_e32 v11, v198, v11
	v_add_f32_e32 v11, v199, v11
	v_fmac_f32_e32 v11, v10, v156
	v_add_f32_e32 v10, 0, v200
	v_add_f32_e32 v10, v201, v10
	v_add_f32_e32 v10, v202, v10
	v_add_f32_e32 v10, v203, v10
	v_add_f32_e32 v10, v204, v10
	v_add_f32_e32 v10, v205, v10
	v_add_f32_e32 v10, v206, v10
	v_add_f32_e32 v10, v207, v10
	v_fmac_f32_e32 v10, v11, v158
	v_add_f32_e32 v11, 0, v125
	v_add_f32_e32 v11, v126, v11
	v_add_f32_e32 v11, v127, v11
	v_add_f32_e32 v11, v128, v11
	v_add_f32_e32 v11, v129, v11
	v_add_f32_e32 v11, v208, v11
	v_add_f32_e32 v11, v209, v11
	v_add_f32_e32 v11, v210, v11
	v_fmac_f32_e32 v11, v10, v0
	v_add_f32_e32 v0, 0, v213
	v_add_f32_e32 v0, v214, v0
	v_add_f32_e32 v0, v215, v0
	v_add_f32_e32 v0, v216, v0
	v_add_f32_e32 v0, v217, v0
	v_add_f32_e32 v0, v218, v0
	v_add_f32_e32 v0, v219, v0
	v_add_f32_e32 v101, v220, v0
	v_lshlrev_b32_e32 v0, 11, v141
	v_fmac_f32_e32 v101, v11, v124
	v_lshl_add_u64 v[10:11], s[8:9], 0, v[0:1]
	s_mov_b32 s31, s45
	v_lshl_add_u64 v[128:129], v[10:11], 0, s[30:31]
	v_max_f32_e32 v0, v100, v100
	v_max_f32_e32 v10, v211, v211
	v_max_f32_e32 v0, v10, v0
	v_max_f32_e32 v10, v98, v98
	v_max_f32_e32 v11, v96, v96
	v_max_f32_e32 v10, v11, v10
	v_max_f32_e32 v11, v93, v93
	v_max_f32_e32 v94, v92, v92
	v_max_f32_e32 v11, v94, v11
	v_max3_f32 v11, v97, v99, v11
	v_max3_f32 v0, v0, v10, v11
	v_mov_b32_e32 v10, v0
	s_nop 1
	v_permlane16_swap_b32_e32 v10, v0
	v_mov_b32_e32 v149, v1
	v_mov_b32_e32 v145, v1
	s_mov_b64 s[0:1], 0xc000
	s_waitcnt vmcnt(15)
	v_mfma_f32_16x16x32_bf16 v[88:91], v[88:91], v[6:9], 0
	s_waitcnt lgkmcnt(0)
	v_max_f32_e32 v10, v10, v10
	v_max_f32_e32 v0, v0, v10
	v_mov_b32_e32 v10, v0
	s_nop 1
	v_permlane32_swap_b32_e32 v10, v0
	v_mov_b32_e32 v143, v1
	s_waitcnt vmcnt(13)
	v_mfma_f32_16x16x32_bf16 v[84:87], v[84:87], v[6:9], 0
	v_mov_b32_e32 v147, v1
	s_waitcnt lgkmcnt(0)
	v_max3_f32 v124, v212, v0, v10
	v_sub_f32_e32 v94, v96, v124
	v_mul_f32_e32 v94, 0x3fb8aa3b, v94
	v_sub_f32_e32 v10, v211, v124
	v_sub_f32_e32 v11, v100, v124
	v_exp_f32_e32 v100, v94
	v_sub_f32_e32 v94, v98, v124
	v_mul_f32_e32 v10, 0x3fb8aa3b, v10
	v_mul_f32_e32 v94, 0x3fb8aa3b, v94
	v_exp_f32_e32 v10, v10
	v_mul_f32_e32 v11, 0x3fb8aa3b, v11
	v_exp_f32_e32 v102, v94
	v_sub_f32_e32 v94, v97, v124
	v_exp_f32_e32 v11, v11
	v_mul_f32_e32 v94, 0x3fb8aa3b, v94
	v_sub_f32_e32 v92, v92, v124
	v_exp_f32_e32 v103, v94
	v_sub_f32_e32 v94, v99, v124
	v_mul_f32_e32 v92, 0x3fb8aa3b, v92
	v_mul_f32_e32 v94, 0x3fb8aa3b, v94
	v_exp_f32_e32 v126, v92
	v_sub_f32_e32 v92, v93, v124
	v_sub_f32_e32 v0, v212, v124
	v_exp_f32_e32 v125, v94
	v_mul_f32_e32 v92, 0x3fb8aa3b, v92
	v_add_u32_e32 v93, 0x8000, v10
	v_add_f32_e32 v10, 0, v10
	v_mul_f32_e32 v0, 0x3fb8aa3b, v0
	v_exp_f32_e32 v127, v92
	v_add_f32_e32 v10, v11, v10
	v_exp_f32_e32 v0, v0
	v_add_u32_e32 v92, 0x8000, v11
	v_add_f32_e32 v10, v100, v10
	v_perm_b32 v92, v92, v93, s87
	v_add_u32_e32 v93, 0x8000, v102
	v_add_u32_e32 v94, 0x8000, v100
	v_add_f32_e32 v10, v102, v10
	v_perm_b32 v93, v93, v94, s87
	v_add_u32_e32 v94, 0x8000, v125
	v_add_u32_e32 v95, 0x8000, v103
	v_add_f32_e32 v10, v103, v10
	v_perm_b32 v94, v94, v95, s87
	v_add_u32_e32 v95, 0x8000, v127
	v_add_u32_e32 v96, 0x8000, v126
	v_add_f32_e32 v10, v125, v10
	v_perm_b32 v95, v95, v96, s87
	v_pk_mul_f32 v[98:99], v[122:123], v[0:1] op_sel_hi:[1,0]
	v_pk_mul_f32 v[96:97], v[120:121], v[0:1] op_sel_hi:[1,0]
	v_add_f32_e32 v10, v126, v10
	v_add_f32_e32 v125, v127, v10
	v_mfma_f32_16x16x32_bf16 v[120:123], v[60:63], v[92:95], v[96:99]
	v_mul_f32_e64 v62, v118, v0
	v_mul_f32_e64 v63, v119, v0
	v_pk_mul_f32 v[60:61], v[116:117], v[0:1] op_sel_hi:[1,0]
	v_lshl_add_u64 v[10:11], s[28:29], 0, v[148:149]
	v_lshl_add_u64 v[144:145], v[10:11], 0, v[144:145]
	v_mfma_f32_16x16x32_bf16 v[108:111], v[52:55], v[92:95], v[60:63]
	v_mul_f32_e64 v54, v114, v0
	v_mul_f32_e64 v55, v115, v0
	v_pk_mul_f32 v[52:53], v[112:113], v[0:1] op_sel_hi:[1,0]
	v_lshl_add_u64 v[10:11], v[144:145], 0, s[0:1]
	s_mov_b32 s0, 0xc000
	v_mfma_f32_16x16x32_bf16 v[112:115], v[48:51], v[92:95], v[52:55]
	v_mul_f32_e64 v50, v106, v0
	v_mul_f32_e64 v51, v107, v0
	v_pk_mul_f32 v[48:49], v[104:105], v[0:1] op_sel_hi:[1,0]
	v_fmac_f32_e32 v125, v101, v0
	v_mfma_f32_16x16x32_bf16 v[80:83], v[80:83], v[2:5], v[88:91]
	v_mfma_f32_16x16x32_bf16 v[116:119], v[44:47], v[92:95], v[48:51]
	v_add_co_u32_e32 v44, vcc, s0, v144
	s_mov_b64 s[0:1], 0x2000
	s_nop 0
	v_addc_co_u32_e32 v45, vcc, 0, v145, vcc
	global_load_dwordx4 v[104:107], v[44:45], off
	global_load_dwordx4 v[96:99], v[10:11], off offset:16
	global_load_dwordx4 v[100:103], v[10:11], off offset:3072
	global_load_dwordx4 v[92:95], v[10:11], off offset:3088
	v_lshl_add_u64 v[10:11], s[26:27], 0, v[142:143]
	v_lshl_add_u64 v[142:143], v[10:11], 0, v[146:147]
	v_lshl_add_u64 v[10:11], v[142:143], 0, s[0:1]
	s_movk_i32 s0, 0x2000
	v_add_co_u32_e32 v44, vcc, s0, v142
	s_waitcnt vmcnt(16)
	v_mfma_f32_16x16x32_bf16 v[68:71], v[68:71], v[2:5], v[84:87]
	v_addc_co_u32_e32 v45, vcc, 0, v143, vcc
	global_load_dwordx4 v[60:63], v[44:45], off
	global_load_dwordx4 v[52:55], v[10:11], off offset:256
	global_load_dwordx4 v[48:51], v[10:11], off offset:512
	s_nop 0
	global_load_dwordx4 v[44:47], v[10:11], off offset:768
	v_max_f32_e32 v0, v81, v81
	v_max_f32_e32 v10, v80, v80
	v_max_f32_e32 v0, v10, v0
	v_max_f32_e32 v10, v83, v83
	v_max_f32_e32 v11, v82, v82
	v_max_f32_e32 v10, v11, v10
	v_max_f32_e32 v11, v71, v71
	v_max_f32_e32 v84, v70, v70
	v_max_f32_e32 v11, v84, v11
	v_max3_f32 v11, v68, v69, v11
	v_max3_f32 v0, v0, v10, v11
	v_mov_b32_e32 v10, v0
	s_nop 1
	v_permlane16_swap_b32_e32 v10, v0
	s_waitcnt vmcnt(13)
	v_mfma_f32_16x16x32_bf16 v[76:79], v[76:79], v[6:9], 0
	s_mov_b32 s0, 0x12000
	s_waitcnt lgkmcnt(0)
	v_max_f32_e32 v10, v10, v10
	v_max_f32_e32 v0, v0, v10
	v_mov_b32_e32 v10, v0
	s_nop 1
	v_permlane32_swap_b32_e32 v10, v0
	v_mfma_f32_16x16x32_bf16 v[72:75], v[72:75], v[6:9], 0
	s_waitcnt lgkmcnt(0)
	v_max3_f32 v11, v124, v0, v10
	v_sub_f32_e32 v10, v80, v11
	v_sub_f32_e32 v68, v68, v11
	v_mul_f32_e32 v10, 0x3fb8aa3b, v10
	v_mul_f32_e32 v68, 0x3fb8aa3b, v68
	v_exp_f32_e32 v88, v10
	v_sub_f32_e32 v10, v81, v11
	v_exp_f32_e32 v148, v68
	v_sub_f32_e32 v68, v69, v11
	v_mul_f32_e32 v10, 0x3fb8aa3b, v10
	v_mul_f32_e32 v68, 0x3fb8aa3b, v68
	v_exp_f32_e32 v89, v10
	v_sub_f32_e32 v10, v82, v11
	v_sub_f32_e32 v80, v83, v11
	v_exp_f32_e32 v152, v68
	v_sub_f32_e32 v68, v70, v11
	v_mul_f32_e32 v10, 0x3fb8aa3b, v10
	v_mul_f32_e32 v80, 0x3fb8aa3b, v80
	v_mul_f32_e32 v68, 0x3fb8aa3b, v68
	v_exp_f32_e32 v10, v10
	v_exp_f32_e32 v146, v80
	v_exp_f32_e32 v154, v68
	v_sub_f32_e32 v68, v71, v11
	v_sub_f32_e32 v0, v124, v11
	v_mul_f32_e32 v68, 0x3fb8aa3b, v68
	v_mul_f32_e32 v0, 0x3fb8aa3b, v0
	v_exp_f32_e32 v156, v68
	v_exp_f32_e32 v0, v0
	v_add_u32_e32 v68, 0x8000, v89
	v_add_u32_e32 v69, 0x8000, v88
	v_perm_b32 v68, v68, v69, s87
	v_add_u32_e32 v69, 0x8000, v146
	v_add_u32_e32 v70, 0x8000, v10
	v_perm_b32 v69, v69, v70, s87
	v_add_u32_e32 v70, 0x8000, v152
	v_add_u32_e32 v71, 0x8000, v148
	v_perm_b32 v70, v70, v71, s87
	v_add_u32_e32 v71, 0x8000, v156
	v_add_u32_e32 v80, 0x8000, v154
	v_perm_b32 v71, v71, v80, s87
	v_pk_mul_f32 v[82:83], v[122:123], v[0:1] op_sel_hi:[1,0]
	v_pk_mul_f32 v[80:81], v[120:121], v[0:1] op_sel_hi:[1,0]
	v_mfma_f32_16x16x32_bf16 v[64:67], v[64:67], v[2:5], v[76:79]
	v_mul_f32_e32 v158, v125, v0
	v_mfma_f32_16x16x32_bf16 v[120:123], v[40:43], v[68:71], v[80:83]
	v_mul_f32_e64 v42, v110, v0
	v_mul_f32_e64 v43, v111, v0
	v_pk_mul_f32 v[40:41], v[108:109], v[0:1] op_sel_hi:[1,0]
	s_waitcnt vmcnt(12)
	v_mfma_f32_16x16x32_bf16 v[56:59], v[56:59], v[2:5], v[72:75]
	v_mfma_f32_16x16x32_bf16 v[124:127], v[36:39], v[68:71], v[40:43]
	v_mul_f32_e64 v38, v114, v0
	v_mul_f32_e64 v39, v115, v0
	v_pk_mul_f32 v[36:37], v[112:113], v[0:1] op_sel_hi:[1,0]
	v_max_f32_e32 v72, v65, v65
	v_max_f32_e32 v73, v64, v64
	v_mfma_f32_16x16x32_bf16 v[40:43], v[32:35], v[68:71], v[36:39]
	v_mul_f32_e64 v34, v118, v0
	v_mul_f32_e64 v35, v119, v0
	v_pk_mul_f32 v[32:33], v[116:117], v[0:1] op_sel_hi:[1,0]
	v_add_f32_e32 v0, 0, v88
	v_add_f32_e32 v0, v89, v0
	v_mfma_f32_16x16x32_bf16 v[84:87], v[28:31], v[68:71], v[32:35]
	v_add_co_u32_e32 v28, vcc, s0, v130
	v_max_f32_e32 v72, v73, v72
	s_nop 0
	v_addc_co_u32_e32 v29, vcc, 0, v131, vcc
	global_load_dwordx4 v[112:115], v[28:29], off
	global_load_dwordx4 v[88:91], v[28:29], off offset:16
	global_load_dwordx4 v[108:111], v[28:29], off offset:3072
	global_load_dwordx4 v[80:83], v[28:29], off offset:3088
	v_max_f32_e32 v73, v67, v67
	v_max_f32_e32 v74, v66, v66
	v_max_f32_e32 v73, v74, v73
	v_max_f32_e32 v74, v59, v59
	v_max_f32_e32 v75, v58, v58
	v_max_f32_e32 v74, v75, v74
	v_max3_f32 v74, v56, v57, v74
	v_max3_f32 v72, v72, v73, v74
	v_mov_b32_e32 v73, v72
	s_nop 1
	v_permlane16_swap_b32_e32 v73, v72
	s_waitcnt vmcnt(11)
	v_mfma_f32_16x16x32_bf16 v[104:107], v[104:107], v[6:9], 0
	s_movk_i32 s0, 0x3000
	v_add_co_u32_e32 v28, vcc, s0, v150
	s_waitcnt lgkmcnt(0)
	v_max_f32_e32 v73, v73, v73
	v_max_f32_e32 v72, v72, v73
	v_mov_b32_e32 v73, v72
	s_nop 1
	v_permlane32_swap_b32_e32 v73, v72
	s_waitcnt vmcnt(9)
	v_mfma_f32_16x16x32_bf16 v[100:103], v[100:103], v[6:9], 0
	s_mov_b64 s[0:1], 0x18000
	v_addc_co_u32_e32 v29, vcc, 0, v151, vcc
	s_waitcnt lgkmcnt(0)
	v_max3_f32 v141, v11, v72, v73
	v_sub_f32_e32 v11, v11, v141
	v_mul_f32_e32 v72, 0x3fb8aa3b, v11
	v_sub_f32_e32 v11, v64, v141
	v_sub_f32_e32 v64, v65, v141
	v_sub_f32_e32 v56, v56, v141
	v_mul_f32_e32 v64, 0x3fb8aa3b, v64
	v_mul_f32_e32 v56, 0x3fb8aa3b, v56
	v_exp_f32_e32 v147, v64
	v_sub_f32_e32 v64, v66, v141
	v_exp_f32_e32 v155, v56
	v_sub_f32_e32 v56, v57, v141
	v_mul_f32_e32 v11, 0x3fb8aa3b, v11
	v_mul_f32_e32 v64, 0x3fb8aa3b, v64
	v_mul_f32_e32 v56, 0x3fb8aa3b, v56
	v_exp_f32_e32 v11, v11
	v_exp_f32_e32 v149, v64
	v_sub_f32_e32 v64, v67, v141
	v_exp_f32_e32 v157, v56
	v_sub_f32_e32 v56, v58, v141
	v_mul_f32_e32 v64, 0x3fb8aa3b, v64
	v_mul_f32_e32 v56, 0x3fb8aa3b, v56
	v_exp_f32_e32 v153, v64
	v_exp_f32_e32 v159, v56
	v_sub_f32_e32 v56, v59, v141
	v_mul_f32_e32 v56, 0x3fb8aa3b, v56
	v_exp_f32_e32 v73, v56
	v_add_u32_e32 v57, 0x8000, v11
	v_pk_add_f32 v[10:11], v[10:11], v[0:1]
	v_exp_f32_e32 v72, v72
	v_add_u32_e32 v56, 0x8000, v147
	v_pk_add_f32 v[10:11], v[146:147], v[10:11]
	v_perm_b32 v56, v56, v57, s87
	v_add_u32_e32 v57, 0x8000, v153
	v_add_u32_e32 v58, 0x8000, v149
	v_pk_add_f32 v[10:11], v[148:149], v[10:11]
	v_perm_b32 v57, v57, v58, s87
	v_add_u32_e32 v58, 0x8000, v157
	v_add_u32_e32 v59, 0x8000, v155
	v_pk_add_f32 v[10:11], v[152:153], v[10:11]
	v_perm_b32 v58, v58, v59, s87
	v_add_u32_e32 v59, 0x8000, v73
	v_add_u32_e32 v64, 0x8000, v159
	v_pk_add_f32 v[10:11], v[154:155], v[10:11]
	v_mfma_f32_16x16x32_bf16 v[96:99], v[96:99], v[2:5], v[104:107]
	v_perm_b32 v59, v59, v64, s87
	v_pk_mul_f32 v[66:67], v[122:123], v[72:73] op_sel_hi:[1,0]
	v_pk_mul_f32 v[64:65], v[120:121], v[72:73] op_sel_hi:[1,0]
	v_pk_add_f32 v[10:11], v[156:157], v[10:11]
	s_waitcnt vmcnt(8)
	v_mfma_f32_16x16x32_bf16 v[92:95], v[92:95], v[2:5], v[100:103]
	v_add_f32_e64 v10, v158, v10
	v_add_f32_e64 v11, v159, v11
	v_max_f32_e32 v0, v97, v97
	global_load_dwordx4 v[68:71], v[28:29], off
	global_load_dwordx4 v[36:39], v[28:29], off offset:256
	global_load_dwordx4 v[32:35], v[28:29], off offset:512
	s_nop 0
	global_load_dwordx4 v[28:31], v[28:29], off offset:768
	v_mfma_f32_16x16x32_bf16 v[120:123], v[24:27], v[56:59], v[64:67]
	v_mul_f32_e64 v26, v126, v72
	v_mul_f32_e64 v27, v127, v72
	v_pk_mul_f32 v[24:25], v[124:125], v[72:73] op_sel_hi:[1,0]
	v_max_f32_e32 v100, v98, v98
	v_max_f32_e32 v101, v94, v94
	v_mfma_f32_16x16x32_bf16 v[116:119], v[20:23], v[56:59], v[24:27]
	v_mul_f32_e64 v22, v42, v72
	v_mul_f32_e64 v23, v43, v72
	v_pk_mul_f32 v[20:21], v[40:41], v[72:73] op_sel_hi:[1,0]
	v_add_f32_e32 v27, v11, v73
	s_nop 0
	v_mfma_f32_16x16x32_bf16 v[40:43], v[16:19], v[56:59], v[20:23]
	v_mul_f32_e64 v18, v86, v72
	v_mul_f32_e64 v19, v87, v72
	v_pk_mul_f32 v[16:17], v[84:85], v[72:73] op_sel_hi:[1,0]
	v_fmac_f32_e32 v27, v10, v72
	v_lshl_add_u64 v[10:11], v[144:145], 0, s[0:1]
	s_mov_b32 s0, 0x18000
	v_max_f32_e32 v26, v96, v96
	v_mfma_f32_16x16x32_bf16 v[56:59], v[12:15], v[56:59], v[16:19]
	v_add_co_u32_e32 v12, vcc, s0, v144
	v_max_f32_e32 v0, v26, v0
	v_max_f32_e32 v26, v99, v99
	v_addc_co_u32_e32 v13, vcc, 0, v145, vcc
	v_max_f32_e32 v26, v100, v26
	v_max_f32_e32 v100, v95, v95
	global_load_dwordx4 v[84:87], v[12:13], off
	global_load_dwordx4 v[72:75], v[10:11], off offset:16
	global_load_dwordx4 v[76:79], v[10:11], off offset:3072
	global_load_dwordx4 v[64:67], v[10:11], off offset:3088
	v_max_f32_e32 v100, v101, v100
	v_max3_f32 v100, v92, v93, v100
	v_max3_f32 v0, v0, v26, v100
	v_mov_b32_e32 v26, v0
	s_nop 1
	v_permlane16_swap_b32_e32 v26, v0
	s_mov_b64 s[0:1], 0x4000
	v_lshl_add_u64 v[10:11], v[142:143], 0, s[0:1]
	s_movk_i32 s0, 0x5000
	v_add_co_u32_e32 v156, vcc, s0, v142
	s_waitcnt lgkmcnt(0)
	v_max_f32_e32 v26, v26, v26
	v_max_f32_e32 v0, v0, v26
	v_mov_b32_e32 v26, v0
	s_nop 1
	v_permlane32_swap_b32_e32 v26, v0
	s_mov_b64 s[0:1], 0x1e000
	v_addc_co_u32_e32 v157, vcc, 0, v143, vcc
	global_load_dwordx4 v[22:25], v[156:157], off offset:-4096
	global_load_dwordx4 v[18:21], v[10:11], off offset:256
	global_load_dwordx4 v[14:17], v[10:11], off offset:512
	s_nop 0
	global_load_dwordx4 v[10:13], v[10:11], off offset:768
	s_waitcnt lgkmcnt(0)
	v_max3_f32 v125, v141, v0, v26
	v_sub_f32_e32 v26, v96, v125
	v_sub_f32_e32 v92, v92, v125
	v_mul_f32_e32 v26, 0x3fb8aa3b, v26
	v_mul_f32_e32 v92, 0x3fb8aa3b, v92
	v_exp_f32_e32 v100, v26
	v_sub_f32_e32 v26, v97, v125
	v_exp_f32_e32 v126, v92
	v_sub_f32_e32 v92, v93, v125
	v_sub_f32_e32 v0, v141, v125
	v_mul_f32_e32 v26, 0x3fb8aa3b, v26
	v_mul_f32_e32 v92, 0x3fb8aa3b, v92
	v_mul_f32_e32 v0, 0x3fb8aa3b, v0
	v_exp_f32_e32 v101, v26
	v_sub_f32_e32 v26, v98, v125
	v_sub_f32_e32 v96, v99, v125
	v_exp_f32_e32 v146, v92
	v_sub_f32_e32 v92, v94, v125
	v_mul_f32_e32 v26, 0x3fb8aa3b, v26
	v_mul_f32_e32 v96, 0x3fb8aa3b, v96
	v_mul_f32_e32 v92, 0x3fb8aa3b, v92
	v_exp_f32_e32 v0, v0
	v_exp_f32_e32 v26, v26
	v_exp_f32_e32 v124, v96
	v_exp_f32_e32 v148, v92
	v_sub_f32_e32 v92, v95, v125
	v_mul_f32_e32 v92, 0x3fb8aa3b, v92
	v_exp_f32_e32 v152, v92
	v_mul_f32_e32 v154, v27, v0
	v_add_u32_e32 v27, 0x8000, v101
	v_add_u32_e32 v92, 0x8000, v100
	v_perm_b32 v92, v27, v92, s87
	v_add_u32_e32 v27, 0x8000, v124
	v_add_u32_e32 v93, 0x8000, v26
	v_perm_b32 v93, v27, v93, s87
	v_add_u32_e32 v27, 0x8000, v146
	v_add_u32_e32 v94, 0x8000, v126
	v_perm_b32 v94, v27, v94, s87
	v_add_u32_e32 v27, 0x8000, v152
	v_add_u32_e32 v95, 0x8000, v148
	v_perm_b32 v95, v27, v95, s87
	v_pk_mul_f32 v[42:43], v[42:43], v[0:1] op_sel_hi:[1,0]
	v_pk_mul_f32 v[40:41], v[40:41], v[0:1] op_sel_hi:[1,0]
	v_pk_mul_f32 v[98:99], v[122:123], v[0:1] op_sel_hi:[1,0]
	v_pk_mul_f32 v[96:97], v[120:121], v[0:1] op_sel_hi:[1,0]
	s_waitcnt vmcnt(17)
	v_mfma_f32_16x16x32_bf16 v[104:107], v[48:51], v[92:95], v[40:43]
	s_nop 2
	v_mul_f32_e64 v42, v58, v0
	v_mul_f32_e64 v43, v59, v0
	v_pk_mul_f32 v[40:41], v[56:57], v[0:1] op_sel_hi:[1,0]
	v_mfma_f32_16x16x32_bf16 v[120:123], v[60:63], v[92:95], v[96:99]
	v_mul_f32_e64 v62, v118, v0
	v_mul_f32_e64 v63, v119, v0
	v_pk_mul_f32 v[60:61], v[116:117], v[0:1] op_sel_hi:[1,0]
	v_add_f32_e32 v0, 0, v100
	s_waitcnt vmcnt(16)
	v_mfma_f32_16x16x32_bf16 v[56:59], v[44:47], v[92:95], v[40:43]
	v_add_f32_e32 v0, v101, v0
	s_nop 1
	v_lshl_add_u64 v[40:41], v[144:145], 0, s[0:1]
	s_mov_b32 s0, 0x1e000
	v_add_co_u32_e32 v42, vcc, s0, v144
	v_mfma_f32_16x16x32_bf16 v[116:119], v[52:55], v[92:95], v[60:63]
	s_nop 0
	v_addc_co_u32_e32 v43, vcc, 0, v145, vcc
	global_load_dwordx4 v[100:103], v[42:43], off
	global_load_dwordx4 v[92:95], v[40:41], off offset:16
	global_load_dwordx4 v[96:99], v[40:41], off offset:3072
	global_load_dwordx4 v[60:63], v[40:41], off offset:3088
	s_waitcnt vmcnt(19)
	v_mfma_f32_16x16x32_bf16 v[112:115], v[112:115], v[6:9], 0
	s_mov_b64 s[0:1], 0x5000
	v_lshl_add_u64 v[40:41], v[142:143], 0, s[0:1]
	global_load_dwordx4 v[52:55], v[156:157], off
	global_load_dwordx4 v[48:51], v[40:41], off offset:256
	global_load_dwordx4 v[44:47], v[40:41], off offset:512
	s_nop 0
	global_load_dwordx4 v[40:43], v[40:41], off offset:768
	s_waitcnt vmcnt(21)
	v_mfma_f32_16x16x32_bf16 v[108:111], v[108:111], v[6:9], 0
	s_mov_b32 s0, 0x24000
	v_mfma_f32_16x16x32_bf16 v[88:91], v[88:91], v[2:5], v[112:115]
	s_waitcnt vmcnt(20)
	v_mfma_f32_16x16x32_bf16 v[80:83], v[80:83], v[2:5], v[108:111]
	s_waitcnt vmcnt(15)
	v_mfma_f32_16x16x32_bf16 v[84:87], v[84:87], v[6:9], 0
	s_nop 3
	v_max_f32_e32 v27, v89, v89
	v_max_f32_e32 v108, v88, v88
	v_max_f32_e32 v27, v108, v27
	v_max_f32_e32 v108, v91, v91
	v_max_f32_e32 v109, v90, v90
	v_max_f32_e32 v108, v109, v108
	v_max_f32_e32 v109, v83, v83
	v_max_f32_e32 v110, v82, v82
	v_max_f32_e32 v109, v110, v109
	v_max3_f32 v109, v80, v81, v109
	v_max3_f32 v27, v27, v108, v109
	v_mov_b32_e32 v108, v27
	s_nop 1
	v_permlane16_swap_b32_e32 v108, v27
	s_waitcnt vmcnt(13)
	v_mfma_f32_16x16x32_bf16 v[76:79], v[76:79], v[6:9], 0
	s_waitcnt lgkmcnt(0)
	v_max_f32_e32 v108, v108, v108
	v_max_f32_e32 v27, v27, v108
	v_mov_b32_e32 v108, v27
	s_nop 1
	v_permlane32_swap_b32_e32 v108, v27
	v_mfma_f32_16x16x32_bf16 v[72:75], v[72:75], v[2:5], v[84:87]
	s_waitcnt lgkmcnt(0)
	v_max3_f32 v141, v125, v27, v108
	v_sub_f32_e32 v27, v125, v141
	v_mul_f32_e32 v108, 0x3fb8aa3b, v27
	v_sub_f32_e32 v27, v88, v141
	v_sub_f32_e32 v88, v89, v141
	v_sub_f32_e32 v80, v80, v141
	v_mul_f32_e32 v88, 0x3fb8aa3b, v88
	v_mul_f32_e32 v80, 0x3fb8aa3b, v80
	v_exp_f32_e32 v125, v88
	v_sub_f32_e32 v88, v90, v141
	v_exp_f32_e32 v149, v80
	v_sub_f32_e32 v80, v81, v141
	v_mul_f32_e32 v88, 0x3fb8aa3b, v88
	v_mul_f32_e32 v80, 0x3fb8aa3b, v80
	v_mul_f32_e32 v27, 0x3fb8aa3b, v27
	v_exp_f32_e32 v127, v88
	v_sub_f32_e32 v88, v91, v141
	v_exp_f32_e32 v153, v80
	v_sub_f32_e32 v80, v82, v141
	v_exp_f32_e32 v27, v27
	v_mul_f32_e32 v88, 0x3fb8aa3b, v88
	v_mul_f32_e32 v80, 0x3fb8aa3b, v80
	v_exp_f32_e32 v147, v88
	v_exp_f32_e32 v155, v80
	v_sub_f32_e32 v80, v83, v141
	v_mul_f32_e32 v80, 0x3fb8aa3b, v80
	v_exp_f32_e32 v157, v80
	v_exp_f32_e32 v156, v108
	v_add_u32_e32 v80, 0x8000, v125
	v_add_u32_e32 v81, 0x8000, v27
	v_pk_add_f32 v[26:27], v[26:27], v[0:1]
	v_perm_b32 v80, v80, v81, s87
	v_add_u32_e32 v81, 0x8000, v147
	v_add_u32_e32 v82, 0x8000, v127
	v_pk_add_f32 v[26:27], v[124:125], v[26:27]
	v_perm_b32 v81, v81, v82, s87
	v_add_u32_e32 v82, 0x8000, v153
	v_add_u32_e32 v83, 0x8000, v149
	v_pk_add_f32 v[26:27], v[126:127], v[26:27]
	v_perm_b32 v82, v82, v83, s87
	v_add_u32_e32 v83, 0x8000, v157
	v_add_u32_e32 v88, 0x8000, v155
	v_pk_add_f32 v[26:27], v[146:147], v[26:27]
	v_perm_b32 v83, v83, v88, s87
	v_pk_mul_f32 v[90:91], v[122:123], v[156:157] op_sel_hi:[1,0]
	v_pk_mul_f32 v[88:89], v[120:121], v[156:157] op_sel_hi:[1,0]
	v_pk_add_f32 v[26:27], v[148:149], v[26:27]
	s_waitcnt vmcnt(12)
	v_mfma_f32_16x16x32_bf16 v[64:67], v[64:67], v[2:5], v[76:79]
	v_add_f32_e64 v26, v152, v26
	v_add_f32_e64 v27, v153, v27
	v_max_f32_e32 v0, v73, v73
	v_pk_add_f32 v[26:27], v[154:155], v[26:27]
	v_mfma_f32_16x16x32_bf16 v[112:115], v[68:71], v[80:83], v[88:91]
	v_mul_f32_e64 v70, v118, v156
	v_mul_f32_e64 v71, v119, v156
	v_pk_mul_f32 v[68:69], v[116:117], v[156:157] op_sel_hi:[1,0]
	v_max_f32_e32 v76, v74, v74
	v_max_f32_e32 v77, v66, v66
	v_mfma_f32_16x16x32_bf16 v[120:123], v[36:39], v[80:83], v[68:71]
	v_mul_f32_e64 v38, v106, v156
	v_mul_f32_e64 v39, v107, v156
	v_pk_mul_f32 v[36:37], v[104:105], v[156:157] op_sel_hi:[1,0]
	s_waitcnt vmcnt(7)
	v_mfma_f32_16x16x32_bf16 v[100:103], v[100:103], v[6:9], 0
	v_mfma_f32_16x16x32_bf16 v[108:111], v[32:35], v[80:83], v[36:39]
	v_mul_f32_e64 v34, v58, v156
	v_mul_f32_e64 v35, v59, v156
	v_pk_mul_f32 v[32:33], v[56:57], v[156:157] op_sel_hi:[1,0]
	v_add_f32_e32 v38, v27, v157
	v_fmac_f32_e32 v38, v26, v156
	v_add_co_u32_e32 v26, vcc, s0, v130
	v_max_f32_e32 v39, v72, v72
	s_nop 0
	v_addc_co_u32_e32 v27, vcc, 0, v131, vcc
	v_mfma_f32_16x16x32_bf16 v[116:119], v[28:31], v[80:83], v[32:35]
	global_load_dwordx4 v[104:107], v[26:27], off
	global_load_dwordx4 v[80:83], v[26:27], off offset:16
	global_load_dwordx4 v[88:91], v[26:27], off offset:3072
	global_load_dwordx4 v[68:71], v[26:27], off offset:3088
	v_max_f32_e32 v0, v39, v0
	v_max_f32_e32 v39, v75, v75
	v_max_f32_e32 v39, v76, v39
	v_max_f32_e32 v76, v67, v67
	v_max_f32_e32 v76, v77, v76
	v_max3_f32 v76, v64, v65, v76
	v_max3_f32 v0, v0, v39, v76
	v_mov_b32_e32 v39, v0
	s_nop 1
	v_permlane16_swap_b32_e32 v39, v0
	s_movk_i32 s0, 0x6000
	v_add_co_u32_e32 v26, vcc, s0, v150
	s_waitcnt vmcnt(9)
	v_mfma_f32_16x16x32_bf16 v[96:99], v[96:99], v[6:9], 0
	s_waitcnt lgkmcnt(0)
	v_max_f32_e32 v39, v39, v39
	v_max_f32_e32 v0, v0, v39
	v_mov_b32_e32 v39, v0
	s_nop 1
	v_permlane32_swap_b32_e32 v39, v0
	v_mfma_f32_16x16x32_bf16 v[92:95], v[92:95], v[2:5], v[100:103]
	v_addc_co_u32_e32 v27, vcc, 0, v151, vcc
	s_mov_b64 s[0:1], 0x2a000
	s_waitcnt lgkmcnt(0)
	v_max3_f32 v39, v141, v0, v39
	v_sub_f32_e32 v72, v72, v39
	v_mul_f32_e32 v72, 0x3fb8aa3b, v72
	v_exp_f32_e32 v76, v72
	v_sub_f32_e32 v72, v73, v39
	v_sub_f32_e32 v64, v64, v39
	v_mul_f32_e32 v72, 0x3fb8aa3b, v72
	v_mul_f32_e32 v64, 0x3fb8aa3b, v64
	v_exp_f32_e32 v77, v72
	v_sub_f32_e32 v72, v74, v39
	v_exp_f32_e32 v148, v64
	v_sub_f32_e32 v64, v65, v39
	v_sub_f32_e32 v0, v141, v39
	v_mul_f32_e32 v72, 0x3fb8aa3b, v72
	v_mul_f32_e32 v64, 0x3fb8aa3b, v64
	v_mul_f32_e32 v0, 0x3fb8aa3b, v0
	v_exp_f32_e32 v130, v72
	v_sub_f32_e32 v72, v75, v39
	v_exp_f32_e32 v150, v64
	v_sub_f32_e32 v64, v66, v39
	v_mul_f32_e32 v72, 0x3fb8aa3b, v72
	v_mul_f32_e32 v64, 0x3fb8aa3b, v64
	v_exp_f32_e32 v0, v0
	v_exp_f32_e32 v146, v72
	v_exp_f32_e32 v152, v64
	v_sub_f32_e32 v64, v67, v39
	v_mul_f32_e32 v64, 0x3fb8aa3b, v64
	v_exp_f32_e32 v154, v64
	v_mul_f32_e32 v156, v38, v0
	v_add_u32_e32 v38, 0x8000, v77
	v_add_u32_e32 v64, 0x8000, v76
	v_perm_b32 v64, v38, v64, s87
	v_add_u32_e32 v38, 0x8000, v146
	v_add_u32_e32 v65, 0x8000, v130
	v_perm_b32 v65, v38, v65, s87
	v_add_u32_e32 v38, 0x8000, v150
	v_add_u32_e32 v66, 0x8000, v148
	s_waitcnt vmcnt(8)
	v_mfma_f32_16x16x32_bf16 v[60:63], v[60:63], v[2:5], v[96:99]
	v_perm_b32 v66, v38, v66, s87
	v_add_u32_e32 v38, 0x8000, v154
	v_add_u32_e32 v67, 0x8000, v152
	v_perm_b32 v67, v38, v67, s87
	v_max_f32_e32 v38, v93, v93
	v_max_f32_e32 v96, v92, v92
	v_max_f32_e32 v38, v96, v38
	v_max_f32_e32 v96, v95, v95
	v_max_f32_e32 v97, v94, v94
	v_max_f32_e32 v96, v97, v96
	v_max_f32_e32 v97, v63, v63
	v_max_f32_e32 v98, v62, v62
	v_max_f32_e32 v97, v98, v97
	v_max3_f32 v97, v60, v61, v97
	v_max3_f32 v38, v38, v96, v97
	v_mov_b32_e32 v96, v38
	s_nop 1
	v_permlane16_swap_b32_e32 v96, v38
	v_pk_mul_f32 v[74:75], v[114:115], v[0:1] op_sel_hi:[1,0]
	v_pk_mul_f32 v[72:73], v[112:113], v[0:1] op_sel_hi:[1,0]
	global_load_dwordx4 v[56:59], v[26:27], off
	global_load_dwordx4 v[34:37], v[26:27], off offset:256
	global_load_dwordx4 v[30:33], v[26:27], off offset:512
	s_nop 0
	global_load_dwordx4 v[26:29], v[26:27], off offset:768
	v_mfma_f32_16x16x32_bf16 v[124:127], v[22:25], v[64:67], v[72:75]
	v_mul_f32_e64 v24, v122, v0
	v_mul_f32_e64 v25, v123, v0
	v_pk_mul_f32 v[22:23], v[120:121], v[0:1] op_sel_hi:[1,0]
	s_waitcnt lgkmcnt(0)
	v_max_f32_e32 v96, v96, v96
	v_max_f32_e32 v38, v38, v96
	v_mfma_f32_16x16x32_bf16 v[120:123], v[18:21], v[64:67], v[22:25]
	v_mul_f32_e64 v20, v110, v0
	v_mul_f32_e64 v21, v111, v0
	v_pk_mul_f32 v[18:19], v[108:109], v[0:1] op_sel_hi:[1,0]
	v_mov_b32_e32 v96, v38
	s_nop 1
	v_permlane32_swap_b32_e32 v96, v38
	s_waitcnt vmcnt(5)
	v_mfma_f32_16x16x32_bf16 v[88:91], v[88:91], v[6:9], 0
	v_mov_b32_e32 v141, v1
	s_waitcnt lgkmcnt(0)
	v_max3_f32 v97, v39, v38, v96
	v_mfma_f32_16x16x32_bf16 v[108:111], v[14:17], v[64:67], v[18:21]
	v_mul_f32_e64 v16, v118, v0
	v_mul_f32_e64 v17, v119, v0
	v_pk_mul_f32 v[14:15], v[116:117], v[0:1] op_sel_hi:[1,0]
	v_add_f32_e32 v0, 0, v76
	v_add_f32_e32 v0, v77, v0
	v_mfma_f32_16x16x32_bf16 v[112:115], v[10:13], v[64:67], v[14:17]
	v_lshl_add_u64 v[10:11], v[144:145], 0, s[0:1]
	s_mov_b32 s0, 0x2a000
	v_add_co_u32_e32 v12, vcc, s0, v144
	v_sub_f32_e32 v38, v39, v97
	s_nop 0
	v_addc_co_u32_e32 v13, vcc, 0, v145, vcc
	global_load_dwordx4 v[84:87], v[12:13], off
	global_load_dwordx4 v[72:75], v[10:11], off offset:16
	global_load_dwordx4 v[76:79], v[10:11], off offset:3072
	global_load_dwordx4 v[64:67], v[10:11], off offset:3088
	v_sub_f32_e32 v39, v92, v97
	v_mul_f32_e32 v39, 0x3fb8aa3b, v39
	v_exp_f32_e32 v131, v39
	v_sub_f32_e32 v39, v93, v97
	v_mul_f32_e32 v39, 0x3fb8aa3b, v39
	v_exp_f32_e32 v147, v39
	v_sub_f32_e32 v39, v94, v97
	v_mul_f32_e32 v39, 0x3fb8aa3b, v39
	v_exp_f32_e32 v149, v39
	v_sub_f32_e32 v39, v95, v97
	v_mul_f32_e32 v39, 0x3fb8aa3b, v39
	v_exp_f32_e32 v151, v39
	v_sub_f32_e32 v39, v60, v97
	v_mul_f32_e32 v39, 0x3fb8aa3b, v39
	v_exp_f32_e32 v153, v39
	v_sub_f32_e32 v39, v61, v97
	v_mul_f32_e32 v39, 0x3fb8aa3b, v39
	v_exp_f32_e32 v155, v39
	v_sub_f32_e32 v39, v62, v97
	v_mul_f32_e32 v39, 0x3fb8aa3b, v39
	v_exp_f32_e32 v157, v39
	v_sub_f32_e32 v39, v63, v97
	v_mul_f32_e32 v39, 0x3fb8aa3b, v39
	v_mul_f32_e32 v38, 0x3fb8aa3b, v38
	v_exp_f32_e32 v98, v39
	v_exp_f32_e32 v96, v38
	v_add_u32_e32 v38, 0x8000, v147
	v_add_u32_e32 v39, 0x8000, v131
	v_perm_b32 v60, v38, v39, s87
	v_add_u32_e32 v38, 0x8000, v151
	v_add_u32_e32 v39, 0x8000, v149
	v_perm_b32 v61, v38, v39, s87
	v_add_u32_e32 v38, 0x8000, v155
	v_add_u32_e32 v39, 0x8000, v153
	v_perm_b32 v62, v38, v39, s87
	v_add_u32_e32 v38, 0x8000, v98
	v_add_u32_e32 v39, 0x8000, v157
	v_perm_b32 v63, v38, v39, s87
	v_pk_mul_f32 v[94:95], v[126:127], v[96:97] op_sel_hi:[1,0]
	v_pk_mul_f32 v[92:93], v[124:125], v[96:97] op_sel_hi:[1,0]
	s_waitcnt vmcnt(8)
	v_mfma_f32_16x16x32_bf16 v[88:91], v[68:71], v[2:5], v[88:91]
	s_mov_b64 s[0:1], 0x7000
	v_lshl_add_u64 v[10:11], v[142:143], 0, s[0:1]
	s_movk_i32 s0, 0x7000
	v_mfma_f32_16x16x32_bf16 v[52:55], v[52:55], v[60:63], v[92:95]
	v_add_co_u32_e32 v12, vcc, s0, v142
	s_nop 2
	v_max_f32_e32 v69, v90, v90
	v_pk_mul_f32 v[94:95], v[122:123], v[96:97] op_sel_hi:[1,0]
	v_pk_mul_f32 v[92:93], v[120:121], v[96:97] op_sel_hi:[1,0]
	v_addc_co_u32_e32 v13, vcc, 0, v143, vcc
	s_nop 0
	v_mfma_f32_16x16x32_bf16 v[48:51], v[48:51], v[60:63], v[92:95]
	global_load_dwordx4 v[22:25], v[12:13], off
	global_load_dwordx4 v[18:21], v[10:11], off offset:256
	global_load_dwordx4 v[14:17], v[10:11], off offset:512
	s_nop 0
	global_load_dwordx4 v[10:13], v[10:11], off offset:768
	v_pk_mul_f32 v[94:95], v[110:111], v[96:97] op_sel_hi:[1,0]
	v_pk_mul_f32 v[92:93], v[108:109], v[96:97] op_sel_hi:[1,0]
	s_mov_b64 s[0:1], 0xd800200
	s_nop 0
	v_mfma_f32_16x16x32_bf16 v[44:47], v[44:47], v[60:63], v[92:95]
	s_nop 2
	v_mul_f32_e64 v94, v114, v96
	v_mul_f32_e64 v95, v115, v96
	v_pk_mul_f32 v[92:93], v[112:113], v[96:97] op_sel_hi:[1,0]
	s_nop 1
	v_mfma_f32_16x16x32_bf16 v[38:41], v[40:43], v[60:63], v[92:95]
	v_add_f32_e64 v42, v130, v0
	v_add_f32_e64 v43, v131, v1
	v_pk_add_f32 v[42:43], v[146:147], v[42:43]
	v_mfma_f32_16x16x32_bf16 v[60:63], v[104:107], v[6:9], 0
	v_add_f32_e64 v42, v148, v42
	v_add_f32_e64 v43, v149, v43
	v_pk_add_f32 v[42:43], v[150:151], v[42:43]
	v_mfma_f32_16x16x32_bf16 v[60:63], v[80:83], v[2:5], v[60:63]
	v_add_f32_e64 v42, v152, v42
	v_add_f32_e64 v43, v153, v43
	v_pk_add_f32 v[42:43], v[154:155], v[42:43]
	s_nop 0
	v_pk_add_f32 v[42:43], v[156:157], v[42:43]
	s_nop 2
	v_max_f32_e32 v0, v61, v61
	v_add_f32_e32 v43, v43, v98
	v_fmac_f32_e32 v43, v42, v96
	v_max_f32_e32 v42, v60, v60
	v_max_f32_e32 v0, v42, v0
	v_max_f32_e32 v42, v63, v63
	v_max_f32_e32 v68, v62, v62
	v_max_f32_e32 v42, v68, v42
	v_max_f32_e32 v68, v91, v91
	v_max_f32_e32 v68, v69, v68
	v_max3_f32 v68, v88, v89, v68
	v_max3_f32 v0, v0, v42, v68
	v_mov_b32_e32 v42, v0
	s_nop 1
	v_permlane16_swap_b32_e32 v42, v0
	s_waitcnt lgkmcnt(0)
	v_max_f32_e32 v42, v42, v42
	v_max_f32_e32 v0, v0, v42
	v_mov_b32_e32 v42, v0
	s_nop 1
	v_permlane32_swap_b32_e32 v42, v0
	s_waitcnt lgkmcnt(0)
	v_max3_f32 v69, v97, v0, v42
	v_sub_f32_e32 v42, v60, v69
	v_mul_f32_e32 v42, 0x3fb8aa3b, v42
	v_exp_f32_e32 v71, v42
	v_sub_f32_e32 v42, v61, v69
	v_mul_f32_e32 v42, 0x3fb8aa3b, v42
	v_exp_f32_e32 v61, v42
	v_sub_f32_e32 v42, v62, v69
	v_mul_f32_e32 v42, 0x3fb8aa3b, v42
	v_exp_f32_e32 v82, v42
	v_sub_f32_e32 v42, v63, v69
	v_mul_f32_e32 v42, 0x3fb8aa3b, v42
	v_exp_f32_e32 v80, v42
	v_sub_f32_e32 v42, v88, v69
	v_mul_f32_e32 v42, 0x3fb8aa3b, v42
	v_exp_f32_e32 v70, v42
	v_sub_f32_e32 v42, v89, v69
	v_sub_f32_e32 v0, v97, v69
	v_mul_f32_e32 v42, 0x3fb8aa3b, v42
	v_mul_f32_e32 v0, 0x3fb8aa3b, v0
	v_exp_f32_e32 v68, v42
	v_sub_f32_e32 v42, v90, v69
	v_mul_f32_e32 v42, 0x3fb8aa3b, v42
	v_exp_f32_e32 v0, v0
	v_exp_f32_e32 v62, v42
	v_sub_f32_e32 v42, v91, v69
	v_mul_f32_e32 v42, 0x3fb8aa3b, v42
	v_exp_f32_e32 v60, v42
	v_mul_f32_e32 v42, v43, v0
	v_add_u32_e32 v43, 0x8000, v61
	v_add_u32_e32 v63, 0x8000, v71
	v_perm_b32 v88, v43, v63, s87
	v_add_u32_e32 v43, 0x8000, v80
	v_add_u32_e32 v63, 0x8000, v82
	v_perm_b32 v89, v43, v63, s87
	v_add_u32_e32 v43, 0x8000, v68
	v_add_u32_e32 v63, 0x8000, v70
	v_perm_b32 v90, v43, v63, s87
	v_add_u32_e32 v43, 0x8000, v60
	v_add_u32_e32 v63, 0x8000, v62
	v_perm_b32 v91, v43, v63, s87
	v_pk_mul_f32 v[40:41], v[40:41], v[0:1] op_sel_hi:[1,0]
	v_pk_mul_f32 v[38:39], v[38:39], v[0:1] op_sel_hi:[1,0]
	v_pk_mul_f32 v[54:55], v[54:55], v[0:1] op_sel_hi:[1,0]
	v_pk_mul_f32 v[52:53], v[52:53], v[0:1] op_sel_hi:[1,0]
	s_waitcnt vmcnt(8)
	v_mfma_f32_16x16x32_bf16 v[26:29], v[26:29], v[88:91], v[38:41]
	v_mul_f32_e64 v50, v50, v0
	v_mul_f32_e64 v51, v51, v0
	v_pk_mul_f32 v[48:49], v[48:49], v[0:1] op_sel_hi:[1,0]
	v_pk_mul_f32 v[46:47], v[46:47], v[0:1] op_sel_hi:[1,0]
	s_waitcnt vmcnt(7)
	v_mfma_f32_16x16x32_bf16 v[38:41], v[84:87], v[6:9], 0
	v_mul_f32_e64 v44, v44, v0
	v_mul_f32_e64 v45, v45, v0
	v_add_f32_e32 v0, 0, v71
	v_add_f32_e32 v0, v61, v0
	s_waitcnt vmcnt(5)
	v_mfma_f32_16x16x32_bf16 v[6:9], v[76:79], v[6:9], 0
	v_mfma_f32_16x16x32_bf16 v[38:41], v[72:75], v[2:5], v[38:41]
	s_waitcnt vmcnt(4)
	v_mfma_f32_16x16x32_bf16 v[2:5], v[64:67], v[2:5], v[6:9]
	v_mfma_f32_16x16x32_bf16 v[52:55], v[56:59], v[88:91], v[52:55]
	s_nop 4
	v_max_f32_e32 v6, v39, v39
	v_max_f32_e32 v7, v38, v38
	v_max_f32_e32 v6, v7, v6
	v_max_f32_e32 v7, v41, v41
	v_max_f32_e32 v8, v40, v40
	v_max_f32_e32 v7, v8, v7
	v_max_f32_e32 v8, v5, v5
	v_max_f32_e32 v9, v4, v4
	v_max_f32_e32 v8, v9, v8
	v_max3_f32 v8, v2, v3, v8
	v_max3_f32 v6, v6, v7, v8
	v_mov_b32_e32 v7, v6
	s_nop 1
	v_permlane16_swap_b32_e32 v7, v6
	v_mfma_f32_16x16x32_bf16 v[34:37], v[34:37], v[88:91], v[48:51]
	s_waitcnt lgkmcnt(0)
	v_max_f32_e32 v7, v7, v7
	v_max_f32_e32 v6, v6, v7
	v_mov_b32_e32 v7, v6
	s_nop 1
	v_permlane32_swap_b32_e32 v7, v6
	v_mfma_f32_16x16x32_bf16 v[30:33], v[30:33], v[88:91], v[44:47]
	s_waitcnt lgkmcnt(0)
	v_max3_f32 v6, v69, v6, v7
	v_sub_f32_e32 v8, v38, v6
	v_mul_f32_e32 v8, 0x3fb8aa3b, v8
	v_exp_f32_e32 v83, v8
	v_sub_f32_e32 v8, v39, v6
	v_sub_f32_e32 v2, v2, v6
	v_mul_f32_e32 v8, 0x3fb8aa3b, v8
	v_mul_f32_e32 v2, 0x3fb8aa3b, v2
	v_exp_f32_e32 v81, v8
	v_sub_f32_e32 v8, v40, v6
	v_exp_f32_e32 v63, v2
	v_sub_f32_e32 v2, v3, v6
	v_mul_f32_e32 v8, 0x3fb8aa3b, v8
	v_mul_f32_e32 v2, 0x3fb8aa3b, v2
	v_exp_f32_e32 v71, v8
	v_sub_f32_e32 v8, v41, v6
	v_exp_f32_e32 v61, v2
	v_sub_f32_e32 v2, v4, v6
	v_mul_f32_e32 v8, 0x3fb8aa3b, v8
	v_mul_f32_e32 v2, 0x3fb8aa3b, v2
	v_sub_f32_e32 v7, v69, v6
	v_exp_f32_e32 v69, v8
	v_exp_f32_e32 v43, v2
	v_sub_f32_e32 v2, v5, v6
	v_mul_f32_e32 v2, 0x3fb8aa3b, v2
	v_mul_f32_e32 v7, 0x3fb8aa3b, v7
	v_exp_f32_e32 v39, v2
	v_exp_f32_e32 v38, v7
	v_add_u32_e32 v2, 0x8000, v81
	v_add_u32_e32 v3, 0x8000, v83
	v_perm_b32 v2, v2, v3, s87
	v_add_u32_e32 v3, 0x8000, v69
	v_add_u32_e32 v4, 0x8000, v71
	v_perm_b32 v3, v3, v4, s87
	v_add_u32_e32 v4, 0x8000, v61
	v_add_u32_e32 v5, 0x8000, v63
	v_perm_b32 v4, v4, v5, s87
	v_add_u32_e32 v5, 0x8000, v39
	v_add_u32_e32 v6, 0x8000, v43
	v_perm_b32 v5, v5, v6, s87
	v_pk_mul_f32 v[8:9], v[54:55], v[38:39] op_sel_hi:[1,0]
	v_pk_mul_f32 v[6:7], v[52:53], v[38:39] op_sel_hi:[1,0]
	s_waitcnt vmcnt(3)
	s_nop 0
	v_mfma_f32_16x16x32_bf16 v[6:9], v[22:25], v[2:5], v[6:9]
	v_mul_f32_e64 v24, v36, v38
	v_mul_f32_e64 v25, v37, v38
	v_pk_mul_f32 v[22:23], v[34:35], v[38:39] op_sel_hi:[1,0]
	s_waitcnt vmcnt(2)
	s_nop 0
	v_mfma_f32_16x16x32_bf16 v[18:21], v[18:21], v[2:5], v[22:25]
	s_nop 2
	v_mul_f32_e64 v24, v32, v38
	v_mul_f32_e64 v25, v33, v38
	v_pk_mul_f32 v[22:23], v[30:31], v[38:39] op_sel_hi:[1,0]
	s_waitcnt vmcnt(1)
	s_nop 0
	v_mfma_f32_16x16x32_bf16 v[14:17], v[14:17], v[2:5], v[22:25]
	s_nop 2
	v_mul_f32_e64 v24, v28, v38
	v_mul_f32_e64 v25, v29, v38
	v_pk_mul_f32 v[22:23], v[26:27], v[38:39] op_sel_hi:[1,0]
	s_waitcnt vmcnt(0)
	s_nop 0
	v_mfma_f32_16x16x32_bf16 v[2:5], v[10:13], v[2:5], v[22:25]
	v_add_f32_e64 v10, v82, v0
	v_add_f32_e64 v11, v83, v1
	v_pk_add_f32 v[10:11], v[80:81], v[10:11]
	s_nop 0
	v_pk_add_f32 v[10:11], v[70:71], v[10:11]
	s_nop 0
	v_pk_add_f32 v[10:11], v[68:69], v[10:11]
	s_nop 0
	v_pk_add_f32 v[10:11], v[62:63], v[10:11]
	s_nop 0
	v_pk_add_f32 v[10:11], v[60:61], v[10:11]
	s_nop 0
	v_pk_add_f32 v[10:11], v[42:43], v[10:11]
	s_nop 0
	v_add_f32_e32 v0, v11, v39
	v_fmac_f32_e32 v0, v10, v38
	v_mov_b32_e32 v22, v0
	s_nop 1
	v_permlane16_swap_b32_e32 v22, v0
	v_lshl_add_u64 v[10:11], v[128:129], 0, v[140:141]
	v_lshl_add_u64 v[12:13], v[10:11], 0, s[0:1]
	s_waitcnt lgkmcnt(0)
	v_add_f32_e32 v0, v0, v22
	v_mov_b32_e32 v22, v0
	s_nop 1
	v_permlane32_swap_b32_e32 v22, v0
	s_waitcnt lgkmcnt(0)
	v_add_f32_e32 v0, v0, v22
	v_div_scale_f32 v22, s[0:1], v0, v0, 1.0
	v_rcp_f32_e32 v23, v22
	s_mov_b32 s0, 0xd800000
	v_fma_f32 v24, -v22, v23, 1.0
	v_fmac_f32_e32 v23, v24, v23
	v_div_scale_f32 v24, vcc, 1.0, v0, 1.0
	v_mul_f32_e32 v25, v24, v23
	v_fma_f32 v26, -v22, v25, v24
	v_fmac_f32_e32 v25, v26, v23
	v_fma_f32 v22, -v22, v25, v24
	v_div_fmas_f32 v22, v22, v23, v25
	v_div_fixup_f32 v0, v22, v0, 1.0
	v_mov_b32_e32 v22, v6
	v_mov_b32_e32 v23, v8
	v_pk_mul_f32 v[22:23], v[22:23], v[0:1] op_sel_hi:[1,0]
	v_mov_b32_e32 v8, v7
	v_pk_mul_f32 v[6:7], v[8:9], v[0:1] op_sel_hi:[1,0]
	v_and_b32_sdwa v9, v22, v236 dst_sel:DWORD dst_unused:UNUSED_PAD src0_sel:WORD_1 src1_sel:DWORD
	v_and_b32_sdwa v8, v23, v236 dst_sel:DWORD dst_unused:UNUSED_PAD src0_sel:WORD_1 src1_sel:DWORD
	v_add3_u32 v9, v22, v9, s60
	v_and_b32_sdwa v22, v7, v236 dst_sel:DWORD dst_unused:UNUSED_PAD src0_sel:WORD_1 src1_sel:DWORD
	v_add3_u32 v8, v23, v8, s60
	v_and_b32_sdwa v23, v6, v236 dst_sel:DWORD dst_unused:UNUSED_PAD src0_sel:WORD_1 src1_sel:DWORD
	v_add3_u32 v7, v7, v22, s60
	v_add3_u32 v6, v6, v23, s60
	v_and_b32_e32 v7, 0xffff0000, v7
	v_and_b32_e32 v6, 0xffff0000, v6
	v_or_b32_sdwa v7, v7, v8 dst_sel:DWORD dst_unused:UNUSED_PAD src0_sel:DWORD src1_sel:WORD_1
	v_add_co_u32_e32 v8, vcc, s0, v10
	v_or_b32_sdwa v6, v6, v9 dst_sel:DWORD dst_unused:UNUSED_PAD src0_sel:DWORD src1_sel:WORD_1
	s_nop 0
	v_addc_co_u32_e32 v9, vcc, 0, v11, vcc
	global_store_dwordx2 v[8:9], v[6:7], off offset:512 sc1
	v_mov_b32_e32 v6, v18
	v_mov_b32_e32 v7, v20
	v_pk_mul_f32 v[6:7], v[6:7], v[0:1] op_sel_hi:[1,0]
	v_mov_b32_e32 v20, v19
	v_pk_mul_f32 v[8:9], v[20:21], v[0:1] op_sel_hi:[1,0]
	v_and_b32_sdwa v10, v7, v236 dst_sel:DWORD dst_unused:UNUSED_PAD src0_sel:WORD_1 src1_sel:DWORD
	v_and_b32_sdwa v11, v6, v236 dst_sel:DWORD dst_unused:UNUSED_PAD src0_sel:WORD_1 src1_sel:DWORD
	v_add3_u32 v6, v6, v11, s60
	v_add3_u32 v7, v7, v10, s60
	v_and_b32_sdwa v10, v9, v236 dst_sel:DWORD dst_unused:UNUSED_PAD src0_sel:WORD_1 src1_sel:DWORD
	v_and_b32_sdwa v11, v8, v236 dst_sel:DWORD dst_unused:UNUSED_PAD src0_sel:WORD_1 src1_sel:DWORD
	v_add3_u32 v9, v9, v10, s60
	v_add3_u32 v8, v8, v11, s60
	v_and_b32_e32 v9, 0xffff0000, v9
	v_and_b32_e32 v8, 0xffff0000, v8
	v_or_b32_sdwa v7, v9, v7 dst_sel:DWORD dst_unused:UNUSED_PAD src0_sel:DWORD src1_sel:WORD_1
	v_or_b32_sdwa v6, v8, v6 dst_sel:DWORD dst_unused:UNUSED_PAD src0_sel:DWORD src1_sel:WORD_1
	global_store_dwordx2 v[12:13], v[6:7], off offset:32 sc1
	v_mov_b32_e32 v6, v14
	v_mov_b32_e32 v7, v16
	v_pk_mul_f32 v[6:7], v[6:7], v[0:1] op_sel_hi:[1,0]
	v_mov_b32_e32 v16, v15
	v_pk_mul_f32 v[8:9], v[16:17], v[0:1] op_sel_hi:[1,0]
	v_and_b32_sdwa v10, v7, v236 dst_sel:DWORD dst_unused:UNUSED_PAD src0_sel:WORD_1 src1_sel:DWORD
	v_and_b32_sdwa v11, v6, v236 dst_sel:DWORD dst_unused:UNUSED_PAD src0_sel:WORD_1 src1_sel:DWORD
	v_add3_u32 v6, v6, v11, s60
	v_add3_u32 v7, v7, v10, s60
	v_and_b32_sdwa v10, v9, v236 dst_sel:DWORD dst_unused:UNUSED_PAD src0_sel:WORD_1 src1_sel:DWORD
	v_and_b32_sdwa v11, v8, v236 dst_sel:DWORD dst_unused:UNUSED_PAD src0_sel:WORD_1 src1_sel:DWORD
	v_add3_u32 v9, v9, v10, s60
	v_add3_u32 v8, v8, v11, s60
	v_and_b32_e32 v9, 0xffff0000, v9
	v_and_b32_e32 v8, 0xffff0000, v8
	v_or_b32_sdwa v7, v9, v7 dst_sel:DWORD dst_unused:UNUSED_PAD src0_sel:DWORD src1_sel:WORD_1
	v_or_b32_sdwa v6, v8, v6 dst_sel:DWORD dst_unused:UNUSED_PAD src0_sel:DWORD src1_sel:WORD_1
	global_store_dwordx2 v[12:13], v[6:7], off offset:64 sc1
	v_mov_b32_e32 v6, v2
	v_mov_b32_e32 v7, v4
	v_pk_mul_f32 v[6:7], v[6:7], v[0:1] op_sel_hi:[1,0]
	v_mov_b32_e32 v4, v3
	v_pk_mul_f32 v[2:3], v[4:5], v[0:1] op_sel_hi:[1,0]
	v_and_b32_sdwa v4, v6, v236 dst_sel:DWORD dst_unused:UNUSED_PAD src0_sel:WORD_1 src1_sel:DWORD
	v_add3_u32 v4, v6, v4, s60
	v_and_b32_sdwa v5, v3, v236 dst_sel:DWORD dst_unused:UNUSED_PAD src0_sel:WORD_1 src1_sel:DWORD
	v_and_b32_sdwa v6, v2, v236 dst_sel:DWORD dst_unused:UNUSED_PAD src0_sel:WORD_1 src1_sel:DWORD
	v_and_b32_sdwa v0, v7, v236 dst_sel:DWORD dst_unused:UNUSED_PAD src0_sel:WORD_1 src1_sel:DWORD
	v_add3_u32 v3, v3, v5, s60
	v_add3_u32 v2, v2, v6, s60
	v_add3_u32 v0, v7, v0, s60
	v_and_b32_e32 v3, 0xffff0000, v3
	v_and_b32_e32 v2, 0xffff0000, v2
	v_or_b32_sdwa v3, v3, v0 dst_sel:DWORD dst_unused:UNUSED_PAD src0_sel:DWORD src1_sel:WORD_1
	v_or_b32_sdwa v2, v2, v4 dst_sel:DWORD dst_unused:UNUSED_PAD src0_sel:DWORD src1_sel:WORD_1
	global_store_dwordx2 v[12:13], v[2:3], off offset:96 sc1

.LBB0_1197:
	s_bitcmp0_b32 s17, 0
	s_cselect_b32 s0, s11, s16
	s_add_i32 s0, s0, s10
	s_add_i32 s1, s0, 0xfffff900
	s_cmp_lt_u32 s1, 0xfffffd00
	s_cbranch_scc1 .LBB0_1196
	s_add_i32 s0, s0, 0xfc00
	s_and_b32 s1, s0, 0xffff
	s_mul_i32 s1, s1, 0xaaab
	s_lshr_b32 s2, s1, 21
	s_mul_i32 s1, s2, 48
	s_sub_i32 s0, s0, s1
	s_bfe_u32 s3, s0, 0xd0003
	s_lshl_b32 s0, s0, 5
	s_lshl_b32 s1, s2, 8
	s_and_b32 s0, s0, 0xe0
	s_or_b32 s0, s0, s1
	v_or_b32_e32 v0, s0, v149
	v_mov_b64_e32 v[6:7], s[8:9]
	v_mad_u64_u32 v[8:9], s[0:1], v0, s33, v[6:7]
	s_lshl_b32 s44, s3, 7
	s_mul_i32 s2, s2, 0x30000
	s_add_u32 s0, s12, s2
	s_addc_u32 s1, s13, 0
	s_add_u32 s0, s0, s44
	s_addc_u32 s1, s1, 0
	v_mov_b32_e32 v83, v1
	v_mov_b32_e32 v81, v1
	v_lshl_add_u64 v[2:3], s[0:1], 0, v[82:83]
	v_lshl_add_u64 v[204:205], v[2:3], 0, v[80:81]
	global_load_dwordx4 v[2:5], v[204:205], off
	v_lshl_add_u64 v[8:9], v[8:9], 0, s[44:45]
	v_lshl_add_u64 v[8:9], v[8:9], 0, v[80:81]
	global_load_dwordx4 v[48:51], v[8:9], off
	global_load_dwordx4 v[16:19], v[204:205], off offset:3072
	v_or_b32_e32 v89, 16, v0
	v_mad_u64_u32 v[6:7], s[0:1], v89, s33, v[6:7]
	v_lshl_add_u64 v[6:7], v[6:7], 0, s[44:45]
	v_lshl_add_u64 v[6:7], v[6:7], 0, v[80:81]
	global_load_dwordx4 v[12:15], v[6:7], off
	global_load_dwordx4 v[20:23], v[204:205], off offset:16
	global_load_dwordx4 v[64:67], v[8:9], off offset:16
	global_load_dwordx4 v[24:27], v[204:205], off offset:3088
	s_nop 0
	global_load_dwordx4 v[8:11], v[6:7], off offset:16
	s_add_u32 s0, s14, s2
	s_addc_u32 s1, s15, 0
	s_lshl_b32 s2, s3, 15
	s_add_u32 s0, s0, s2
	v_mov_b32_e32 v85, v1
	s_addc_u32 s1, s1, 0
	v_mov_b32_e32 v87, v1
	v_lshl_add_u64 v[6:7], s[0:1], 0, v[84:85]
	v_lshl_add_u64 v[202:203], v[6:7], 0, v[86:87]
	global_load_dwordx4 v[28:31], v[202:203], off
	global_load_dwordx4 v[44:47], v[202:203], off offset:256
	v_cmp_lt_i32_e32 vcc, v231, v226
	global_load_dwordx4 v[52:55], v[202:203], off offset:768
	global_load_dwordx4 v[40:43], v[202:203], off offset:512
	v_cndmask_b32_e32 v6, v225, v231, vcc
	v_lshlrev_b32_e32 v81, 2, v6
	v_cmp_lt_i32_e32 vcc, v232, v226
	s_movk_i32 s1, 0x6000
	s_mov_b32 s0, 0xf149f2ca
	v_lshlrev_b32_e32 v0, 11, v0
	s_mov_b64 s[18:19], 0xd800200
	s_mov_b32 s2, 0xd800000
	s_waitcnt vmcnt(9)
	v_mfma_f32_16x16x32_bf16 v[36:39], v[16:19], v[48:51], 0
	v_mfma_f32_16x16x32_bf16 v[32:35], v[2:5], v[48:51], 0
	s_waitcnt vmcnt(6)
	v_mfma_f32_16x16x32_bf16 v[56:59], v[20:23], v[64:67], v[32:35]
	s_waitcnt vmcnt(5)
	v_mfma_f32_16x16x32_bf16 v[36:39], v[24:27], v[64:67], v[36:39]
	v_mfma_f32_16x16x32_bf16 v[2:5], v[2:5], v[12:15], 0
	s_nop 4
	v_max_f32_e32 v6, v57, v57
	v_max_f32_e32 v7, v56, v56
	v_max_f32_e32 v32, v59, v59
	v_max_f32_e32 v33, v58, v58
	v_max_f32_e32 v34, v39, v39
	v_max_f32_e32 v35, v38, v38
	v_max_f32_e32 v6, v7, v6
	v_max_f32_e32 v7, v33, v32
	v_max_f32_e32 v32, v35, v34
	v_max3_f32 v32, v36, v37, v32
	v_max3_f32 v6, v6, v7, v32
	ds_bpermute_b32 v7, v81, v6
	v_cndmask_b32_e32 v32, v225, v232, vcc
	v_lshlrev_b32_e32 v83, 2, v32
	s_waitcnt vmcnt(4)
	v_mfma_f32_16x16x32_bf16 v[32:35], v[20:23], v[8:11], v[2:5]
	v_add_co_u32_e32 v72, vcc, s1, v204
	s_waitcnt lgkmcnt(0)
	s_nop 0
	v_max_f32_e32 v2, v7, v7
	v_max_f32_e32 v2, v6, v2
	v_mov_b32_e32 v3, v2
	s_nop 1
	v_permlane32_swap_b32_e32 v3, v2
	v_mfma_f32_16x16x32_bf16 v[16:19], v[16:19], v[12:15], 0
	v_addc_co_u32_e32 v73, vcc, 0, v205, vcc
	global_load_dwordx4 v[68:71], v[72:73], off offset:16
	s_waitcnt lgkmcnt(0)
	v_max3_f32 v91, v2, v3, s0
	v_mfma_f32_16x16x32_bf16 v[60:63], v[24:27], v[8:11], v[16:19]
	v_sub_f32_e32 v20, v39, v91
	v_max_f32_e32 v6, v33, v33
	v_max_f32_e32 v7, v32, v32
	v_sub_f32_e32 v17, v36, v91
	v_sub_f32_e32 v18, v37, v91
	v_sub_f32_e32 v19, v38, v91
	global_load_dwordx4 v[36:39], v[72:73], off
	v_max_f32_e32 v24, v35, v35
	v_max_f32_e32 v25, v34, v34
	v_max_f32_e32 v6, v7, v6
	v_max_f32_e32 v7, v25, v24
	v_max_f32_e32 v24, v63, v63
	v_max_f32_e32 v25, v62, v62
	v_max_f32_e32 v24, v25, v24
	v_max3_f32 v24, v60, v61, v24
	v_max3_f32 v6, v6, v7, v24
	v_mov_b32_e32 v7, v6
	s_nop 1
	v_permlane16_swap_b32_e32 v7, v6
	v_sub_f32_e32 v2, 0xf149f2ca, v91
	v_sub_f32_e32 v3, v56, v91
	v_sub_f32_e32 v4, v57, v91
	v_sub_f32_e32 v5, v58, v91
	v_sub_f32_e32 v16, v59, v91
	s_waitcnt lgkmcnt(0)
	v_max_f32_e32 v7, v7, v7
	v_mul_f32_e32 v2, 0x3fb8aa3b, v2
	v_mul_f32_e32 v3, 0x3fb8aa3b, v3
	v_mul_f32_e32 v4, 0x3fb8aa3b, v4
	v_mul_f32_e32 v5, 0x3fb8aa3b, v5
	v_mul_f32_e32 v16, 0x3fb8aa3b, v16
	v_mul_f32_e32 v17, 0x3fb8aa3b, v17
	v_mul_f32_e32 v18, 0x3fb8aa3b, v18
	v_mul_f32_e32 v19, 0x3fb8aa3b, v19
	v_mul_f32_e32 v20, 0x3fb8aa3b, v20
	v_max_f32_e32 v6, v6, v7
	v_exp_f32_e32 v85, v3
	v_exp_f32_e32 v87, v4
	v_exp_f32_e32 v100, v5
	v_exp_f32_e32 v98, v16
	v_exp_f32_e32 v96, v17
	v_exp_f32_e32 v94, v18
	v_exp_f32_e32 v92, v19
	v_exp_f32_e32 v90, v20
	v_exp_f32_e32 v2, v2
	v_mov_b32_e32 v7, v6
	s_nop 1
	v_permlane32_swap_b32_e32 v7, v6
	v_add_u32_e32 v3, 0x8000, v87
	v_add_u32_e32 v4, 0x8000, v85
	v_add_u32_e32 v5, 0x8000, v98
	v_add_u32_e32 v16, 0x8000, v100
	v_add_u32_e32 v17, 0x8000, v94
	v_add_u32_e32 v18, 0x8000, v96
	v_add_u32_e32 v19, 0x8000, v90
	v_add_u32_e32 v23, 0x8000, v92
	v_mul_f32_e32 v2, 0, v2
	v_perm_b32 v20, v3, v4, s87
	v_perm_b32 v21, v5, v16, s87
	v_perm_b32 v22, v17, v18, s87
	v_perm_b32 v23, v19, v23, s87
	v_mov_b32_e32 v3, v2
	v_mov_b32_e32 v4, v2
	v_mov_b32_e32 v5, v2
	s_waitcnt lgkmcnt(0)
	v_max3_f32 v103, v6, v7, s0
	s_movk_i32 s0, 0x2000
	s_waitcnt vmcnt(5)
	v_mfma_f32_16x16x32_bf16 v[56:59], v[28:31], v[20:23], v[2:5]
	v_add_co_u32_e32 v120, vcc, s0, v202
	s_movk_i32 s0, 0x1000
	s_waitcnt vmcnt(4)
	v_mfma_f32_16x16x32_bf16 v[16:19], v[44:47], v[20:23], v[2:5]
	v_addc_co_u32_e32 v121, vcc, 0, v203, vcc
	global_load_dwordx4 v[136:139], v[120:121], off
	s_waitcnt vmcnt(3)
	v_mfma_f32_16x16x32_bf16 v[24:27], v[40:43], v[20:23], v[2:5]
	global_load_dwordx4 v[144:147], v[120:121], off offset:512
	global_load_dwordx4 v[154:157], v[120:121], off offset:768
	v_mfma_f32_16x16x32_bf16 v[20:23], v[52:55], v[20:23], v[2:5]
	s_nop 2
	v_sub_f32_e32 v4, v32, v103
	v_mul_f32_e32 v4, 0x3fb8aa3b, v4
	v_exp_f32_e32 v151, v4
	v_sub_f32_e32 v4, v33, v103
	v_mul_f32_e32 v4, 0x3fb8aa3b, v4
	v_exp_f32_e32 v153, v4
	v_sub_f32_e32 v4, v34, v103
	v_mul_f32_e32 v4, 0x3fb8aa3b, v4
	v_exp_f32_e32 v112, v4
	v_sub_f32_e32 v4, v35, v103
	v_mul_f32_e32 v4, 0x3fb8aa3b, v4
	v_exp_f32_e32 v110, v4
	v_sub_f32_e32 v4, v60, v103
	v_mul_f32_e32 v4, 0x3fb8aa3b, v4
	v_exp_f32_e32 v108, v4
	v_sub_f32_e32 v4, v61, v103
	v_mul_f32_e32 v4, 0x3fb8aa3b, v4
	v_exp_f32_e32 v106, v4
	v_sub_f32_e32 v4, v62, v103
	v_mul_f32_e32 v4, 0x3fb8aa3b, v4
	v_exp_f32_e32 v104, v4
	v_sub_f32_e32 v4, v63, v103
	v_sub_f32_e32 v3, 0xf149f2ca, v103
	v_mul_f32_e32 v4, 0x3fb8aa3b, v4
	v_mul_f32_e32 v3, 0x3fb8aa3b, v3
	v_exp_f32_e32 v102, v4
	v_exp_f32_e32 v3, v3
	v_add_u32_e32 v4, 0x8000, v153
	v_add_u32_e32 v5, 0x8000, v151
	v_perm_b32 v76, v4, v5, s87
	v_add_u32_e32 v4, 0x8000, v110
	v_add_u32_e32 v5, 0x8000, v112
	v_perm_b32 v77, v4, v5, s87
	v_add_u32_e32 v4, 0x8000, v106
	v_add_u32_e32 v5, 0x8000, v108
	v_perm_b32 v78, v4, v5, s87
	v_add_u32_e32 v4, 0x8000, v102
	v_add_u32_e32 v5, 0x8000, v104
	v_perm_b32 v79, v4, v5, s87
	v_mul_f32_e32 v4, 0, v3
	v_mov_b32_e32 v5, v4
	v_mov_b32_e32 v6, v4
	v_mov_b32_e32 v7, v4
	global_load_dwordx4 v[60:63], v[72:73], off offset:3072
	s_nop 0
	v_mfma_f32_16x16x32_bf16 v[32:35], v[28:31], v[76:79], v[4:7]
	v_mfma_f32_16x16x32_bf16 v[28:31], v[44:47], v[76:79], v[4:7]
	s_waitcnt vmcnt(4)
	v_mfma_f32_16x16x32_bf16 v[44:47], v[36:39], v[48:51], 0
	v_mfma_f32_16x16x32_bf16 v[122:125], v[68:71], v[64:67], v[44:47]
	v_mfma_f32_16x16x32_bf16 v[40:43], v[40:43], v[76:79], v[4:7]
	s_nop 5
	global_load_dwordx4 v[44:47], v[120:121], off offset:-4096
	v_max_f32_e32 v3, v123, v123
	global_load_dwordx4 v[72:75], v[72:73], off offset:3088
	s_waitcnt vmcnt(2)
	v_mfma_f32_16x16x32_bf16 v[114:117], v[60:63], v[48:51], 0
	v_max_f32_e32 v93, v122, v122
	v_max_f32_e32 v3, v93, v3
	v_max_f32_e32 v93, v125, v125
	s_waitcnt vmcnt(0)
	v_mfma_f32_16x16x32_bf16 v[126:129], v[72:75], v[64:67], v[114:117]
	v_max_f32_e32 v95, v124, v124
	v_max_f32_e32 v93, v95, v93
	s_nop 0
	v_add_co_u32_e32 v116, vcc, s0, v202
	s_nop 3
	v_max_f32_e32 v95, v129, v129
	v_max_f32_e32 v97, v128, v128
	v_max_f32_e32 v95, v97, v95
	v_max3_f32 v95, v126, v127, v95
	v_max3_f32 v3, v3, v93, v95
	v_mov_b32_e32 v93, v3
	s_nop 1
	v_permlane16_swap_b32_e32 v93, v3
	v_mfma_f32_16x16x32_bf16 v[52:55], v[52:55], v[76:79], v[4:7]
	v_addc_co_u32_e32 v117, vcc, 0, v203, vcc
	s_mov_b32 s0, 0xc000
	s_waitcnt lgkmcnt(0)
	v_max_f32_e32 v93, v93, v93
	v_max_f32_e32 v3, v3, v93
	v_mov_b32_e32 v93, v3
	s_nop 1
	v_permlane32_swap_b32_e32 v93, v3
	v_mfma_f32_16x16x32_bf16 v[36:39], v[36:39], v[12:15], 0
	s_waitcnt lgkmcnt(0)
	v_max3_f32 v6, v91, v3, v93
	v_sub_f32_e32 v3, v91, v6
	v_mul_f32_e32 v5, 0x3fb8aa3b, v3
	v_sub_f32_e32 v3, v122, v6
	v_mul_f32_e32 v3, 0x3fb8aa3b, v3
	v_exp_f32_e32 v101, v3
	v_sub_f32_e32 v3, v123, v6
	v_mul_f32_e32 v3, 0x3fb8aa3b, v3
	v_exp_f32_e32 v99, v3
	v_sub_f32_e32 v3, v124, v6
	v_mul_f32_e32 v3, 0x3fb8aa3b, v3
	v_exp_f32_e32 v97, v3
	v_sub_f32_e32 v3, v125, v6
	global_load_dwordx4 v[122:125], v[116:117], off offset:256
	v_mul_f32_e32 v3, 0x3fb8aa3b, v3
	v_exp_f32_e32 v95, v3
	v_sub_f32_e32 v3, v126, v6
	v_mul_f32_e32 v3, 0x3fb8aa3b, v3
	v_exp_f32_e32 v93, v3
	v_sub_f32_e32 v3, v127, v6
	v_mul_f32_e32 v3, 0x3fb8aa3b, v3
	v_exp_f32_e32 v91, v3
	v_sub_f32_e32 v3, v128, v6
	v_sub_f32_e32 v7, v129, v6
	v_mul_f32_e32 v3, 0x3fb8aa3b, v3
	v_mul_f32_e32 v7, 0x3fb8aa3b, v7
	v_mfma_f32_16x16x32_bf16 v[60:63], v[60:63], v[12:15], 0
	v_exp_f32_e32 v3, v3
	v_exp_f32_e32 v167, v7
	v_exp_f32_e32 v114, v5
	v_add_u32_e32 v5, 0x8000, v99
	v_add_u32_e32 v7, 0x8000, v101
	v_mfma_f32_16x16x32_bf16 v[36:39], v[68:71], v[8:11], v[36:39]
	v_perm_b32 v76, v5, v7, s87
	v_add_u32_e32 v5, 0x8000, v95
	v_add_u32_e32 v7, 0x8000, v97
	v_perm_b32 v77, v5, v7, s87
	v_add_u32_e32 v5, 0x8000, v91
	v_add_u32_e32 v7, 0x8000, v93
	v_mfma_f32_16x16x32_bf16 v[60:63], v[72:75], v[8:11], v[60:63]
	v_perm_b32 v78, v5, v7, s87
	v_add_u32_e32 v5, 0x8000, v167
	v_add_u32_e32 v7, 0x8000, v3
	v_perm_b32 v79, v5, v7, s87
	v_max_f32_e32 v5, v37, v37
	v_max_f32_e32 v7, v36, v36
	v_max_f32_e32 v5, v7, v5
	v_max_f32_e32 v7, v39, v39
	v_max_f32_e32 v72, v38, v38
	v_max_f32_e32 v7, v72, v7
	v_max_f32_e32 v72, v63, v63
	v_max_f32_e32 v73, v62, v62
	v_max_f32_e32 v72, v73, v72
	v_max3_f32 v72, v60, v61, v72
	v_max3_f32 v5, v5, v7, v72
	v_mov_b32_e32 v7, v5
	s_nop 1
	v_permlane16_swap_b32_e32 v7, v5
	v_pk_mul_f32 v[58:59], v[58:59], v[114:115] op_sel_hi:[1,0]
	v_pk_mul_f32 v[56:57], v[56:57], v[114:115] op_sel_hi:[1,0]
	v_pk_mul_f32 v[18:19], v[18:19], v[114:115] op_sel_hi:[1,0]
	v_pk_mul_f32 v[16:17], v[16:17], v[114:115] op_sel_hi:[1,0]
	s_waitcnt lgkmcnt(0)
	v_max_f32_e32 v7, v7, v7
	v_max_f32_e32 v5, v5, v7
	v_mov_b32_e32 v7, v5
	s_nop 1
	v_permlane32_swap_b32_e32 v7, v5
	v_pk_mul_f32 v[26:27], v[26:27], v[114:115] op_sel_hi:[1,0]
	v_pk_mul_f32 v[24:25], v[24:25], v[114:115] op_sel_hi:[1,0]
	v_pk_mul_f32 v[22:23], v[22:23], v[114:115] op_sel_hi:[1,0]
	v_pk_mul_f32 v[20:21], v[20:21], v[114:115] op_sel_hi:[1,0]
	s_waitcnt lgkmcnt(0)
	v_max3_f32 v115, v103, v5, v7
	v_sub_f32_e32 v5, v103, v115
	v_mul_f32_e32 v7, 0x3fb8aa3b, v5
	v_sub_f32_e32 v5, v36, v115
	v_mul_f32_e32 v5, 0x3fb8aa3b, v5
	v_exp_f32_e32 v113, v5
	v_sub_f32_e32 v5, v37, v115
	v_mul_f32_e32 v5, 0x3fb8aa3b, v5
	v_exp_f32_e32 v111, v5
	v_sub_f32_e32 v5, v38, v115
	v_mul_f32_e32 v5, 0x3fb8aa3b, v5
	v_exp_f32_e32 v109, v5
	v_sub_f32_e32 v5, v39, v115
	v_mul_f32_e32 v5, 0x3fb8aa3b, v5
	v_exp_f32_e32 v107, v5
	v_sub_f32_e32 v5, v60, v115
	v_mul_f32_e32 v5, 0x3fb8aa3b, v5
	v_exp_f32_e32 v105, v5
	v_sub_f32_e32 v5, v61, v115
	v_mul_f32_e32 v5, 0x3fb8aa3b, v5
	v_exp_f32_e32 v103, v5
	v_sub_f32_e32 v5, v62, v115
	v_sub_f32_e32 v36, v63, v115
	v_mul_f32_e32 v5, 0x3fb8aa3b, v5
	v_mul_f32_e32 v36, 0x3fb8aa3b, v36
	v_exp_f32_e32 v5, v5
	v_exp_f32_e32 v206, v36
	v_exp_f32_e32 v118, v7
	v_add_u32_e32 v7, 0x8000, v111
	v_add_u32_e32 v36, 0x8000, v113
	v_perm_b32 v36, v7, v36, s87
	v_add_u32_e32 v7, 0x8000, v107
	v_add_u32_e32 v37, 0x8000, v109
	v_perm_b32 v37, v7, v37, s87
	v_add_u32_e32 v7, 0x8000, v103
	v_add_u32_e32 v38, 0x8000, v105
	global_load_dwordx4 v[126:129], v[116:117], off offset:512
	global_load_dwordx4 v[68:71], v[116:117], off offset:768
	v_add_co_u32_e32 v116, vcc, s0, v204
	v_perm_b32 v38, v7, v38, s87
	v_add_u32_e32 v7, 0x8000, v206
	v_add_u32_e32 v39, 0x8000, v5
	v_addc_co_u32_e32 v117, vcc, 0, v205, vcc
	v_perm_b32 v39, v7, v39, s87
	v_pk_mul_f32 v[34:35], v[34:35], v[118:119] op_sel_hi:[1,0]
	v_pk_mul_f32 v[32:33], v[32:33], v[118:119] op_sel_hi:[1,0]
	v_mfma_f32_16x16x32_bf16 v[56:59], v[44:47], v[76:79], v[56:59]
	global_load_dwordx4 v[60:63], v[116:117], off offset:3072
	global_load_dwordx4 v[130:133], v[116:117], off offset:3088
	v_pk_mul_f32 v[30:31], v[30:31], v[118:119] op_sel_hi:[1,0]
	v_mfma_f32_16x16x32_bf16 v[32:35], v[44:47], v[36:39], v[32:35]
	global_load_dwordx4 v[44:47], v[116:117], off
	v_pk_mul_f32 v[28:29], v[28:29], v[118:119] op_sel_hi:[1,0]
	v_pk_mul_f32 v[42:43], v[42:43], v[118:119] op_sel_hi:[1,0]
	s_waitcnt vmcnt(5)
	v_mfma_f32_16x16x32_bf16 v[16:19], v[122:125], v[76:79], v[16:19]
	v_mul_f32_e64 v40, v40, v118
	v_mul_f32_e64 v41, v41, v118
	v_pk_mul_f32 v[54:55], v[54:55], v[118:119] op_sel_hi:[1,0]
	v_pk_mul_f32 v[52:53], v[52:53], v[118:119] op_sel_hi:[1,0]
	v_mfma_f32_16x16x32_bf16 v[28:31], v[122:125], v[36:39], v[28:31]
	global_load_dwordx4 v[122:125], v[116:117], off offset:16
	s_mov_b32 s0, 0x12000
	s_waitcnt vmcnt(1)
	v_mfma_f32_16x16x32_bf16 v[72:75], v[44:47], v[48:51], 0
	v_mfma_f32_16x16x32_bf16 v[24:27], v[126:129], v[76:79], v[24:27]
	v_mfma_f32_16x16x32_bf16 v[20:23], v[68:71], v[76:79], v[20:23]
	v_mfma_f32_16x16x32_bf16 v[76:79], v[60:63], v[48:51], 0
	s_waitcnt vmcnt(0)
	v_mfma_f32_16x16x32_bf16 v[72:75], v[122:125], v[64:67], v[72:75]
	v_mfma_f32_16x16x32_bf16 v[140:143], v[130:133], v[64:67], v[76:79]
	v_mfma_f32_16x16x32_bf16 v[40:43], v[126:129], v[36:39], v[40:43]
	s_nop 5
	v_max_f32_e32 v7, v73, v73
	v_max_f32_e32 v76, v72, v72
	v_max_f32_e32 v7, v76, v7
	v_max_f32_e32 v76, v75, v75
	v_max_f32_e32 v77, v74, v74
	v_max_f32_e32 v76, v77, v76
	v_max_f32_e32 v77, v143, v143
	v_max_f32_e32 v78, v142, v142
	v_max_f32_e32 v77, v78, v77
	v_max3_f32 v77, v140, v141, v77
	v_max3_f32 v7, v7, v76, v77
	v_mov_b32_e32 v76, v7
	s_nop 1
	v_permlane16_swap_b32_e32 v76, v7
	v_mfma_f32_16x16x32_bf16 v[36:39], v[68:71], v[36:39], v[52:55]
	s_waitcnt lgkmcnt(0)
	v_max_f32_e32 v76, v76, v76
	v_max_f32_e32 v7, v7, v76
	v_mov_b32_e32 v76, v7
	s_nop 1
	v_permlane32_swap_b32_e32 v76, v7
	v_mfma_f32_16x16x32_bf16 v[44:47], v[44:47], v[12:15], 0
	s_waitcnt lgkmcnt(0)
	v_max3_f32 v69, v6, v7, v76
	v_sub_f32_e32 v7, v72, v69
	v_mul_f32_e32 v7, 0x3fb8aa3b, v7
	v_exp_f32_e32 v181, v7
	v_sub_f32_e32 v7, v73, v69
	v_mul_f32_e32 v7, 0x3fb8aa3b, v7
	v_exp_f32_e32 v193, v7
	v_sub_f32_e32 v7, v74, v69
	v_mul_f32_e32 v7, 0x3fb8aa3b, v7
	v_exp_f32_e32 v78, v7
	v_sub_f32_e32 v7, v75, v69
	v_mul_f32_e32 v7, 0x3fb8aa3b, v7
	v_exp_f32_e32 v76, v7
	v_sub_f32_e32 v7, v140, v69
	v_mul_f32_e32 v7, 0x3fb8aa3b, v7
	v_exp_f32_e32 v74, v7
	v_sub_f32_e32 v7, v141, v69
	v_mul_f32_e32 v7, 0x3fb8aa3b, v7
	v_exp_f32_e32 v72, v7
	v_sub_f32_e32 v7, v142, v69
	v_mul_f32_e32 v7, 0x3fb8aa3b, v7
	v_exp_f32_e32 v70, v7
	v_sub_f32_e32 v7, v143, v69
	global_load_dwordx4 v[140:143], v[120:121], off offset:256
	v_mfma_f32_16x16x32_bf16 v[60:63], v[60:63], v[12:15], 0
	v_sub_f32_e32 v6, v6, v69
	v_mul_f32_e32 v6, 0x3fb8aa3b, v6
	v_exp_f32_e32 v116, v6
	v_mfma_f32_16x16x32_bf16 v[44:47], v[122:125], v[8:11], v[44:47]
	v_mul_f32_e32 v7, 0x3fb8aa3b, v7
	v_exp_f32_e32 v68, v7
	v_pk_mul_f32 v[58:59], v[58:59], v[116:117] op_sel_hi:[1,0]
	v_mfma_f32_16x16x32_bf16 v[60:63], v[130:133], v[8:11], v[60:63]
	v_mul_f32_e64 v56, v56, v116
	v_mul_f32_e64 v57, v57, v116
	s_nop 1
	v_max_f32_e32 v71, v45, v45
	v_max_f32_e32 v73, v44, v44
	v_max_f32_e32 v71, v73, v71
	v_max_f32_e32 v73, v47, v47
	v_max_f32_e32 v75, v46, v46
	v_max_f32_e32 v73, v75, v73
	v_max_f32_e32 v75, v63, v63
	v_max_f32_e32 v77, v62, v62
	v_max_f32_e32 v75, v77, v75
	v_max3_f32 v75, v60, v61, v75
	v_max3_f32 v71, v71, v73, v75
	v_mov_b32_e32 v73, v71
	s_nop 1
	v_permlane16_swap_b32_e32 v73, v71
	v_pk_mul_f32 v[18:19], v[18:19], v[116:117] op_sel_hi:[1,0]
	v_pk_mul_f32 v[16:17], v[16:17], v[116:117] op_sel_hi:[1,0]
	v_pk_mul_f32 v[26:27], v[26:27], v[116:117] op_sel_hi:[1,0]
	v_pk_mul_f32 v[24:25], v[24:25], v[116:117] op_sel_hi:[1,0]
	s_waitcnt lgkmcnt(0)
	v_max_f32_e32 v73, v73, v73
	v_max_f32_e32 v71, v71, v73
	v_mov_b32_e32 v73, v71
	s_nop 1
	v_permlane32_swap_b32_e32 v73, v71
	v_pk_mul_f32 v[22:23], v[22:23], v[116:117] op_sel_hi:[1,0]
	v_pk_mul_f32 v[20:21], v[20:21], v[116:117] op_sel_hi:[1,0]
	v_add_u32_e32 v6, 0x8000, v193
	v_add_u32_e32 v7, 0x8000, v181
	s_waitcnt lgkmcnt(0)
	v_max3_f32 v117, v115, v71, v73
	v_sub_f32_e32 v44, v44, v117
	v_mul_f32_e32 v44, 0x3fb8aa3b, v44
	v_exp_f32_e32 v207, v44
	v_sub_f32_e32 v44, v45, v117
	v_mul_f32_e32 v44, 0x3fb8aa3b, v44
	v_exp_f32_e32 v208, v44
	v_sub_f32_e32 v44, v46, v117
	v_mul_f32_e32 v44, 0x3fb8aa3b, v44
	v_exp_f32_e32 v132, v44
	v_sub_f32_e32 v44, v47, v117
	v_mul_f32_e32 v44, 0x3fb8aa3b, v44
	v_exp_f32_e32 v130, v44
	v_sub_f32_e32 v44, v60, v117
	v_mul_f32_e32 v44, 0x3fb8aa3b, v44
	v_exp_f32_e32 v128, v44
	v_sub_f32_e32 v44, v61, v117
	v_mul_f32_e32 v44, 0x3fb8aa3b, v44
	v_exp_f32_e32 v126, v44
	v_sub_f32_e32 v44, v62, v117
	v_mul_f32_e32 v44, 0x3fb8aa3b, v44
	v_perm_b32 v52, v6, v7, s87
	v_add_u32_e32 v6, 0x8000, v76
	v_add_u32_e32 v7, 0x8000, v78
	v_exp_f32_e32 v124, v44
	v_sub_f32_e32 v44, v63, v117
	v_perm_b32 v53, v6, v7, s87
	v_add_u32_e32 v6, 0x8000, v72
	v_add_u32_e32 v7, 0x8000, v74
	v_mul_f32_e32 v44, 0x3fb8aa3b, v44
	v_perm_b32 v54, v6, v7, s87
	v_add_u32_e32 v6, 0x8000, v68
	v_add_u32_e32 v7, 0x8000, v70
	v_exp_f32_e32 v122, v44
	v_perm_b32 v55, v6, v7, s87
	v_add_co_u32_e32 v6, vcc, s0, v204
	v_add_u32_e32 v44, 0x8000, v208
	v_add_u32_e32 v45, 0x8000, v207
	v_mfma_f32_16x16x32_bf16 v[56:59], v[136:139], v[52:55], v[56:59]
	v_addc_co_u32_e32 v7, vcc, 0, v205, vcc
	v_perm_b32 v44, v44, v45, s87
	s_waitcnt vmcnt(0)
	v_mfma_f32_16x16x32_bf16 v[16:19], v[140:143], v[52:55], v[16:19]
	v_add_u32_e32 v45, 0x8000, v130
	v_add_u32_e32 v46, 0x8000, v132
	global_load_dwordx4 v[158:161], v[6:7], off
	global_load_dwordx4 v[60:63], v[6:7], off offset:16
	v_mfma_f32_16x16x32_bf16 v[24:27], v[144:147], v[52:55], v[24:27]
	v_perm_b32 v45, v45, v46, s87
	v_add_u32_e32 v46, 0x8000, v126
	v_add_u32_e32 v47, 0x8000, v128
	v_mfma_f32_16x16x32_bf16 v[20:23], v[154:157], v[52:55], v[20:23]
	v_sub_f32_e32 v52, v115, v117
	v_mul_f32_e32 v52, 0x3fb8aa3b, v52
	v_exp_f32_e32 v134, v52
	v_perm_b32 v46, v46, v47, s87
	v_add_u32_e32 v47, 0x8000, v122
	v_add_u32_e32 v52, 0x8000, v124
	v_perm_b32 v47, v47, v52, s87
	global_load_dwordx4 v[52:55], v[6:7], off offset:3072
	v_pk_mul_f32 v[30:31], v[30:31], v[134:135] op_sel_hi:[1,0]
	v_pk_mul_f32 v[28:29], v[28:29], v[134:135] op_sel_hi:[1,0]
	v_pk_mul_f32 v[34:35], v[34:35], v[134:135] op_sel_hi:[1,0]
	v_pk_mul_f32 v[32:33], v[32:33], v[134:135] op_sel_hi:[1,0]
	v_mfma_f32_16x16x32_bf16 v[28:31], v[140:143], v[44:47], v[28:31]
	global_load_dwordx4 v[140:143], v[6:7], off offset:3088
	v_pk_mul_f32 v[42:43], v[42:43], v[134:135] op_sel_hi:[1,0]
	v_pk_mul_f32 v[40:41], v[40:41], v[134:135] op_sel_hi:[1,0]
	v_mfma_f32_16x16x32_bf16 v[32:35], v[136:139], v[44:47], v[32:35]
	v_mul_f32_e64 v38, v38, v134
	v_mul_f32_e64 v39, v39, v134
	v_pk_mul_f32 v[36:37], v[36:37], v[134:135] op_sel_hi:[1,0]
	s_movk_i32 s0, 0x4000
	s_waitcnt vmcnt(3)
	v_mfma_f32_16x16x32_bf16 v[136:139], v[158:161], v[48:51], 0
	v_add_co_u32_e32 v6, vcc, s0, v202
	s_movk_i32 s0, 0x3000
	s_waitcnt vmcnt(1)
	v_mfma_f32_16x16x32_bf16 v[162:165], v[52:55], v[48:51], 0
	v_addc_co_u32_e32 v7, vcc, 0, v203, vcc
	v_add_co_u32_e32 v172, vcc, s0, v202
	v_mfma_f32_16x16x32_bf16 v[136:139], v[60:63], v[64:67], v[136:139]
	s_nop 0
	v_addc_co_u32_e32 v173, vcc, 0, v203, vcc
	global_load_dwordx4 v[168:171], v[6:7], off offset:-4096
	global_load_dwordx4 v[176:179], v[6:7], off offset:512
	s_waitcnt vmcnt(2)
	v_mfma_f32_16x16x32_bf16 v[162:165], v[140:143], v[64:67], v[162:165]
	s_nop 1
	v_max_f32_e32 v71, v137, v137
	v_max_f32_e32 v73, v136, v136
	v_max_f32_e32 v71, v73, v71
	v_max_f32_e32 v73, v139, v139
	v_max_f32_e32 v75, v138, v138
	v_max_f32_e32 v73, v75, v73
	v_max_f32_e32 v75, v165, v165
	v_max_f32_e32 v77, v164, v164
	v_max_f32_e32 v75, v77, v75
	v_max3_f32 v75, v162, v163, v75
	v_max3_f32 v71, v71, v73, v75
	v_mov_b32_e32 v73, v71
	s_nop 1
	v_permlane16_swap_b32_e32 v73, v71
	v_mfma_f32_16x16x32_bf16 v[40:43], v[144:147], v[44:47], v[40:43]
	s_mov_b32 s0, 0x18000
	global_load_dwordx4 v[188:191], v[6:7], off offset:768
	s_waitcnt lgkmcnt(0)
	v_max_f32_e32 v73, v73, v73
	v_max_f32_e32 v71, v71, v73
	v_mov_b32_e32 v73, v71
	s_nop 1
	v_permlane32_swap_b32_e32 v73, v71
	v_mfma_f32_16x16x32_bf16 v[36:39], v[154:157], v[44:47], v[36:39]
	global_load_dwordx4 v[154:157], v[172:173], off offset:512
	s_waitcnt lgkmcnt(0)
	v_max3_f32 v135, v69, v71, v73
	v_sub_f32_e32 v45, v136, v135
	v_mul_f32_e32 v45, 0x3fb8aa3b, v45
	v_exp_f32_e32 v79, v45
	v_sub_f32_e32 v45, v137, v135
	v_mfma_f32_16x16x32_bf16 v[144:147], v[158:161], v[12:15], 0
	v_mul_f32_e32 v45, 0x3fb8aa3b, v45
	v_exp_f32_e32 v77, v45
	v_sub_f32_e32 v45, v138, v135
	v_mul_f32_e32 v45, 0x3fb8aa3b, v45
	v_exp_f32_e32 v75, v45
	v_sub_f32_e32 v45, v139, v135
	global_load_dwordx4 v[136:139], v[172:173], off offset:256
	v_mfma_f32_16x16x32_bf16 v[60:63], v[60:63], v[8:11], v[144:147]
	v_mul_f32_e32 v45, 0x3fb8aa3b, v45
	v_exp_f32_e32 v73, v45
	v_sub_f32_e32 v45, v162, v135
	global_load_dwordx4 v[144:147], v[172:173], off offset:768
	v_mul_f32_e32 v45, 0x3fb8aa3b, v45
	v_exp_f32_e32 v71, v45
	v_sub_f32_e32 v45, v163, v135
	v_mul_f32_e32 v45, 0x3fb8aa3b, v45
	v_sub_f32_e32 v44, v69, v135
	v_exp_f32_e32 v69, v45
	v_sub_f32_e32 v45, v164, v135
	v_mul_f32_e32 v45, 0x3fb8aa3b, v45
	v_exp_f32_e32 v115, v45
	v_sub_f32_e32 v45, v165, v135
	v_mul_f32_e32 v45, 0x3fb8aa3b, v45
	v_mfma_f32_16x16x32_bf16 v[52:55], v[52:55], v[12:15], 0
	v_mul_f32_e32 v44, 0x3fb8aa3b, v44
	v_exp_f32_e32 v121, v45
	v_exp_f32_e32 v120, v44
	v_add_u32_e32 v44, 0x8000, v77
	v_add_u32_e32 v45, 0x8000, v79
	v_perm_b32 v44, v44, v45, s87
	v_add_u32_e32 v45, 0x8000, v73
	v_add_u32_e32 v46, 0x8000, v75
	v_perm_b32 v45, v45, v46, s87
	v_add_u32_e32 v46, 0x8000, v69
	v_add_u32_e32 v47, 0x8000, v71
	v_mfma_f32_16x16x32_bf16 v[52:55], v[140:143], v[8:11], v[52:55]
	v_perm_b32 v46, v46, v47, s87
	v_add_u32_e32 v47, 0x8000, v121
	v_add_u32_e32 v119, 0x8000, v115
	v_perm_b32 v47, v47, v119, s87
	v_max_f32_e32 v119, v61, v61
	v_max_f32_e32 v123, v60, v60
	v_max_f32_e32 v119, v123, v119
	v_max_f32_e32 v123, v63, v63
	v_max_f32_e32 v125, v62, v62
	v_max_f32_e32 v123, v125, v123
	v_max_f32_e32 v125, v55, v55
	v_max_f32_e32 v127, v54, v54
	v_max_f32_e32 v125, v127, v125
	v_max3_f32 v125, v52, v53, v125
	v_max3_f32 v119, v119, v123, v125
	v_mov_b32_e32 v123, v119
	s_nop 1
	v_permlane16_swap_b32_e32 v123, v119
	v_pk_mul_f32 v[58:59], v[58:59], v[120:121] op_sel_hi:[1,0]
	v_pk_mul_f32 v[56:57], v[56:57], v[120:121] op_sel_hi:[1,0]
	v_pk_mul_f32 v[18:19], v[18:19], v[120:121] op_sel_hi:[1,0]
	v_pk_mul_f32 v[16:17], v[16:17], v[120:121] op_sel_hi:[1,0]
	s_waitcnt lgkmcnt(0)
	v_max_f32_e32 v123, v123, v123
	v_max_f32_e32 v119, v119, v123
	v_mov_b32_e32 v123, v119
	s_nop 1
	v_permlane32_swap_b32_e32 v123, v119
	v_pk_mul_f32 v[26:27], v[26:27], v[120:121] op_sel_hi:[1,0]
	v_pk_mul_f32 v[24:25], v[24:25], v[120:121] op_sel_hi:[1,0]
	v_pk_mul_f32 v[22:23], v[22:23], v[120:121] op_sel_hi:[1,0]
	v_pk_mul_f32 v[20:21], v[20:21], v[120:121] op_sel_hi:[1,0]
	s_waitcnt lgkmcnt(0)
	v_max3_f32 v152, v117, v119, v123
	s_waitcnt vmcnt(5)
	v_mfma_f32_16x16x32_bf16 v[56:59], v[168:171], v[44:47], v[56:59]
	v_add_co_u32_e32 v162, vcc, s0, v204
	s_mov_b32 s0, 0x1e000
	s_waitcnt vmcnt(1)
	v_mfma_f32_16x16x32_bf16 v[16:19], v[136:139], v[44:47], v[16:19]
	v_addc_co_u32_e32 v163, vcc, 0, v205, vcc
	global_load_dwordx4 v[158:161], v[162:163], off offset:16
	v_mfma_f32_16x16x32_bf16 v[24:27], v[154:157], v[44:47], v[24:27]
	s_waitcnt vmcnt(1)
	v_mfma_f32_16x16x32_bf16 v[20:23], v[144:147], v[44:47], v[20:23]
	v_sub_f32_e32 v45, v60, v152
	v_mul_f32_e32 v45, 0x3fb8aa3b, v45
	v_exp_f32_e32 v133, v45
	v_sub_f32_e32 v45, v61, v152
	v_mul_f32_e32 v45, 0x3fb8aa3b, v45
	v_exp_f32_e32 v131, v45
	v_sub_f32_e32 v45, v62, v152
	v_mul_f32_e32 v45, 0x3fb8aa3b, v45
	v_exp_f32_e32 v129, v45
	v_sub_f32_e32 v45, v63, v152
	v_mul_f32_e32 v45, 0x3fb8aa3b, v45
	v_exp_f32_e32 v127, v45
	v_sub_f32_e32 v45, v52, v152
	v_mul_f32_e32 v45, 0x3fb8aa3b, v45
	v_exp_f32_e32 v125, v45
	v_sub_f32_e32 v45, v53, v152
	v_mul_f32_e32 v45, 0x3fb8aa3b, v45
	v_exp_f32_e32 v123, v45
	v_sub_f32_e32 v45, v54, v152
	v_mul_f32_e32 v45, 0x3fb8aa3b, v45
	v_exp_f32_e32 v119, v45
	v_sub_f32_e32 v45, v55, v152
	v_sub_f32_e32 v44, v117, v152
	v_mul_f32_e32 v45, 0x3fb8aa3b, v45
	v_mul_f32_e32 v44, 0x3fb8aa3b, v44
	v_exp_f32_e32 v211, v45
	v_exp_f32_e32 v150, v44
	v_add_u32_e32 v44, 0x8000, v131
	v_add_u32_e32 v45, 0x8000, v133
	v_perm_b32 v44, v44, v45, s87
	v_add_u32_e32 v45, 0x8000, v127
	v_add_u32_e32 v46, 0x8000, v129
	v_perm_b32 v45, v45, v46, s87
	v_add_u32_e32 v46, 0x8000, v123
	v_add_u32_e32 v47, 0x8000, v125
	v_perm_b32 v46, v46, v47, s87
	v_add_u32_e32 v47, 0x8000, v211
	v_add_u32_e32 v52, 0x8000, v119
	v_perm_b32 v47, v47, v52, s87
	global_load_dwordx4 v[52:55], v[162:163], off
	global_load_dwordx4 v[60:63], v[162:163], off offset:3072
	v_pk_mul_f32 v[30:31], v[30:31], v[150:151] op_sel_hi:[1,0]
	global_load_dwordx4 v[162:165], v[162:163], off offset:3088
	v_pk_mul_f32 v[28:29], v[28:29], v[150:151] op_sel_hi:[1,0]
	s_waitcnt vmcnt(1)
	v_mfma_f32_16x16x32_bf16 v[140:143], v[60:63], v[48:51], 0
	v_mul_f32_e64 v34, v34, v150
	v_mul_f32_e64 v35, v35, v150
	v_pk_mul_f32 v[32:33], v[32:33], v[150:151] op_sel_hi:[1,0]
	v_pk_mul_f32 v[42:43], v[42:43], v[150:151] op_sel_hi:[1,0]
	v_mfma_f32_16x16x32_bf16 v[28:31], v[136:139], v[44:47], v[28:31]
	v_mul_f32_e64 v40, v40, v150
	v_mul_f32_e64 v41, v41, v150
	v_pk_mul_f32 v[38:39], v[38:39], v[150:151] op_sel_hi:[1,0]
	v_pk_mul_f32 v[36:37], v[36:37], v[150:151] op_sel_hi:[1,0]
	v_mfma_f32_16x16x32_bf16 v[136:139], v[52:55], v[48:51], 0
	v_mfma_f32_16x16x32_bf16 v[136:139], v[158:161], v[64:67], v[136:139]
	s_waitcnt vmcnt(0)
	v_mfma_f32_16x16x32_bf16 v[172:175], v[162:165], v[64:67], v[140:143]
	v_mfma_f32_16x16x32_bf16 v[32:35], v[168:171], v[44:47], v[32:35]
	s_nop 4
	v_max_f32_e32 v117, v137, v137
	v_max_f32_e32 v140, v136, v136
	v_max_f32_e32 v117, v140, v117
	v_max_f32_e32 v140, v139, v139
	v_max_f32_e32 v141, v138, v138
	v_max_f32_e32 v140, v141, v140
	v_max_f32_e32 v141, v175, v175
	v_max_f32_e32 v142, v174, v174
	v_max_f32_e32 v141, v142, v141
	v_max3_f32 v141, v172, v173, v141
	v_max3_f32 v117, v117, v140, v141
	v_mov_b32_e32 v140, v117
	s_nop 1
	v_permlane16_swap_b32_e32 v140, v117
	v_mfma_f32_16x16x32_bf16 v[40:43], v[154:157], v[44:47], v[40:43]
	global_load_dwordx4 v[168:171], v[6:7], off
	s_waitcnt lgkmcnt(0)
	v_max_f32_e32 v140, v140, v140
	v_max_f32_e32 v117, v117, v140
	v_mov_b32_e32 v140, v117
	s_nop 1
	v_permlane32_swap_b32_e32 v140, v117
	v_mfma_f32_16x16x32_bf16 v[36:39], v[144:147], v[44:47], v[36:39]
	s_waitcnt lgkmcnt(0)
	v_max3_f32 v117, v135, v117, v140
	v_sub_f32_e32 v45, v136, v117
	v_mul_f32_e32 v45, 0x3fb8aa3b, v45
	v_exp_f32_e32 v209, v45
	v_sub_f32_e32 v45, v137, v117
	v_mul_f32_e32 v45, 0x3fb8aa3b, v45
	v_exp_f32_e32 v210, v45
	v_sub_f32_e32 v45, v138, v117
	v_mul_f32_e32 v45, 0x3fb8aa3b, v45
	v_exp_f32_e32 v146, v45
	v_sub_f32_e32 v45, v139, v117
	v_mul_f32_e32 v45, 0x3fb8aa3b, v45
	v_exp_f32_e32 v144, v45
	v_sub_f32_e32 v45, v172, v117
	v_mul_f32_e32 v45, 0x3fb8aa3b, v45
	v_exp_f32_e32 v142, v45
	v_sub_f32_e32 v45, v173, v117
	v_mul_f32_e32 v45, 0x3fb8aa3b, v45
	v_exp_f32_e32 v140, v45
	v_sub_f32_e32 v45, v174, v117
	v_mul_f32_e32 v45, 0x3fb8aa3b, v45
	v_exp_f32_e32 v138, v45
	v_sub_f32_e32 v45, v175, v117
	global_load_dwordx4 v[172:175], v[6:7], off offset:256
	v_mfma_f32_16x16x32_bf16 v[52:55], v[52:55], v[12:15], 0
	v_sub_f32_e32 v44, v135, v117
	v_mul_f32_e32 v45, 0x3fb8aa3b, v45
	v_mul_f32_e32 v44, 0x3fb8aa3b, v44
	v_mfma_f32_16x16x32_bf16 v[60:63], v[60:63], v[12:15], 0
	v_exp_f32_e32 v136, v45
	v_exp_f32_e32 v148, v44
	v_add_u32_e32 v44, 0x8000, v210
	v_add_u32_e32 v45, 0x8000, v209
	v_mfma_f32_16x16x32_bf16 v[52:55], v[158:161], v[8:11], v[52:55]
	v_perm_b32 v44, v44, v45, s87
	v_add_u32_e32 v45, 0x8000, v144
	v_add_u32_e32 v46, 0x8000, v146
	v_perm_b32 v45, v45, v46, s87
	v_add_u32_e32 v46, 0x8000, v140
	v_add_u32_e32 v47, 0x8000, v142
	v_mfma_f32_16x16x32_bf16 v[60:63], v[162:165], v[8:11], v[60:63]
	v_perm_b32 v46, v46, v47, s87
	v_add_u32_e32 v47, 0x8000, v136
	v_add_u32_e32 v135, 0x8000, v138
	v_perm_b32 v47, v47, v135, s87
	v_max_f32_e32 v135, v53, v53
	v_max_f32_e32 v137, v52, v52
	v_max_f32_e32 v135, v137, v135
	v_max_f32_e32 v137, v55, v55
	v_max_f32_e32 v139, v54, v54
	v_max_f32_e32 v137, v139, v137
	v_max_f32_e32 v139, v63, v63
	v_max_f32_e32 v141, v62, v62
	v_max_f32_e32 v139, v141, v139
	v_max3_f32 v139, v60, v61, v139
	v_max3_f32 v135, v135, v137, v139
	v_mov_b32_e32 v137, v135
	s_nop 1
	v_permlane16_swap_b32_e32 v137, v135
	v_pk_mul_f32 v[58:59], v[58:59], v[148:149] op_sel_hi:[1,0]
	v_pk_mul_f32 v[56:57], v[56:57], v[148:149] op_sel_hi:[1,0]
	v_pk_mul_f32 v[18:19], v[18:19], v[148:149] op_sel_hi:[1,0]
	v_pk_mul_f32 v[16:17], v[16:17], v[148:149] op_sel_hi:[1,0]
	s_waitcnt lgkmcnt(0)
	v_max_f32_e32 v137, v137, v137
	v_max_f32_e32 v135, v135, v137
	v_mov_b32_e32 v137, v135
	s_nop 1
	v_permlane32_swap_b32_e32 v137, v135
	v_pk_mul_f32 v[26:27], v[26:27], v[148:149] op_sel_hi:[1,0]
	v_pk_mul_f32 v[24:25], v[24:25], v[148:149] op_sel_hi:[1,0]
	v_pk_mul_f32 v[22:23], v[22:23], v[148:149] op_sel_hi:[1,0]
	v_pk_mul_f32 v[20:21], v[20:21], v[148:149] op_sel_hi:[1,0]
	s_waitcnt lgkmcnt(0)
	v_max3_f32 v135, v152, v135, v137
	s_waitcnt vmcnt(1)
	v_mfma_f32_16x16x32_bf16 v[56:59], v[168:171], v[44:47], v[56:59]
	v_add_co_u32_e32 v6, vcc, s0, v204
	s_movk_i32 s0, 0x5000
	s_waitcnt vmcnt(0)
	v_mfma_f32_16x16x32_bf16 v[16:19], v[172:175], v[44:47], v[16:19]
	v_addc_co_u32_e32 v7, vcc, 0, v205, vcc
	global_load_dwordx4 v[194:197], v[6:7], off
	v_mfma_f32_16x16x32_bf16 v[24:27], v[176:179], v[44:47], v[24:27]
	v_add_co_u32_e32 v184, vcc, s1, v202
	v_mfma_f32_16x16x32_bf16 v[20:23], v[188:191], v[44:47], v[20:23]
	v_sub_f32_e32 v45, v52, v135
	v_mul_f32_e32 v45, 0x3fb8aa3b, v45
	v_exp_f32_e32 v213, v45
	v_sub_f32_e32 v45, v53, v135
	v_mul_f32_e32 v45, 0x3fb8aa3b, v45
	v_exp_f32_e32 v214, v45
	v_sub_f32_e32 v45, v54, v135
	v_mul_f32_e32 v45, 0x3fb8aa3b, v45
	v_exp_f32_e32 v164, v45
	v_sub_f32_e32 v45, v55, v135
	v_mul_f32_e32 v45, 0x3fb8aa3b, v45
	v_exp_f32_e32 v162, v45
	v_sub_f32_e32 v45, v60, v135
	v_mul_f32_e32 v45, 0x3fb8aa3b, v45
	v_exp_f32_e32 v160, v45
	v_sub_f32_e32 v45, v61, v135
	v_mul_f32_e32 v45, 0x3fb8aa3b, v45
	v_exp_f32_e32 v158, v45
	v_sub_f32_e32 v45, v62, v135
	v_mul_f32_e32 v45, 0x3fb8aa3b, v45
	v_exp_f32_e32 v156, v45
	v_sub_f32_e32 v45, v63, v135
	v_sub_f32_e32 v44, v152, v135
	v_mul_f32_e32 v45, 0x3fb8aa3b, v45
	v_mul_f32_e32 v44, 0x3fb8aa3b, v44
	v_exp_f32_e32 v154, v45
	v_exp_f32_e32 v166, v44
	v_add_u32_e32 v44, 0x8000, v214
	v_add_u32_e32 v45, 0x8000, v213
	v_perm_b32 v44, v44, v45, s87
	v_add_u32_e32 v45, 0x8000, v162
	v_add_u32_e32 v46, 0x8000, v164
	v_perm_b32 v45, v45, v46, s87
	v_add_u32_e32 v46, 0x8000, v158
	v_add_u32_e32 v47, 0x8000, v160
	v_perm_b32 v46, v46, v47, s87
	v_add_u32_e32 v47, 0x8000, v154
	v_add_u32_e32 v52, 0x8000, v156
	v_perm_b32 v47, v47, v52, s87
	global_load_dwordx4 v[52:55], v[6:7], off offset:3072
	global_load_dwordx4 v[60:63], v[6:7], off offset:16
	v_pk_mul_f32 v[30:31], v[30:31], v[166:167] op_sel_hi:[1,0]
	v_pk_mul_f32 v[28:29], v[28:29], v[166:167] op_sel_hi:[1,0]
	v_pk_mul_f32 v[34:35], v[34:35], v[166:167] op_sel_hi:[1,0]
	v_pk_mul_f32 v[32:33], v[32:33], v[166:167] op_sel_hi:[1,0]
	v_mfma_f32_16x16x32_bf16 v[28:31], v[172:175], v[44:47], v[28:31]
	global_load_dwordx4 v[172:175], v[6:7], off offset:3088
	v_pk_mul_f32 v[42:43], v[42:43], v[166:167] op_sel_hi:[1,0]
	v_pk_mul_f32 v[40:41], v[40:41], v[166:167] op_sel_hi:[1,0]
	v_mfma_f32_16x16x32_bf16 v[32:35], v[168:171], v[44:47], v[32:35]
	v_mul_f32_e64 v38, v38, v166
	v_mul_f32_e64 v39, v39, v166
	v_pk_mul_f32 v[36:37], v[36:37], v[166:167] op_sel_hi:[1,0]
	v_addc_co_u32_e32 v185, vcc, 0, v203, vcc
	s_waitcnt vmcnt(3)
	v_mfma_f32_16x16x32_bf16 v[168:171], v[194:197], v[48:51], 0
	global_load_dwordx4 v[216:219], v[184:185], off offset:-4096
	s_waitcnt vmcnt(3)
	v_mfma_f32_16x16x32_bf16 v[198:201], v[52:55], v[48:51], 0
	s_waitcnt vmcnt(2)
	v_mfma_f32_16x16x32_bf16 v[168:171], v[60:63], v[64:67], v[168:171]
	s_waitcnt vmcnt(1)
	v_mfma_f32_16x16x32_bf16 v[198:201], v[172:175], v[64:67], v[198:201]
	v_mfma_f32_16x16x32_bf16 v[40:43], v[176:179], v[44:47], v[40:43]
	s_nop 4
	v_max_f32_e32 v6, v169, v169
	v_max_f32_e32 v7, v168, v168
	v_max_f32_e32 v6, v7, v6
	v_max_f32_e32 v7, v171, v171
	v_max_f32_e32 v137, v170, v170
	v_max_f32_e32 v7, v137, v7
	v_max_f32_e32 v137, v201, v201
	v_max_f32_e32 v139, v200, v200
	v_max_f32_e32 v137, v139, v137
	v_max3_f32 v137, v198, v199, v137
	v_max3_f32 v7, v6, v7, v137
	v_mov_b32_e32 v137, v7
	s_nop 1
	v_permlane16_swap_b32_e32 v137, v7
	v_mfma_f32_16x16x32_bf16 v[36:39], v[188:191], v[44:47], v[36:39]
	v_add_co_u32_e32 v6, vcc, s0, v202
	s_mov_b32 s0, 0x24000
	s_waitcnt lgkmcnt(0)
	v_max_f32_e32 v137, v137, v137
	v_max_f32_e32 v137, v7, v137
	v_mov_b32_e32 v139, v137
	s_nop 1
	v_permlane32_swap_b32_e32 v139, v137
	v_mfma_f32_16x16x32_bf16 v[176:179], v[194:197], v[12:15], 0
	v_addc_co_u32_e32 v7, vcc, 0, v203, vcc
	global_load_dwordx4 v[188:191], v[6:7], off offset:512
	s_waitcnt lgkmcnt(0)
	v_max3_f32 v180, v117, v137, v139
	v_sub_f32_e32 v45, v168, v180
	v_mul_f32_e32 v45, 0x3fb8aa3b, v45
	v_exp_f32_e32 v147, v45
	v_sub_f32_e32 v45, v169, v180
	v_mul_f32_e32 v45, 0x3fb8aa3b, v45
	v_exp_f32_e32 v145, v45
	v_sub_f32_e32 v45, v170, v180
	v_mul_f32_e32 v45, 0x3fb8aa3b, v45
	v_exp_f32_e32 v143, v45
	v_sub_f32_e32 v45, v171, v180
	global_load_dwordx4 v[168:171], v[6:7], off offset:256
	v_mfma_f32_16x16x32_bf16 v[60:63], v[60:63], v[8:11], v[176:179]
	v_mul_f32_e32 v45, 0x3fb8aa3b, v45
	v_exp_f32_e32 v141, v45
	v_sub_f32_e32 v45, v198, v180
	global_load_dwordx4 v[176:179], v[6:7], off offset:768
	v_mul_f32_e32 v45, 0x3fb8aa3b, v45
	v_exp_f32_e32 v139, v45
	v_sub_f32_e32 v45, v199, v180
	v_mul_f32_e32 v45, 0x3fb8aa3b, v45
	v_exp_f32_e32 v137, v45
	v_sub_f32_e32 v45, v200, v180
	v_mul_f32_e32 v45, 0x3fb8aa3b, v45
	v_sub_f32_e32 v44, v117, v180
	v_exp_f32_e32 v117, v45
	v_sub_f32_e32 v45, v201, v180
	v_mfma_f32_16x16x32_bf16 v[52:55], v[52:55], v[12:15], 0
	v_mul_f32_e32 v45, 0x3fb8aa3b, v45
	v_mul_f32_e32 v44, 0x3fb8aa3b, v44
	v_exp_f32_e32 v212, v45
	v_exp_f32_e32 v152, v44
	v_add_u32_e32 v44, 0x8000, v145
	v_add_u32_e32 v45, 0x8000, v147
	v_perm_b32 v44, v44, v45, s87
	v_add_u32_e32 v45, 0x8000, v141
	v_add_u32_e32 v46, 0x8000, v143
	v_mfma_f32_16x16x32_bf16 v[52:55], v[172:175], v[8:11], v[52:55]
	v_perm_b32 v45, v45, v46, s87
	v_add_u32_e32 v46, 0x8000, v137
	v_add_u32_e32 v47, 0x8000, v139
	v_perm_b32 v46, v46, v47, s87
	v_add_u32_e32 v47, 0x8000, v212
	v_add_u32_e32 v155, 0x8000, v117
	v_max_f32_e32 v6, v61, v61
	v_max_f32_e32 v7, v60, v60
	v_perm_b32 v47, v47, v155, s87
	v_max_f32_e32 v6, v7, v6
	v_max_f32_e32 v7, v63, v63
	v_max_f32_e32 v155, v62, v62
	v_max_f32_e32 v7, v155, v7
	v_max_f32_e32 v155, v55, v55
	v_max_f32_e32 v157, v54, v54
	v_max_f32_e32 v155, v157, v155
	v_max3_f32 v155, v52, v53, v155
	v_max3_f32 v7, v6, v7, v155
	v_mov_b32_e32 v155, v7
	s_nop 1
	v_permlane16_swap_b32_e32 v155, v7
	v_pk_mul_f32 v[58:59], v[58:59], v[152:153] op_sel_hi:[1,0]
	v_pk_mul_f32 v[56:57], v[56:57], v[152:153] op_sel_hi:[1,0]
	v_pk_mul_f32 v[18:19], v[18:19], v[152:153] op_sel_hi:[1,0]
	v_pk_mul_f32 v[16:17], v[16:17], v[152:153] op_sel_hi:[1,0]
	s_waitcnt lgkmcnt(0)
	v_max_f32_e32 v155, v155, v155
	v_max_f32_e32 v155, v7, v155
	v_mov_b32_e32 v157, v155
	s_nop 1
	v_permlane32_swap_b32_e32 v157, v155
	v_pk_mul_f32 v[26:27], v[26:27], v[152:153] op_sel_hi:[1,0]
	v_pk_mul_f32 v[24:25], v[24:25], v[152:153] op_sel_hi:[1,0]
	v_pk_mul_f32 v[22:23], v[22:23], v[152:153] op_sel_hi:[1,0]
	v_pk_mul_f32 v[20:21], v[20:21], v[152:153] op_sel_hi:[1,0]
	s_waitcnt lgkmcnt(0)
	v_max3_f32 v173, v135, v155, v157
	s_waitcnt vmcnt(3)
	v_mfma_f32_16x16x32_bf16 v[56:59], v[216:219], v[44:47], v[56:59]
	v_add_co_u32_e32 v6, vcc, s0, v204
	s_mov_b32 s0, 0x2a000
	s_waitcnt vmcnt(1)
	v_mfma_f32_16x16x32_bf16 v[16:19], v[168:171], v[44:47], v[16:19]
	v_addc_co_u32_e32 v7, vcc, 0, v205, vcc
	global_load_dwordx4 v[194:197], v[6:7], off offset:16
	v_mfma_f32_16x16x32_bf16 v[24:27], v[188:191], v[44:47], v[24:27]
	global_load_dwordx4 v[198:201], v[6:7], off offset:3088
	v_add_co_u32_e32 v204, vcc, s0, v204
	s_waitcnt vmcnt(2)
	v_mfma_f32_16x16x32_bf16 v[20:23], v[176:179], v[44:47], v[20:23]
	v_sub_f32_e32 v45, v60, v173
	v_mul_f32_e32 v45, 0x3fb8aa3b, v45
	v_exp_f32_e32 v165, v45
	v_sub_f32_e32 v45, v61, v173
	v_mul_f32_e32 v45, 0x3fb8aa3b, v45
	v_exp_f32_e32 v163, v45
	v_sub_f32_e32 v45, v62, v173
	v_mul_f32_e32 v45, 0x3fb8aa3b, v45
	v_exp_f32_e32 v161, v45
	v_sub_f32_e32 v45, v63, v173
	v_mul_f32_e32 v45, 0x3fb8aa3b, v45
	v_exp_f32_e32 v159, v45
	v_sub_f32_e32 v45, v52, v173
	v_mul_f32_e32 v45, 0x3fb8aa3b, v45
	v_exp_f32_e32 v157, v45
	v_sub_f32_e32 v45, v53, v173
	v_mul_f32_e32 v45, 0x3fb8aa3b, v45
	v_exp_f32_e32 v155, v45
	v_sub_f32_e32 v45, v54, v173
	v_mul_f32_e32 v45, 0x3fb8aa3b, v45
	v_sub_f32_e32 v44, v135, v173
	v_exp_f32_e32 v135, v45
	v_sub_f32_e32 v45, v55, v173
	v_mul_f32_e32 v45, 0x3fb8aa3b, v45
	v_mul_f32_e32 v44, 0x3fb8aa3b, v44
	v_exp_f32_e32 v215, v45
	v_exp_f32_e32 v192, v44
	v_add_u32_e32 v44, 0x8000, v163
	v_add_u32_e32 v45, 0x8000, v165
	v_perm_b32 v44, v44, v45, s87
	v_add_u32_e32 v45, 0x8000, v159
	v_add_u32_e32 v46, 0x8000, v161
	v_perm_b32 v45, v45, v46, s87
	v_add_u32_e32 v46, 0x8000, v155
	v_add_u32_e32 v47, 0x8000, v157
	v_perm_b32 v46, v46, v47, s87
	v_add_u32_e32 v47, 0x8000, v215
	v_add_u32_e32 v52, 0x8000, v135
	v_perm_b32 v47, v47, v52, s87
	v_pk_mul_f32 v[30:31], v[30:31], v[192:193] op_sel_hi:[1,0]
	v_pk_mul_f32 v[28:29], v[28:29], v[192:193] op_sel_hi:[1,0]
	global_load_dwordx4 v[60:63], v[6:7], off
	v_pk_mul_f32 v[34:35], v[34:35], v[192:193] op_sel_hi:[1,0]
	v_mfma_f32_16x16x32_bf16 v[220:223], v[168:171], v[44:47], v[28:31]
	v_mul_f32_e64 v32, v32, v192
	v_mul_f32_e64 v33, v33, v192
	v_pk_mul_f32 v[38:39], v[38:39], v[192:193] op_sel_hi:[1,0]
	v_pk_mul_f32 v[36:37], v[36:37], v[192:193] op_sel_hi:[1,0]
	global_load_dwordx4 v[28:31], v[6:7], off offset:3072
	v_mfma_f32_16x16x32_bf16 v[52:55], v[216:219], v[44:47], v[32:35]
	v_mul_f32_e64 v42, v42, v192
	v_mul_f32_e64 v43, v43, v192
	v_pk_mul_f32 v[40:41], v[40:41], v[192:193] op_sel_hi:[1,0]
	v_addc_co_u32_e32 v205, vcc, 0, v205, vcc
	s_waitcnt vmcnt(1)
	v_mfma_f32_16x16x32_bf16 v[32:35], v[60:63], v[48:51], 0
	s_movk_i32 s0, 0x7000
	s_waitcnt vmcnt(0)
	v_mfma_f32_16x16x32_bf16 v[168:171], v[28:31], v[48:51], 0
	v_mfma_f32_16x16x32_bf16 v[32:35], v[194:197], v[64:67], v[32:35]
	v_mfma_f32_16x16x32_bf16 v[238:241], v[198:201], v[64:67], v[168:171]
	v_mfma_f32_16x16x32_bf16 v[250:253], v[176:179], v[44:47], v[36:39]
	s_nop 5
	v_max_f32_e32 v6, v33, v33
	v_max_f32_e32 v7, v32, v32
	v_max_f32_e32 v168, v241, v241
	v_max_f32_e32 v169, v240, v240
	v_max_f32_e32 v6, v7, v6
	v_max_f32_e32 v7, v35, v35
	v_max_f32_e32 v172, v34, v34
	v_max_f32_e32 v168, v169, v168
	v_max_f32_e32 v7, v172, v7
	v_max3_f32 v168, v238, v239, v168
	v_max3_f32 v6, v6, v7, v168
	v_mov_b32_e32 v7, v6
	s_nop 1
	v_permlane16_swap_b32_e32 v7, v6
	v_mfma_f32_16x16x32_bf16 v[246:249], v[188:191], v[44:47], v[40:43]
	s_waitcnt lgkmcnt(0)
	v_max_f32_e32 v7, v7, v7
	v_max_f32_e32 v6, v6, v7
	v_mov_b32_e32 v7, v6
	s_nop 1
	v_permlane32_swap_b32_e32 v7, v6
	s_waitcnt lgkmcnt(0)
	v_max3_f32 v6, v180, v6, v7
	v_sub_f32_e32 v32, v32, v6
	v_mul_f32_e32 v32, 0x3fb8aa3b, v32
	v_exp_f32_e32 v216, v32
	v_sub_f32_e32 v32, v33, v6
	v_mul_f32_e32 v32, 0x3fb8aa3b, v32
	v_exp_f32_e32 v217, v32
	v_sub_f32_e32 v32, v34, v6
	v_mul_f32_e32 v32, 0x3fb8aa3b, v32
	v_exp_f32_e32 v176, v32
	v_sub_f32_e32 v32, v35, v6
	v_mul_f32_e32 v32, 0x3fb8aa3b, v32
	v_exp_f32_e32 v174, v32
	v_sub_f32_e32 v32, v238, v6
	v_mul_f32_e32 v32, 0x3fb8aa3b, v32
	v_sub_f32_e32 v7, v180, v6
	v_exp_f32_e32 v172, v32
	v_sub_f32_e32 v32, v239, v6
	v_mul_f32_e32 v7, 0x3fb8aa3b, v7
	v_mul_f32_e32 v32, 0x3fb8aa3b, v32
	v_exp_f32_e32 v170, v32
	v_sub_f32_e32 v32, v240, v6
	v_exp_f32_e32 v180, v7
	v_mul_f32_e32 v32, 0x3fb8aa3b, v32
	v_exp_f32_e32 v168, v32
	v_sub_f32_e32 v32, v241, v6
	v_mul_f32_e32 v32, 0x3fb8aa3b, v32
	v_exp_f32_e32 v178, v32
	v_pk_mul_f32 v[34:35], v[58:59], v[180:181] op_sel_hi:[1,0]
	v_pk_mul_f32 v[32:33], v[56:57], v[180:181] op_sel_hi:[1,0]
	global_load_dwordx4 v[56:59], v[184:185], off
	global_load_dwordx4 v[238:241], v[184:185], off offset:256
	v_add_u32_e32 v7, 0x8000, v217
	v_add_u32_e32 v36, 0x8000, v216
	v_perm_b32 v44, v7, v36, s87
	v_add_u32_e32 v7, 0x8000, v174
	v_add_u32_e32 v36, 0x8000, v176
	v_perm_b32 v45, v7, v36, s87
	v_add_u32_e32 v7, 0x8000, v170
	v_add_u32_e32 v36, 0x8000, v172
	v_perm_b32 v46, v7, v36, s87
	v_add_u32_e32 v7, 0x8000, v178
	v_add_u32_e32 v36, 0x8000, v168
	v_pk_mul_f32 v[18:19], v[18:19], v[180:181] op_sel_hi:[1,0]
	v_pk_mul_f32 v[16:17], v[16:17], v[180:181] op_sel_hi:[1,0]
	v_perm_b32 v47, v7, v36, s87
	v_pk_mul_f32 v[26:27], v[26:27], v[180:181] op_sel_hi:[1,0]
	v_pk_mul_f32 v[24:25], v[24:25], v[180:181] op_sel_hi:[1,0]
	s_waitcnt vmcnt(0)
	v_mfma_f32_16x16x32_bf16 v[36:39], v[238:241], v[44:47], v[16:19]
	s_nop 2
	global_load_dwordx4 v[16:19], v[184:185], off offset:512
	v_pk_mul_f32 v[22:23], v[22:23], v[180:181] op_sel_hi:[1,0]
	global_load_dwordx4 v[184:187], v[184:185], off offset:768
	v_pk_mul_f32 v[20:21], v[20:21], v[180:181] op_sel_hi:[1,0]
	v_mfma_f32_16x16x32_bf16 v[32:35], v[56:59], v[44:47], v[32:35]
	s_waitcnt vmcnt(1)
	v_mfma_f32_16x16x32_bf16 v[40:43], v[16:19], v[44:47], v[24:27]
	s_waitcnt vmcnt(0)
	v_mfma_f32_16x16x32_bf16 v[44:47], v[184:187], v[44:47], v[20:23]
	v_mfma_f32_16x16x32_bf16 v[20:23], v[60:63], v[12:15], 0
	global_load_dwordx4 v[60:63], v[204:205], off
	v_mfma_f32_16x16x32_bf16 v[24:27], v[28:31], v[12:15], 0
	v_mfma_f32_16x16x32_bf16 v[20:23], v[194:197], v[8:11], v[20:23]
	v_mfma_f32_16x16x32_bf16 v[24:27], v[198:201], v[8:11], v[24:27]
	s_nop 6
	v_max_f32_e32 v7, v21, v21
	v_max_f32_e32 v28, v20, v20
	v_max_f32_e32 v7, v28, v7
	v_max_f32_e32 v28, v23, v23
	v_max_f32_e32 v29, v22, v22
	v_max_f32_e32 v28, v29, v28
	v_max_f32_e32 v29, v27, v27
	v_max_f32_e32 v30, v26, v26
	v_max_f32_e32 v29, v30, v29
	v_max3_f32 v29, v24, v25, v29
	v_max3_f32 v7, v7, v28, v29
	v_mov_b32_e32 v28, v7
	s_nop 1
	v_permlane16_swap_b32_e32 v28, v7
	s_waitcnt lgkmcnt(0)
	v_max_f32_e32 v28, v28, v28
	v_max_f32_e32 v7, v7, v28
	v_mov_b32_e32 v28, v7
	s_nop 1
	v_permlane32_swap_b32_e32 v28, v7
	s_waitcnt lgkmcnt(0)
	v_max3_f32 v189, v173, v7, v28
	v_sub_f32_e32 v7, v173, v189
	v_mul_f32_e32 v7, 0x3fb8aa3b, v7
	v_exp_f32_e32 v182, v7
	v_sub_f32_e32 v7, v20, v189
	v_sub_f32_e32 v20, v21, v189
	v_mul_f32_e32 v7, 0x3fb8aa3b, v7
	v_exp_f32_e32 v218, v7
	v_mul_f32_e32 v7, 0x3fb8aa3b, v20
	v_exp_f32_e32 v219, v7
	v_sub_f32_e32 v21, v22, v189
	v_sub_f32_e32 v22, v23, v189
	v_mul_f32_e32 v7, 0x3fb8aa3b, v21
	v_mul_f32_e32 v20, 0x3fb8aa3b, v22
	v_sub_f32_e32 v23, v24, v189
	v_sub_f32_e32 v24, v25, v189
	v_exp_f32_e32 v188, v20
	v_exp_f32_e32 v190, v7
	v_add_u32_e32 v7, 0x8000, v219
	v_add_u32_e32 v20, 0x8000, v218
	v_pk_mul_f32 v[28:29], v[52:53], v[182:183] op_sel_hi:[1,0]
	v_perm_b32 v52, v7, v20, s87
	v_mul_f32_e32 v7, 0x3fb8aa3b, v23
	v_mul_f32_e32 v20, 0x3fb8aa3b, v24
	v_exp_f32_e32 v194, v20
	v_exp_f32_e32 v196, v7
	v_sub_f32_e32 v25, v26, v189
	v_sub_f32_e32 v26, v27, v189
	v_add_u32_e32 v7, 0x8000, v194
	v_add_u32_e32 v20, 0x8000, v196
	v_pk_mul_f32 v[30:31], v[54:55], v[182:183] op_sel_hi:[1,0]
	v_perm_b32 v54, v7, v20, s87
	v_mul_f32_e32 v7, 0x3fb8aa3b, v25
	v_mul_f32_e32 v20, 0x3fb8aa3b, v26
	v_exp_f32_e32 v198, v20
	v_exp_f32_e32 v200, v7
	v_add_u32_e32 v21, 0x8000, v188
	v_add_u32_e32 v22, 0x8000, v190
	v_add_u32_e32 v7, 0x8000, v198
	v_add_u32_e32 v20, 0x8000, v200
	v_perm_b32 v53, v21, v22, s87
	v_perm_b32 v55, v7, v20, s87
	v_pk_mul_f32 v[22:23], v[222:223], v[182:183] op_sel_hi:[1,0]
	v_pk_mul_f32 v[20:21], v[220:221], v[182:183] op_sel_hi:[1,0]
	v_mfma_f32_16x16x32_bf16 v[28:31], v[56:59], v[52:55], v[28:31]
	global_load_dwordx4 v[56:59], v[204:205], off offset:3072
	v_mfma_f32_16x16x32_bf16 v[24:27], v[238:241], v[52:55], v[20:23]
	s_nop 2
	v_mul_f32_e64 v22, v248, v182
	v_mul_f32_e64 v23, v249, v182
	v_pk_mul_f32 v[20:21], v[246:247], v[182:183] op_sel_hi:[1,0]
	s_waitcnt vmcnt(0)
	v_mfma_f32_16x16x32_bf16 v[220:223], v[56:59], v[48:51], 0
	v_mfma_f32_16x16x32_bf16 v[20:23], v[16:19], v[52:55], v[20:23]
	v_mul_f32_e64 v18, v252, v182
	v_mul_f32_e64 v19, v253, v182
	v_pk_mul_f32 v[16:17], v[250:251], v[182:183] op_sel_hi:[1,0]
	s_nop 1
	v_mfma_f32_16x16x32_bf16 v[16:19], v[184:187], v[52:55], v[16:19]
	global_load_dwordx4 v[52:55], v[204:205], off offset:16
	v_mfma_f32_16x16x32_bf16 v[184:187], v[60:63], v[48:51], 0
	global_load_dwordx4 v[48:51], v[204:205], off offset:3088
	s_waitcnt vmcnt(1)
	v_mfma_f32_16x16x32_bf16 v[184:187], v[52:55], v[64:67], v[184:187]
	s_nop 7
	v_max_f32_e32 v7, v185, v185
	s_waitcnt vmcnt(0)
	v_mfma_f32_16x16x32_bf16 v[220:223], v[48:51], v[64:67], v[220:223]
	v_max_f32_e32 v64, v184, v184
	v_max_f32_e32 v7, v64, v7
	v_max_f32_e32 v64, v187, v187
	v_max_f32_e32 v65, v186, v186
	v_max_f32_e32 v64, v65, v64
	s_nop 2
	v_max_f32_e32 v65, v223, v223
	v_max_f32_e32 v66, v222, v222
	v_max_f32_e32 v65, v66, v65
	v_max3_f32 v65, v220, v221, v65
	v_max3_f32 v7, v7, v64, v65
	v_mov_b32_e32 v64, v7
	s_nop 1
	v_permlane16_swap_b32_e32 v64, v7
	v_mfma_f32_16x16x32_bf16 v[60:63], v[60:63], v[12:15], 0
	s_waitcnt lgkmcnt(0)
	v_max_f32_e32 v64, v64, v64
	v_max_f32_e32 v7, v7, v64
	v_mov_b32_e32 v64, v7
	s_nop 1
	v_permlane32_swap_b32_e32 v64, v7
	v_mfma_f32_16x16x32_bf16 v[12:15], v[56:59], v[12:15], 0
	s_waitcnt lgkmcnt(0)
	v_max3_f32 v173, v6, v7, v64
	v_sub_f32_e32 v66, v220, v173
	v_add_co_u32_e32 v220, vcc, s0, v202
	v_sub_f32_e32 v65, v221, v173
	s_nop 0
	v_addc_co_u32_e32 v221, vcc, 0, v203, vcc
	global_load_dwordx4 v[56:59], v[220:221], off
	v_sub_f32_e32 v175, v184, v173
	v_sub_f32_e32 v171, v185, v173
	v_sub_f32_e32 v169, v186, v173
	v_sub_f32_e32 v67, v187, v173
	v_sub_f32_e32 v64, v222, v173
	v_sub_f32_e32 v7, v223, v173
	v_sub_f32_e32 v6, v6, v173
	v_mul_f32_e32 v173, 0x3fb8aa3b, v175
	v_mul_f32_e32 v171, 0x3fb8aa3b, v171
	v_exp_f32_e32 v177, v173
	v_exp_f32_e32 v175, v171
	v_mul_f32_e32 v169, 0x3fb8aa3b, v169
	v_mul_f32_e32 v67, 0x3fb8aa3b, v67
	v_exp_f32_e32 v173, v169
	v_exp_f32_e32 v171, v67
	v_mul_f32_e32 v66, 0x3fb8aa3b, v66
	v_mul_f32_e32 v65, 0x3fb8aa3b, v65
	v_exp_f32_e32 v169, v66
	v_exp_f32_e32 v179, v65
	v_mul_f32_e32 v64, 0x3fb8aa3b, v64
	v_mul_f32_e32 v7, 0x3fb8aa3b, v7
	v_mul_f32_e32 v6, 0x3fb8aa3b, v6
	v_exp_f32_e32 v67, v64
	v_exp_f32_e32 v65, v7
	v_exp_f32_e32 v64, v6
	v_add_u32_e32 v6, 0x8000, v175
	v_add_u32_e32 v7, 0x8000, v177
	v_perm_b32 v184, v6, v7, s87
	v_add_u32_e32 v6, 0x8000, v171
	v_add_u32_e32 v7, 0x8000, v173
	v_perm_b32 v185, v6, v7, s87
	v_add_u32_e32 v6, 0x8000, v179
	v_add_u32_e32 v7, 0x8000, v169
	v_perm_b32 v186, v6, v7, s87
	v_add_u32_e32 v6, 0x8000, v65
	v_add_u32_e32 v7, 0x8000, v67
	v_mfma_f32_16x16x32_bf16 v[52:55], v[52:55], v[8:11], v[60:63]
	v_perm_b32 v187, v6, v7, s87
	v_pk_mul_f32 v[6:7], v[32:33], v[64:65] op_sel_hi:[1,0]
	v_pk_mul_f32 v[204:205], v[46:47], v[64:65] op_sel_hi:[1,0]
	v_mfma_f32_16x16x32_bf16 v[48:51], v[48:51], v[8:11], v[12:15]
	v_mul_f32_e64 v8, v34, v64
	v_mul_f32_e64 v9, v35, v64
	v_pk_mul_f32 v[202:203], v[44:45], v[64:65] op_sel_hi:[1,0]
	global_load_dwordx4 v[44:47], v[220:221], off offset:256
	s_waitcnt vmcnt(1)
	v_mfma_f32_16x16x32_bf16 v[32:35], v[56:59], v[184:187], v[6:9]
	s_nop 2
	v_mul_f32_e64 v8, v38, v64
	v_mul_f32_e64 v9, v39, v64
	v_pk_mul_f32 v[6:7], v[36:37], v[64:65] op_sel_hi:[1,0]
	v_pk_mul_f32 v[38:39], v[42:43], v[64:65] op_sel_hi:[1,0]
	v_pk_mul_f32 v[36:37], v[40:41], v[64:65] op_sel_hi:[1,0]
	global_load_dwordx4 v[40:43], v[220:221], off offset:512
	global_load_dwordx4 v[60:63], v[220:221], off offset:768
	v_max_f32_e32 v14, v53, v53
	v_max_f32_e32 v15, v52, v52
	v_max_f32_e32 v14, v15, v14
	v_max_f32_e32 v15, v55, v55
	v_max_f32_e32 v66, v54, v54
	s_waitcnt vmcnt(2)
	v_mfma_f32_16x16x32_bf16 v[10:13], v[44:47], v[184:187], v[6:9]
	v_max_f32_e32 v15, v66, v15
	v_max_f32_e32 v66, v51, v51
	s_waitcnt vmcnt(1)
	v_mfma_f32_16x16x32_bf16 v[6:9], v[40:43], v[184:187], v[36:39]
	s_waitcnt vmcnt(0)
	v_mfma_f32_16x16x32_bf16 v[36:39], v[60:63], v[184:187], v[202:205]
	v_max_f32_e32 v184, v50, v50
	v_max_f32_e32 v66, v184, v66
	v_max3_f32 v66, v48, v49, v66
	v_max3_f32 v14, v14, v15, v66
	v_mov_b32_e32 v15, v14
	s_nop 1
	v_permlane16_swap_b32_e32 v15, v14
	s_waitcnt lgkmcnt(0)
	v_max_f32_e32 v15, v15, v15
	v_max_f32_e32 v14, v14, v15
	v_mov_b32_e32 v15, v14
	s_nop 1
	v_permlane32_swap_b32_e32 v15, v14
	s_waitcnt lgkmcnt(0)
	v_max3_f32 v14, v189, v14, v15
	v_sub_f32_e32 v52, v52, v14
	v_mul_f32_e32 v52, 0x3fb8aa3b, v52
	v_exp_f32_e32 v191, v52
	v_sub_f32_e32 v52, v53, v14
	v_mul_f32_e32 v52, 0x3fb8aa3b, v52
	v_sub_f32_e32 v15, v189, v14
	v_exp_f32_e32 v189, v52
	v_sub_f32_e32 v52, v54, v14
	v_sub_f32_e32 v48, v48, v14
	v_mul_f32_e32 v52, 0x3fb8aa3b, v52
	v_mul_f32_e32 v48, 0x3fb8aa3b, v48
	v_exp_f32_e32 v197, v52
	v_sub_f32_e32 v52, v55, v14
	v_exp_f32_e32 v201, v48
	v_sub_f32_e32 v48, v49, v14
	v_mul_f32_e32 v52, 0x3fb8aa3b, v52
	v_mul_f32_e32 v48, 0x3fb8aa3b, v48
	v_exp_f32_e32 v195, v52
	v_exp_f32_e32 v199, v48
	v_sub_f32_e32 v48, v50, v14
	v_sub_f32_e32 v14, v51, v14
	v_mul_f32_e32 v48, 0x3fb8aa3b, v48
	v_mul_f32_e32 v14, 0x3fb8aa3b, v14
	v_mul_f32_e32 v15, 0x3fb8aa3b, v15
	v_exp_f32_e32 v53, v48
	v_exp_f32_e32 v51, v14
	v_exp_f32_e32 v50, v15
	v_add_u32_e32 v14, 0x8000, v189
	v_add_u32_e32 v15, 0x8000, v191
	v_perm_b32 v184, v14, v15, s87
	v_add_u32_e32 v14, 0x8000, v195
	v_add_u32_e32 v15, 0x8000, v197
	v_perm_b32 v185, v14, v15, s87
	v_add_u32_e32 v14, 0x8000, v199
	v_add_u32_e32 v15, 0x8000, v201
	v_perm_b32 v186, v14, v15, s87
	v_add_u32_e32 v14, 0x8000, v51
	v_add_u32_e32 v15, 0x8000, v53
	v_perm_b32 v187, v14, v15, s87
	v_lshl_add_u64 v[14:15], s[6:7], 0, v[0:1]
	v_lshlrev_b32_e32 v0, 11, v89
	v_lshl_add_u64 v[48:49], v[14:15], 0, s[44:45]
	v_lshl_add_u64 v[14:15], s[6:7], 0, v[0:1]
	v_pk_mul_f32 v[22:23], v[22:23], v[50:51] op_sel_hi:[1,0]
	v_pk_mul_f32 v[20:21], v[20:21], v[50:51] op_sel_hi:[1,0]
	v_pk_mul_f32 v[18:19], v[18:19], v[50:51] op_sel_hi:[1,0]
	v_pk_mul_f32 v[16:17], v[16:17], v[50:51] op_sel_hi:[1,0]
	v_add_f32_e32 v0, 0, v218
	v_mfma_f32_16x16x32_bf16 v[20:23], v[40:43], v[184:187], v[20:23]
	v_lshl_add_u64 v[40:41], v[14:15], 0, s[44:45]
	v_pk_mul_f32 v[26:27], v[26:27], v[50:51] op_sel_hi:[1,0]
	v_pk_mul_f32 v[24:25], v[24:25], v[50:51] op_sel_hi:[1,0]
	v_mfma_f32_16x16x32_bf16 v[14:17], v[60:63], v[184:187], v[16:19]
	v_mov_b32_e32 v43, v1
	v_mov_b32_e32 v89, v1
	v_pk_mul_f32 v[30:31], v[30:31], v[50:51] op_sel_hi:[1,0]
	v_add_f32_e32 v18, v219, v0
	v_add_f32_e32 v0, 0, v213
	v_add_f32_e32 v42, v214, v0
	v_add_f32_e32 v0, 0, v207
	v_mfma_f32_16x16x32_bf16 v[24:27], v[44:47], v[184:187], v[24:27]
	v_add_f32_e32 v44, v208, v0
	v_add_f32_e32 v0, 0, v151
	v_add_f32_e32 v0, v153, v0
	v_pk_add_f32 v[46:47], v[112:113], v[0:1]
	v_mov_b32_e32 v45, v1
	v_pk_add_f32 v[46:47], v[110:111], v[46:47]
	v_pk_mul_f32 v[28:29], v[28:29], v[50:51] op_sel_hi:[1,0]
	v_pk_add_f32 v[46:47], v[108:109], v[46:47]
	s_nop 0
	v_pk_add_f32 v[46:47], v[106:107], v[46:47]
	v_mfma_f32_16x16x32_bf16 v[28:31], v[56:59], v[184:187], v[28:31]
	v_add_f32_e64 v46, v104, v46
	v_add_f32_e64 v47, v105, v47
	v_pk_add_f32 v[46:47], v[102:103], v[46:47]
	s_nop 0
	v_pk_add_f32 v[4:5], v[4:5], v[46:47]
	s_nop 0
	v_add_f32_e32 v0, v5, v206
	v_fmac_f32_e32 v0, v4, v118
	v_pk_add_f32 v[4:5], v[132:133], v[44:45]
	v_mul_f32_e32 v118, v0, v134
	v_pk_add_f32 v[4:5], v[130:131], v[4:5]
	s_nop 0
	v_pk_add_f32 v[4:5], v[128:129], v[4:5]
	s_nop 0
	v_pk_add_f32 v[4:5], v[126:127], v[4:5]
	s_nop 0
	v_pk_add_f32 v[4:5], v[124:125], v[4:5]
	s_nop 0
	v_pk_add_f32 v[4:5], v[122:123], v[4:5]
	s_nop 0
	v_pk_add_f32 v[4:5], v[118:119], v[4:5]
	s_nop 0
	v_add_f32_e32 v0, v5, v211
	v_fmac_f32_e32 v0, v4, v150
	v_pk_add_f32 v[4:5], v[164:165], v[42:43]
	v_mul_f32_e32 v134, v0, v166
	v_pk_add_f32 v[4:5], v[162:163], v[4:5]
	v_add_f32_e32 v0, 0, v216
	v_pk_add_f32 v[4:5], v[160:161], v[4:5]
	s_nop 0
	v_pk_add_f32 v[4:5], v[158:159], v[4:5]
	s_nop 0
	v_pk_add_f32 v[4:5], v[156:157], v[4:5]
	s_nop 0
	v_pk_add_f32 v[4:5], v[154:155], v[4:5]
	s_nop 0
	v_pk_add_f32 v[4:5], v[134:135], v[4:5]
	s_nop 0
	v_add_f32_e32 v19, v5, v215
	v_fmac_f32_e32 v19, v4, v192
	v_add_f32_e32 v4, v217, v0
	v_add_f32_e32 v0, 0, v209
	v_add_f32_e32 v42, v210, v0
	v_add_f32_e32 v0, 0, v181
	v_add_f32_e32 v44, v193, v0
	v_add_f32_e32 v0, 0, v85
	v_add_f32_e32 v0, v87, v0
	v_pk_add_f32 v[46:47], v[100:101], v[0:1]
	v_mov_b32_e32 v5, v1
	v_pk_add_f32 v[46:47], v[98:99], v[46:47]
	v_mul_f32_e32 v52, v19, v182
	v_pk_add_f32 v[46:47], v[96:97], v[46:47]
	v_mov_b32_e32 v19, v1
	v_pk_add_f32 v[46:47], v[94:95], v[46:47]
	s_nop 0
	v_pk_add_f32 v[46:47], v[92:93], v[46:47]
	s_nop 0
	v_pk_add_f32 v[46:47], v[90:91], v[46:47]
	s_nop 0
	v_pk_add_f32 v[2:3], v[2:3], v[46:47]
	s_nop 0
	v_add_f32_e32 v0, v3, v167
	v_fmac_f32_e32 v0, v2, v114
	v_pk_add_f32 v[2:3], v[78:79], v[44:45]
	v_mul_f32_e32 v114, v0, v116
	v_pk_add_f32 v[2:3], v[76:77], v[2:3]
	s_nop 0
	v_pk_add_f32 v[2:3], v[74:75], v[2:3]
	s_nop 0
	v_pk_add_f32 v[2:3], v[72:73], v[2:3]
	s_nop 0
	v_pk_add_f32 v[2:3], v[70:71], v[2:3]
	s_nop 0
	v_pk_add_f32 v[2:3], v[68:69], v[2:3]
	s_nop 0
	v_pk_add_f32 v[2:3], v[114:115], v[2:3]
	s_nop 0
	v_add_f32_e32 v0, v3, v121
	v_fmac_f32_e32 v0, v2, v120
	v_pk_add_f32 v[2:3], v[146:147], v[42:43]
	v_mul_f32_e32 v116, v0, v148
	v_pk_add_f32 v[2:3], v[144:145], v[2:3]
	s_nop 0
	v_pk_add_f32 v[2:3], v[142:143], v[2:3]
	s_nop 0
	v_pk_add_f32 v[2:3], v[140:141], v[2:3]
	s_nop 0
	v_pk_add_f32 v[2:3], v[138:139], v[2:3]
	s_nop 0
	v_pk_add_f32 v[2:3], v[136:137], v[2:3]
	s_nop 0
	v_pk_add_f32 v[2:3], v[116:117], v[2:3]
	s_nop 0
	v_add_f32_e32 v0, v3, v212
	v_fmac_f32_e32 v0, v2, v152
	v_pk_add_f32 v[2:3], v[176:177], v[4:5]
	v_mul_f32_e32 v66, v0, v180
	v_pk_add_f32 v[2:3], v[174:175], v[2:3]
	s_nop 0
	v_pk_add_f32 v[2:3], v[172:173], v[2:3]
	s_nop 0
	v_pk_add_f32 v[2:3], v[170:171], v[2:3]
	s_nop 0
	v_pk_add_f32 v[2:3], v[168:169], v[2:3]
	s_nop 0
	v_pk_add_f32 v[2:3], v[178:179], v[2:3]
	s_nop 0
	v_pk_add_f32 v[2:3], v[66:67], v[2:3]
	s_nop 0
	v_add_f32_e32 v0, v3, v65
	v_fmac_f32_e32 v0, v2, v64
	v_mov_b32_e32 v4, v0
	s_nop 1
	v_permlane16_swap_b32_e32 v4, v0
	v_pk_add_f32 v[2:3], v[190:191], v[18:19]
	s_waitcnt lgkmcnt(0)
	v_add_f32_e32 v0, v0, v4
	v_mov_b32_e32 v4, v0
	s_nop 1
	v_permlane32_swap_b32_e32 v4, v0
	v_pk_add_f32 v[2:3], v[188:189], v[2:3]
	s_waitcnt lgkmcnt(0)
	v_add_f32_e32 v0, v0, v4
	v_pk_add_f32 v[2:3], v[196:197], v[2:3]
	v_div_scale_f32 v4, s[0:1], v0, v0, 1.0
	v_pk_add_f32 v[2:3], v[194:195], v[2:3]
	v_rcp_f32_e32 v5, v4
	v_pk_add_f32 v[2:3], v[200:201], v[2:3]
	s_nop 0
	v_pk_add_f32 v[2:3], v[198:199], v[2:3]
	s_nop 0
	v_pk_add_f32 v[2:3], v[52:53], v[2:3]
	s_nop 0
	v_add_f32_e32 v42, v3, v51
	v_fmac_f32_e32 v42, v2, v50
	v_fma_f32 v2, -v4, v5, 1.0
	v_fmac_f32_e32 v5, v2, v5
	v_div_scale_f32 v2, vcc, 1.0, v0, 1.0
	v_mul_f32_e32 v3, v2, v5
	v_fma_f32 v18, -v4, v3, v2
	v_fmac_f32_e32 v3, v18, v5
	v_fma_f32 v2, -v4, v3, v2
	v_div_fmas_f32 v2, v2, v5, v3
	v_div_fixup_f32 v0, v2, v0, 1.0
	v_mov_b32_e32 v2, v32
	v_mov_b32_e32 v3, v34
	v_pk_mul_f32 v[2:3], v[2:3], v[0:1] op_sel_hi:[1,0]
	v_mov_b32_e32 v34, v33
	v_pk_mul_f32 v[4:5], v[34:35], v[0:1] op_sel_hi:[1,0]
	v_and_b32_sdwa v18, v3, v236 dst_sel:DWORD dst_unused:UNUSED_PAD src0_sel:WORD_1 src1_sel:DWORD
	v_and_b32_sdwa v19, v2, v236 dst_sel:DWORD dst_unused:UNUSED_PAD src0_sel:WORD_1 src1_sel:DWORD
	v_add3_u32 v2, v2, v19, s60
	v_add3_u32 v3, v3, v18, s60
	v_and_b32_sdwa v18, v5, v236 dst_sel:DWORD dst_unused:UNUSED_PAD src0_sel:WORD_1 src1_sel:DWORD
	v_and_b32_sdwa v19, v4, v236 dst_sel:DWORD dst_unused:UNUSED_PAD src0_sel:WORD_1 src1_sel:DWORD
	v_add3_u32 v5, v5, v18, s60
	v_add3_u32 v4, v4, v19, s60
	v_and_b32_e32 v5, 0xffff0000, v5
	v_and_b32_e32 v4, 0xffff0000, v4
	v_or_b32_sdwa v3, v5, v3 dst_sel:DWORD dst_unused:UNUSED_PAD src0_sel:DWORD src1_sel:WORD_1
	v_or_b32_sdwa v2, v4, v2 dst_sel:DWORD dst_unused:UNUSED_PAD src0_sel:DWORD src1_sel:WORD_1
	v_lshl_add_u64 v[4:5], v[48:49], 0, v[88:89]
	v_lshl_add_u64 v[18:19], v[4:5], 0, s[18:19]
	v_add_co_u32_e32 v4, vcc, s2, v4
	s_nop 1
	v_addc_co_u32_e32 v5, vcc, 0, v5, vcc
	global_store_dwordx2 v[4:5], v[2:3], off offset:512 sc1
	v_mov_b32_e32 v2, v10
	v_mov_b32_e32 v3, v12
	v_pk_mul_f32 v[2:3], v[2:3], v[0:1] op_sel_hi:[1,0]
	v_mov_b32_e32 v12, v11
	v_pk_mul_f32 v[4:5], v[12:13], v[0:1] op_sel_hi:[1,0]
	v_and_b32_sdwa v10, v3, v236 dst_sel:DWORD dst_unused:UNUSED_PAD src0_sel:WORD_1 src1_sel:DWORD
	v_and_b32_sdwa v11, v2, v236 dst_sel:DWORD dst_unused:UNUSED_PAD src0_sel:WORD_1 src1_sel:DWORD
	v_add3_u32 v2, v2, v11, s60
	v_add3_u32 v3, v3, v10, s60
	v_and_b32_sdwa v10, v5, v236 dst_sel:DWORD dst_unused:UNUSED_PAD src0_sel:WORD_1 src1_sel:DWORD
	v_and_b32_sdwa v11, v4, v236 dst_sel:DWORD dst_unused:UNUSED_PAD src0_sel:WORD_1 src1_sel:DWORD
	v_add3_u32 v5, v5, v10, s60
	v_add3_u32 v4, v4, v11, s60
	v_and_b32_e32 v5, 0xffff0000, v5
	v_and_b32_e32 v4, 0xffff0000, v4
	v_or_b32_sdwa v3, v5, v3 dst_sel:DWORD dst_unused:UNUSED_PAD src0_sel:DWORD src1_sel:WORD_1
	v_or_b32_sdwa v2, v4, v2 dst_sel:DWORD dst_unused:UNUSED_PAD src0_sel:DWORD src1_sel:WORD_1
	global_store_dwordx2 v[18:19], v[2:3], off offset:32 sc1
	v_mov_b32_e32 v2, v6
	v_mov_b32_e32 v3, v8
	v_pk_mul_f32 v[2:3], v[2:3], v[0:1] op_sel_hi:[1,0]
	v_mov_b32_e32 v8, v7
	v_pk_mul_f32 v[4:5], v[8:9], v[0:1] op_sel_hi:[1,0]
	v_and_b32_sdwa v7, v2, v236 dst_sel:DWORD dst_unused:UNUSED_PAD src0_sel:WORD_1 src1_sel:DWORD
	v_add3_u32 v2, v2, v7, s60
	v_and_b32_sdwa v7, v4, v236 dst_sel:DWORD dst_unused:UNUSED_PAD src0_sel:WORD_1 src1_sel:DWORD
	v_add3_u32 v4, v4, v7, s60
	v_mov_b32_e32 v7, v42
	s_nop 1
	v_permlane16_swap_b32_e32 v7, v42
	v_and_b32_sdwa v6, v3, v236 dst_sel:DWORD dst_unused:UNUSED_PAD src0_sel:WORD_1 src1_sel:DWORD
	v_add3_u32 v3, v3, v6, s60
	v_and_b32_sdwa v6, v5, v236 dst_sel:DWORD dst_unused:UNUSED_PAD src0_sel:WORD_1 src1_sel:DWORD
	v_add3_u32 v5, v5, v6, s60
	v_and_b32_e32 v5, 0xffff0000, v5
	v_and_b32_e32 v4, 0xffff0000, v4
	s_waitcnt lgkmcnt(0)
	v_add_f32_e32 v7, v42, v7
	v_or_b32_sdwa v3, v5, v3 dst_sel:DWORD dst_unused:UNUSED_PAD src0_sel:DWORD src1_sel:WORD_1
	v_or_b32_sdwa v2, v4, v2 dst_sel:DWORD dst_unused:UNUSED_PAD src0_sel:DWORD src1_sel:WORD_1
	v_mov_b32_e32 v8, v7
	s_nop 1
	v_permlane32_swap_b32_e32 v8, v7
	global_store_dwordx2 v[18:19], v[2:3], off offset:64 sc1
	v_mov_b32_e32 v2, v36
	v_mov_b32_e32 v3, v38
	v_pk_mul_f32 v[2:3], v[2:3], v[0:1] op_sel_hi:[1,0]
	v_mov_b32_e32 v38, v37
	v_pk_mul_f32 v[4:5], v[38:39], v[0:1] op_sel_hi:[1,0]
	v_and_b32_sdwa v0, v3, v236 dst_sel:DWORD dst_unused:UNUSED_PAD src0_sel:WORD_1 src1_sel:DWORD
	v_and_b32_sdwa v6, v2, v236 dst_sel:DWORD dst_unused:UNUSED_PAD src0_sel:WORD_1 src1_sel:DWORD
	v_add3_u32 v0, v3, v0, s60
	v_and_b32_sdwa v3, v5, v236 dst_sel:DWORD dst_unused:UNUSED_PAD src0_sel:WORD_1 src1_sel:DWORD
	v_add3_u32 v2, v2, v6, s60
	v_and_b32_sdwa v6, v4, v236 dst_sel:DWORD dst_unused:UNUSED_PAD src0_sel:WORD_1 src1_sel:DWORD
	v_add3_u32 v3, v5, v3, s60
	s_waitcnt lgkmcnt(0)
	v_add_f32_e32 v5, v7, v8
	v_add3_u32 v4, v4, v6, s60
	v_div_scale_f32 v6, s[0:1], v5, v5, 1.0
	v_rcp_f32_e32 v7, v6
	v_and_b32_e32 v3, 0xffff0000, v3
	v_and_b32_e32 v4, 0xffff0000, v4
	v_or_b32_sdwa v3, v3, v0 dst_sel:DWORD dst_unused:UNUSED_PAD src0_sel:DWORD src1_sel:WORD_1
	v_fma_f32 v0, -v6, v7, 1.0
	v_or_b32_sdwa v2, v4, v2 dst_sel:DWORD dst_unused:UNUSED_PAD src0_sel:DWORD src1_sel:WORD_1
	v_fmac_f32_e32 v7, v0, v7
	v_div_scale_f32 v0, vcc, 1.0, v5, 1.0
	global_store_dwordx2 v[18:19], v[2:3], off offset:96 sc1
	v_mul_f32_e32 v2, v0, v7
	v_fma_f32 v3, -v6, v2, v0
	v_fmac_f32_e32 v2, v3, v7
	v_fma_f32 v0, -v6, v2, v0
	v_div_fmas_f32 v0, v0, v7, v2
	v_div_fixup_f32 v0, v0, v5, 1.0
	v_mov_b32_e32 v2, v28
	v_mov_b32_e32 v3, v30
	v_pk_mul_f32 v[2:3], v[2:3], v[0:1] op_sel_hi:[1,0]
	v_mov_b32_e32 v30, v29
	v_pk_mul_f32 v[4:5], v[30:31], v[0:1] op_sel_hi:[1,0]
	v_and_b32_sdwa v6, v3, v236 dst_sel:DWORD dst_unused:UNUSED_PAD src0_sel:WORD_1 src1_sel:DWORD
	v_and_b32_sdwa v7, v2, v236 dst_sel:DWORD dst_unused:UNUSED_PAD src0_sel:WORD_1 src1_sel:DWORD
	v_add3_u32 v2, v2, v7, s60
	v_add3_u32 v3, v3, v6, s60
	v_and_b32_sdwa v6, v5, v236 dst_sel:DWORD dst_unused:UNUSED_PAD src0_sel:WORD_1 src1_sel:DWORD
	v_and_b32_sdwa v7, v4, v236 dst_sel:DWORD dst_unused:UNUSED_PAD src0_sel:WORD_1 src1_sel:DWORD
	v_add3_u32 v5, v5, v6, s60
	v_add3_u32 v4, v4, v7, s60
	v_and_b32_e32 v5, 0xffff0000, v5
	v_and_b32_e32 v4, 0xffff0000, v4
	v_or_b32_sdwa v3, v5, v3 dst_sel:DWORD dst_unused:UNUSED_PAD src0_sel:DWORD src1_sel:WORD_1
	v_or_b32_sdwa v2, v4, v2 dst_sel:DWORD dst_unused:UNUSED_PAD src0_sel:DWORD src1_sel:WORD_1
	v_lshl_add_u64 v[4:5], v[40:41], 0, v[88:89]
	v_lshl_add_u64 v[6:7], v[4:5], 0, s[18:19]
	v_add_co_u32_e32 v4, vcc, s2, v4
	s_nop 1
	v_addc_co_u32_e32 v5, vcc, 0, v5, vcc
	global_store_dwordx2 v[4:5], v[2:3], off offset:512 sc1
	v_mov_b32_e32 v2, v24
	v_mov_b32_e32 v3, v26
	v_pk_mul_f32 v[2:3], v[2:3], v[0:1] op_sel_hi:[1,0]
	v_mov_b32_e32 v26, v25
	v_pk_mul_f32 v[4:5], v[26:27], v[0:1] op_sel_hi:[1,0]
	v_and_b32_sdwa v8, v3, v236 dst_sel:DWORD dst_unused:UNUSED_PAD src0_sel:WORD_1 src1_sel:DWORD
	v_and_b32_sdwa v9, v2, v236 dst_sel:DWORD dst_unused:UNUSED_PAD src0_sel:WORD_1 src1_sel:DWORD
	v_add3_u32 v2, v2, v9, s60
	v_add3_u32 v3, v3, v8, s60
	v_and_b32_sdwa v8, v5, v236 dst_sel:DWORD dst_unused:UNUSED_PAD src0_sel:WORD_1 src1_sel:DWORD
	v_and_b32_sdwa v9, v4, v236 dst_sel:DWORD dst_unused:UNUSED_PAD src0_sel:WORD_1 src1_sel:DWORD
	v_add3_u32 v5, v5, v8, s60
	v_add3_u32 v4, v4, v9, s60
	v_and_b32_e32 v5, 0xffff0000, v5
	v_and_b32_e32 v4, 0xffff0000, v4
	v_or_b32_sdwa v3, v5, v3 dst_sel:DWORD dst_unused:UNUSED_PAD src0_sel:DWORD src1_sel:WORD_1
	v_or_b32_sdwa v2, v4, v2 dst_sel:DWORD dst_unused:UNUSED_PAD src0_sel:DWORD src1_sel:WORD_1
	global_store_dwordx2 v[6:7], v[2:3], off offset:32 sc1
	v_mov_b32_e32 v2, v20
	v_mov_b32_e32 v3, v22
	v_pk_mul_f32 v[2:3], v[2:3], v[0:1] op_sel_hi:[1,0]
	v_mov_b32_e32 v22, v21
	v_pk_mul_f32 v[4:5], v[22:23], v[0:1] op_sel_hi:[1,0]
	v_and_b32_sdwa v8, v3, v236 dst_sel:DWORD dst_unused:UNUSED_PAD src0_sel:WORD_1 src1_sel:DWORD
	v_and_b32_sdwa v9, v2, v236 dst_sel:DWORD dst_unused:UNUSED_PAD src0_sel:WORD_1 src1_sel:DWORD
	v_add3_u32 v2, v2, v9, s60
	v_add3_u32 v3, v3, v8, s60
	v_and_b32_sdwa v8, v5, v236 dst_sel:DWORD dst_unused:UNUSED_PAD src0_sel:WORD_1 src1_sel:DWORD
	v_and_b32_sdwa v9, v4, v236 dst_sel:DWORD dst_unused:UNUSED_PAD src0_sel:WORD_1 src1_sel:DWORD
	v_add3_u32 v5, v5, v8, s60
	v_add3_u32 v4, v4, v9, s60
	v_and_b32_e32 v5, 0xffff0000, v5
	v_and_b32_e32 v4, 0xffff0000, v4
	v_or_b32_sdwa v3, v5, v3 dst_sel:DWORD dst_unused:UNUSED_PAD src0_sel:DWORD src1_sel:WORD_1
	v_or_b32_sdwa v2, v4, v2 dst_sel:DWORD dst_unused:UNUSED_PAD src0_sel:DWORD src1_sel:WORD_1
	global_store_dwordx2 v[6:7], v[2:3], off offset:64 sc1
	v_mov_b32_e32 v2, v14
	v_mov_b32_e32 v3, v16
	v_pk_mul_f32 v[2:3], v[2:3], v[0:1] op_sel_hi:[1,0]
	v_mov_b32_e32 v16, v15
	v_pk_mul_f32 v[4:5], v[16:17], v[0:1] op_sel_hi:[1,0]
	v_and_b32_sdwa v0, v3, v236 dst_sel:DWORD dst_unused:UNUSED_PAD src0_sel:WORD_1 src1_sel:DWORD
	v_and_b32_sdwa v8, v2, v236 dst_sel:DWORD dst_unused:UNUSED_PAD src0_sel:WORD_1 src1_sel:DWORD
	v_add3_u32 v2, v2, v8, s60
	v_add3_u32 v0, v3, v0, s60
	v_and_b32_sdwa v3, v5, v236 dst_sel:DWORD dst_unused:UNUSED_PAD src0_sel:WORD_1 src1_sel:DWORD
	v_and_b32_sdwa v8, v4, v236 dst_sel:DWORD dst_unused:UNUSED_PAD src0_sel:WORD_1 src1_sel:DWORD
	v_add3_u32 v3, v5, v3, s60
	v_add3_u32 v4, v4, v8, s60
	v_and_b32_e32 v3, 0xffff0000, v3
	v_and_b32_e32 v4, 0xffff0000, v4
	v_or_b32_sdwa v3, v3, v0 dst_sel:DWORD dst_unused:UNUSED_PAD src0_sel:DWORD src1_sel:WORD_1
	v_or_b32_sdwa v2, v4, v2 dst_sel:DWORD dst_unused:UNUSED_PAD src0_sel:DWORD src1_sel:WORD_1
	global_store_dwordx2 v[6:7], v[2:3], off offset:96 sc1
	s_branch .LBB0_1196

.LBB0_1255:
	s_and_b32 s3, s2, 0xc0
	s_and_b32 s6, s1, 0xffffffc0
	v_or_b32_e32 v0, s3, v12
	s_ashr_i32 s7, s6, 31
	v_lshl_add_u64 v[2:3], s[6:7], 1, v[6:7]
	v_lshlrev_b32_e32 v0, 14, v0
	v_lshl_add_u64 v[10:11], v[2:3], 0, v[0:1]
	v_add_co_u32_e32 v22, vcc, 0x20000, v10
	global_load_dwordx4 v[2:5], v[10:11], off sc1
	s_nop 0
	v_addc_co_u32_e32 v23, vcc, 0, v11, vcc
	global_load_dwordx4 v[22:25], v[22:23], off sc1
	v_add_co_u32_e32 v26, vcc, 0x40000, v10
	v_add_u32_e32 v0, 0x420, v21
	s_nop 0
	v_addc_co_u32_e32 v27, vcc, 0, v11, vcc
	global_load_dwordx4 v[26:29], v[26:27], off sc1
	v_add_co_u32_e32 v30, vcc, 0x60000, v10
	s_lshl_b32 s44, s3, 1
	s_nop 0
	v_addc_co_u32_e32 v31, vcc, 0, v11, vcc
	global_load_dwordx4 v[30:33], v[30:31], off sc1
	v_add_co_u32_e32 v34, vcc, 0x80000, v10
	s_add_i32 s0, s0, s68
	s_nop 0
	v_addc_co_u32_e32 v35, vcc, 0, v11, vcc
	global_load_dwordx4 v[34:37], v[34:35], off sc1
	v_add_co_u32_e32 v38, vcc, 0xa0000, v10
	s_add_i32 s2, s2, s58
	s_nop 0
	v_addc_co_u32_e32 v39, vcc, 0, v11, vcc
	global_load_dwordx4 v[38:41], v[38:39], off sc1
	v_add_co_u32_e32 v42, vcc, 0xc0000, v10
	s_nop 1
	v_addc_co_u32_e32 v43, vcc, 0, v11, vcc
	global_load_dwordx4 v[42:45], v[42:43], off sc1
	v_add_co_u32_e32 v10, vcc, 0xe0000, v10
	s_nop 1
	v_addc_co_u32_e32 v11, vcc, 0, v11, vcc
	global_load_dwordx4 v[46:49], v[10:11], off sc1
	v_lshl_add_u64 v[10:11], v[8:9], 0, s[44:45]
	s_waitcnt vmcnt(7)
	ds_write2_b32 v21, v2, v3 offset1:1
	ds_write2_b32 v21, v4, v5 offset0:2 offset1:3
	s_waitcnt vmcnt(6)
	ds_write2_b32 v0, v22, v23 offset1:1
	v_add_u32_e32 v0, 0x428, v21
	ds_write2_b32 v0, v24, v25 offset1:1
	v_add_u32_e32 v0, 0x840, v21
	v_or_b32_e32 v22, s6, v12
	v_ashrrev_i32_e32 v23, 31, v22
	s_waitcnt vmcnt(5)
	ds_write2_b32 v0, v26, v27 offset1:1
	v_add_u32_e32 v0, 0x848, v21
	ds_write2_b32 v0, v28, v29 offset1:1
	v_add_u32_e32 v0, 0xc60, v21
	v_lshlrev_b64 v[22:23], 11, v[22:23]
	v_lshl_add_u64 v[22:23], v[10:11], 0, v[22:23]
	s_waitcnt vmcnt(4)
	ds_write2_b32 v0, v30, v31 offset1:1
	v_add_u32_e32 v0, 0xc68, v21
	ds_write2_b32 v0, v32, v33 offset1:1
	v_add_u32_e32 v0, 0x1080, v21
	s_waitcnt vmcnt(3)
	ds_write2_b32 v0, v34, v35 offset1:1
	v_add_u32_e32 v0, 0x1088, v21
	ds_write2_b32 v0, v36, v37 offset1:1
	v_add_u32_e32 v0, 0x14a0, v21
	s_waitcnt vmcnt(2)
	ds_write2_b32 v0, v38, v39 offset1:1
	v_add_u32_e32 v0, 0x14a8, v21
	ds_write2_b32 v0, v40, v41 offset1:1
	v_add_u32_e32 v0, 0x18c0, v21
	s_waitcnt vmcnt(1)
	ds_write2_b32 v0, v42, v43 offset1:1
	v_add_u32_e32 v0, 0x18c8, v21
	ds_write2_b32 v0, v44, v45 offset1:1
	v_add_u32_e32 v0, 0x1ce0, v21
	s_waitcnt vmcnt(0)
	ds_write2_b32 v0, v46, v47 offset1:1
	v_add_u32_e32 v0, 0x1ce8, v21
	ds_write2_b32 v0, v48, v49 offset1:1
	s_waitcnt lgkmcnt(0)
	ds_read_u16 v0, v13 offset:132
	ds_read_u16 v2, v13
	ds_read_u16 v24, v13 offset:16
	s_waitcnt lgkmcnt(1)
	v_lshl_or_b32 v2, v0, 16, v2
	ds_read_u16 v0, v13 offset:264
	ds_read_u16 v3, v13 offset:396
	s_waitcnt lgkmcnt(0)
	v_lshl_or_b32 v3, v3, 16, v0
	ds_read_u16 v0, v13 offset:528
	ds_read_u16 v4, v13 offset:660
	s_waitcnt lgkmcnt(0)
	v_lshl_or_b32 v4, v4, 16, v0
	ds_read_u16 v0, v13 offset:792
	ds_read_u16 v5, v13 offset:924
	s_waitcnt lgkmcnt(0)
	v_lshl_or_b32 v5, v5, 16, v0
	ds_read_u16 v0, v13 offset:148
	global_store_dwordx4 v[22:23], v[2:5], off sc1
	v_or_b32_e32 v22, s6, v14
	v_ashrrev_i32_e32 v23, 31, v22
	v_lshlrev_b64 v[22:23], 11, v[22:23]
	s_waitcnt lgkmcnt(0)
	v_lshl_or_b32 v2, v0, 16, v24
	ds_read_u16 v0, v13 offset:280
	ds_read_u16 v3, v13 offset:412
	v_lshl_add_u64 v[22:23], v[10:11], 0, v[22:23]
	s_waitcnt lgkmcnt(0)
	v_lshl_or_b32 v3, v3, 16, v0
	ds_read_u16 v0, v13 offset:544
	ds_read_u16 v4, v13 offset:676
	s_waitcnt lgkmcnt(0)
	v_lshl_or_b32 v4, v4, 16, v0
	ds_read_u16 v0, v13 offset:808
	ds_read_u16 v5, v13 offset:940
	s_waitcnt lgkmcnt(0)
	v_lshl_or_b32 v5, v5, 16, v0
	global_store_dwordx4 v[22:23], v[2:5], off sc1
	ds_read_u16 v0, v13 offset:164
	ds_read_u16 v2, v13 offset:32
	ds_read_u16 v24, v13 offset:48
	v_or_b32_e32 v22, s6, v15
	v_ashrrev_i32_e32 v23, 31, v22
	v_lshlrev_b64 v[22:23], 11, v[22:23]
	s_waitcnt lgkmcnt(1)
	v_lshl_or_b32 v2, v0, 16, v2
	ds_read_u16 v0, v13 offset:296
	ds_read_u16 v3, v13 offset:428
	v_lshl_add_u64 v[22:23], v[10:11], 0, v[22:23]
	s_waitcnt lgkmcnt(0)
	v_lshl_or_b32 v3, v3, 16, v0
	ds_read_u16 v0, v13 offset:560
	ds_read_u16 v4, v13 offset:692
	s_waitcnt lgkmcnt(0)
	v_lshl_or_b32 v4, v4, 16, v0
	ds_read_u16 v0, v13 offset:824
	ds_read_u16 v5, v13 offset:956
	s_waitcnt lgkmcnt(0)
	v_lshl_or_b32 v5, v5, 16, v0
	ds_read_u16 v0, v13 offset:180
	global_store_dwordx4 v[22:23], v[2:5], off sc1
	v_or_b32_e32 v22, s6, v16
	v_ashrrev_i32_e32 v23, 31, v22
	v_lshlrev_b64 v[22:23], 11, v[22:23]
	s_waitcnt lgkmcnt(0)
	v_lshl_or_b32 v2, v0, 16, v24
	ds_read_u16 v0, v13 offset:312
	ds_read_u16 v3, v13 offset:444
	v_lshl_add_u64 v[22:23], v[10:11], 0, v[22:23]
	s_waitcnt lgkmcnt(0)
	v_lshl_or_b32 v3, v3, 16, v0
	ds_read_u16 v0, v13 offset:576
	ds_read_u16 v4, v13 offset:708
	s_waitcnt lgkmcnt(0)
	v_lshl_or_b32 v4, v4, 16, v0
	ds_read_u16 v0, v13 offset:840
	ds_read_u16 v5, v13 offset:972
	s_waitcnt lgkmcnt(0)
	v_lshl_or_b32 v5, v5, 16, v0
	global_store_dwordx4 v[22:23], v[2:5], off sc1
	ds_read_u16 v0, v13 offset:64
	ds_read_u16 v2, v13 offset:196
	v_or_b32_e32 v22, s6, v17
	v_ashrrev_i32_e32 v23, 31, v22
	v_lshlrev_b64 v[22:23], 11, v[22:23]
	v_lshl_add_u64 v[22:23], v[10:11], 0, v[22:23]
	s_waitcnt lgkmcnt(0)
	v_lshl_or_b32 v2, v2, 16, v0
	ds_read_u16 v0, v13 offset:328
	ds_read_u16 v3, v13 offset:460
	s_waitcnt lgkmcnt(0)
	v_lshl_or_b32 v3, v3, 16, v0
	ds_read_u16 v0, v13 offset:592
	ds_read_u16 v4, v13 offset:724
	s_waitcnt lgkmcnt(0)
	v_lshl_or_b32 v4, v4, 16, v0
	ds_read_u16 v0, v13 offset:856
	ds_read_u16 v5, v13 offset:988
	s_waitcnt lgkmcnt(0)
	v_lshl_or_b32 v5, v5, 16, v0
	global_store_dwordx4 v[22:23], v[2:5], off sc1
	ds_read_u16 v0, v13 offset:80
	ds_read_u16 v2, v13 offset:212
	v_or_b32_e32 v22, s6, v18
	v_ashrrev_i32_e32 v23, 31, v22
	v_lshlrev_b64 v[22:23], 11, v[22:23]
	v_lshl_add_u64 v[22:23], v[10:11], 0, v[22:23]
	s_waitcnt lgkmcnt(0)
	v_lshl_or_b32 v2, v2, 16, v0
	ds_read_u16 v0, v13 offset:344
	ds_read_u16 v3, v13 offset:476
	s_waitcnt lgkmcnt(0)
	v_lshl_or_b32 v3, v3, 16, v0
	ds_read_u16 v0, v13 offset:608
	ds_read_u16 v4, v13 offset:740
	s_waitcnt lgkmcnt(0)
	v_lshl_or_b32 v4, v4, 16, v0
	ds_read_u16 v0, v13 offset:872
	ds_read_u16 v5, v13 offset:1004
	s_waitcnt lgkmcnt(0)
	v_lshl_or_b32 v5, v5, 16, v0
	global_store_dwordx4 v[22:23], v[2:5], off sc1
	ds_read_u16 v0, v13 offset:96
	ds_read_u16 v2, v13 offset:228
	v_or_b32_e32 v22, s1, v19
	v_ashrrev_i32_e32 v23, 31, v22
	v_lshlrev_b64 v[22:23], 11, v[22:23]
	v_lshl_add_u64 v[22:23], v[10:11], 0, v[22:23]
	s_waitcnt lgkmcnt(0)
	v_lshl_or_b32 v2, v2, 16, v0
	ds_read_u16 v0, v13 offset:360
	ds_read_u16 v3, v13 offset:492
	s_waitcnt lgkmcnt(0)
	v_lshl_or_b32 v3, v3, 16, v0
	ds_read_u16 v0, v13 offset:624
	ds_read_u16 v4, v13 offset:756
	s_waitcnt lgkmcnt(0)
	v_lshl_or_b32 v4, v4, 16, v0
	ds_read_u16 v0, v13 offset:888
	ds_read_u16 v5, v13 offset:1020
	s_waitcnt lgkmcnt(0)
	v_lshl_or_b32 v5, v5, 16, v0
	global_store_dwordx4 v[22:23], v[2:5], off sc1
	ds_read_u16 v0, v13 offset:112
	ds_read_u16 v2, v13 offset:244
	v_or_b32_e32 v22, s1, v20
	v_ashrrev_i32_e32 v23, 31, v22
	v_lshlrev_b64 v[22:23], 11, v[22:23]
	v_lshl_add_u64 v[10:11], v[10:11], 0, v[22:23]
	s_waitcnt lgkmcnt(0)
	v_lshl_or_b32 v2, v2, 16, v0
	ds_read_u16 v0, v13 offset:376
	ds_read_u16 v3, v13 offset:508
	s_add_i32 s1, s1, s50
	s_cmpk_lt_i32 s0, 0x200
	s_waitcnt lgkmcnt(0)
	v_lshl_or_b32 v3, v3, 16, v0
	ds_read_u16 v0, v13 offset:640
	ds_read_u16 v4, v13 offset:772
	s_waitcnt lgkmcnt(0)
	v_lshl_or_b32 v4, v4, 16, v0
	ds_read_u16 v0, v13 offset:904
	ds_read_u16 v5, v13 offset:1036
	s_waitcnt lgkmcnt(0)
	v_lshl_or_b32 v5, v5, 16, v0
	global_store_dwordx4 v[10:11], v[2:5], off sc1
	s_waitcnt lgkmcnt(0)
	s_cbranch_scc1 .LBB0_1255

.LBB0_1290:
	s_andn2_saveexec_b64 s[0:1], s[12:13]
	s_cbranch_execz .LBB0_1310
	s_mov_b64 s[12:13], exec
	s_waitcnt lgkmcnt(0)
	s_waitcnt vmcnt(0)
	v_mbcnt_lo_u32_b32 v0, s12, 0
	v_mbcnt_hi_u32_b32 v0, s13, v0
	v_cmp_eq_u32_e32 vcc, 0, v0
	s_and_saveexec_b64 s[14:15], vcc
	s_cbranch_execz .LBB0_1293
	s_bcnt1_i32_b64 s0, s[12:13]
	v_mov_b32_e32 v3, s0
	v_mov_b32_e32 v4, 0xe803000
	global_atomic_add v3, v4, v3, s[8:9] offset:1024 sc0
